# GEMM K loops: load super-phase address set-up issued in the middle of the preceding MFMA block (MFMA-shadow interleave)
# baseline (speedup 1.0000x reference)
; #define STAGE(bufoff, gbase, voff) do { _Pragma("unroll") for (int _i = 0; _i < 2; ++_i) \
;     __builtin_amdgcn_global_load_lds((const unsigned*)((const char*)(gbase) + (voff)[_i]), (LAS unsigned*)(lds + (bufoff) + ldsw + _i * 8192), 16, 0, 0); } while (0)
; #define LDA(dst, b, h) do { _Pragma("unroll") for (int m = 0; m < 4; ++m) _Pragma("unroll") for (int k = 0; k < 2; ++k) dst[m][k] = *(const LAS half8*)(lds + SA(b, h) + aoff + m * 2048 + k * 1024); } while (0)
; #define LDB(dst, b, h) do { _Pragma("unroll") for (int n = 0; n < 2; ++n) _Pragma("unroll") for (int k = 0; k < 2; ++k) dst[n][k] = *(const LAS half8*)(lds + SB(b, h) + boff + n * 2048 + k * 1024); } while (0)
; #define MMA(ai, bj, At_, Bt_) do { __builtin_amdgcn_s_setprio(1); \
;     _Pragma("unroll") for (int m = 0; m < 4; ++m) _Pragma("unroll") for (int n = 0; n < 2; ++n) _Pragma("unroll") for (int k = 0; k < 2; ++k) \
;       acc[ai][bj][m][n] = MFMA16(Bt_[n][k], At_[m][k], acc[ai][bj][m][n]); \
;     __builtin_amdgcn_s_setprio(0); } while (0)
; #define WAIT_V(n) asm volatile("s_waitcnt vmcnt(" #n ")" ::: "memory")
; #define WAIT_L(n) asm volatile("s_waitcnt lgkmcnt(" #n ")" ::: "memory")
; #define BAR __builtin_amdgcn_s_barrier()
; #define SCHED __builtin_amdgcn_sched_barrier(0)
; template <int EPI>
; DI void gemm_phase(const int wid_s, const h16* __restrict__ A, const h16* __restrict__ Bt, const int N, const int K, const EpiArgs ea) {
;     ...
;     const char* nA = (const char*)A + (size_t)nbrow * K * 2;
;     const char* nB = (const char*)Bt + (size_t)nbcol * K * 2;
;     for (int t = 0; t < nt; t += 2) {
;       const bool last = (t == nt - 2);
;       const char* a1 = cA + (size_t)(t + 1) * kstep;
;       const char* a2 = last ? nA : cA + (size_t)(t + 2) * kstep; const char* b2 = last ? nB : cB + (size_t)(t + 2) * kstep;
;       const char* a3 = a2 + kstep; const char* b3 = b2 + kstep;
;       LDB(B0, 0, 0); LDB(B1, 0, 1); SCHED; LDA(At, 0, 0); STAGE(SA(1, 1), a1 + hstep, voffA);
;       WAIT_V(8); WAIT_L(0); BAR; MMA(0, 0, At, B0); MMA(0, 1, At, B1); BAR; SCHED;
;       LDA(At, 0, 1); STAGE(SB(0, 0), b2, voffB); STAGE(SB(0, 1), b2 + hstep, voffB); STAGE(SA(0, 0), a2, voffA);
.LBB0_121:
	s_mul_i32 s8, s31, 0x1600
	s_mul_hi_i32 s9, s31, 0x1600
	s_add_u32 s8, s28, s8
	s_addc_u32 s9, s29, s9
	s_mul_i32 s10, s38, 0x1600
	v_readlane_b32 s16, v250, 58
	s_mul_hi_i32 s11, s38, 0x1600
	s_add_u32 s41, s16, s10
	v_readlane_b32 s16, v250, 61
	s_addc_u32 s42, s16, s11
	v_readlane_b32 s16, v249, 21
	s_add_u32 s43, s16, s14
	v_readlane_b32 s14, v249, 22
	v_mov_b32_e32 v6, 0
	s_addc_u32 s44, s14, s15
	s_mov_b32 s45, -2
	s_add_u32 s14, s12, 0x100
	s_addc_u32 s15, s13, 0
	s_add_i32 s46, 0, 0x10000
	s_cmp_eq_u32 s45, 40
	s_cselect_b32 s19, s9, s15
	s_cselect_b32 s18, s8, s14
	v_add_u32_e32 v177, s46, v148
	s_cselect_b32 s17, s42, s44
	s_cselect_b32 s16, s41, s43
	s_add_i32 s47, 0, 0x14000
	ds_read_b128 v[144:147], v177
	ds_read_b128 v[152:155], v177 offset:1024
	ds_read_b128 v[178:181], v177 offset:2048
	ds_read_b128 v[182:185], v177 offset:3072
	v_add_u32_e32 v177, s47, v148
	ds_read_b128 v[186:189], v177
	ds_read_b128 v[190:193], v177 offset:1024
	ds_read_b128 v[194:197], v177 offset:2048
	ds_read_b128 v[198:201], v177 offset:3072
	v_lshl_add_u64 v[234:235], s[12:13], 0, v[142:143]
	s_add_i32 m0, s22, 0xc000
	ds_read_b128 v[202:205], v151
	ds_read_b128 v[206:209], v151 offset:1024
	ds_read_b128 v[210:213], v151 offset:2048
	ds_read_b128 v[214:217], v151 offset:3072
	ds_read_b128 v[218:221], v151 offset:4096
	ds_read_b128 v[222:225], v151 offset:5120
	ds_read_b128 v[226:229], v151 offset:6144
	ds_read_b128 v[230:233], v151 offset:7168
	global_load_lds_dwordx4 v[234:235], off
	v_lshl_add_u64 v[234:235], s[12:13], 0, v[140:141]
	s_add_i32 m0, s22, 0xe000
	s_nop 0
	global_load_lds_dwordx4 v[234:235], off
	s_waitcnt vmcnt(8)
	s_waitcnt lgkmcnt(0)
	s_barrier
	s_waitcnt lgkmcnt(0)
	v_mfma_f32_16x16x32_f16 v[130:133], v[144:147], v[202:205], 0
	v_mfma_f32_16x16x32_f16 v[126:129], v[178:181], v[202:205], 0
	v_mfma_f32_16x16x32_f16 v[114:117], v[144:147], v[210:213], 0
	v_mfma_f32_16x16x32_f16 v[110:113], v[178:181], v[210:213], 0
	v_mfma_f32_16x16x32_f16 v[98:101], v[144:147], v[218:221], 0
	v_mfma_f32_16x16x32_f16 v[94:97], v[178:181], v[218:221], 0
	v_mfma_f32_16x16x32_f16 v[82:85], v[144:147], v[226:229], 0
	v_mfma_f32_16x16x32_f16 v[78:81], v[178:181], v[226:229], 0
	v_mfma_f32_16x16x32_f16 v[130:133], v[152:155], v[206:209], v[130:133]
	v_mfma_f32_16x16x32_f16 v[126:129], v[182:185], v[206:209], v[126:129]
	v_mfma_f32_16x16x32_f16 v[114:117], v[152:155], v[214:217], v[114:117]
	v_mfma_f32_16x16x32_f16 v[110:113], v[182:185], v[214:217], v[110:113]
	v_mfma_f32_16x16x32_f16 v[98:101], v[152:155], v[222:225], v[98:101]
	v_mfma_f32_16x16x32_f16 v[94:97], v[182:185], v[222:225], v[94:97]
	v_mfma_f32_16x16x32_f16 v[82:85], v[152:155], v[230:233], v[82:85]
	v_mfma_f32_16x16x32_f16 v[78:81], v[182:185], v[230:233], v[78:81]
	s_add_i32 s12, s46, s21
	v_lshl_add_u64 v[234:235], s[16:17], 0, v[0:1]
	s_mov_b32 m0, s12
	v_mfma_f32_16x16x32_f16 v[122:125], v[186:189], v[202:205], 0
	v_mfma_f32_16x16x32_f16 v[118:121], v[194:197], v[202:205], 0
	v_mfma_f32_16x16x32_f16 v[106:109], v[186:189], v[210:213], 0
	v_mfma_f32_16x16x32_f16 v[102:105], v[194:197], v[210:213], 0
	v_mfma_f32_16x16x32_f16 v[90:93], v[186:189], v[218:221], 0
	v_mfma_f32_16x16x32_f16 v[86:89], v[194:197], v[218:221], 0
	v_mfma_f32_16x16x32_f16 v[74:77], v[186:189], v[226:229], 0
	v_mfma_f32_16x16x32_f16 v[70:73], v[194:197], v[226:229], 0
	v_mfma_f32_16x16x32_f16 v[122:125], v[190:193], v[206:209], v[122:125]
	v_mfma_f32_16x16x32_f16 v[118:121], v[198:201], v[206:209], v[118:121]
	v_mfma_f32_16x16x32_f16 v[106:109], v[190:193], v[214:217], v[106:109]
	v_mfma_f32_16x16x32_f16 v[102:105], v[198:201], v[214:217], v[102:105]
	v_mfma_f32_16x16x32_f16 v[90:93], v[190:193], v[222:225], v[90:93]
	v_mfma_f32_16x16x32_f16 v[86:89], v[198:201], v[222:225], v[86:89]
	v_mfma_f32_16x16x32_f16 v[74:77], v[190:193], v[230:233], v[74:77]
	v_mfma_f32_16x16x32_f16 v[70:73], v[198:201], v[230:233], v[70:73]
	s_barrier
	ds_read_b128 v[202:205], v151 offset:16384
	ds_read_b128 v[206:209], v151 offset:17408
	ds_read_b128 v[210:213], v151 offset:18432
	ds_read_b128 v[214:217], v151 offset:19456
	ds_read_b128 v[218:221], v151 offset:20480
	ds_read_b128 v[222:225], v151 offset:21504
	ds_read_b128 v[226:229], v151 offset:22528
	ds_read_b128 v[230:233], v151 offset:23552
	global_load_lds_dwordx4 v[234:235], off
	s_add_i32 m0, s12, 0x2000
	s_add_u32 s12, s16, 0xb0000
	v_lshl_add_u64 v[236:237], s[16:17], 0, v[138:139]
	s_addc_u32 s13, s17, 0
	s_add_i32 s46, s47, s21
	global_load_lds_dwordx4 v[236:237], off
	v_lshl_add_u64 v[238:239], s[12:13], 0, v[0:1]
	s_mov_b32 m0, s46
	v_lshl_add_u64 v[240:241], s[18:19], 0, v[134:135]
	global_load_lds_dwordx4 v[238:239], off
	v_lshl_add_u64 v[238:239], s[12:13], 0, v[138:139]
	s_add_i32 m0, s46, 0x2000
	s_nop 0
	global_load_lds_dwordx4 v[238:239], off
	v_lshl_add_u64 v[238:239], s[18:19], 0, v[2:3]
	s_mov_b32 m0, s22
	s_nop 0
	global_load_lds_dwordx4 v[238:239], off
	s_mov_b32 m0, s23
	s_nop 0
	global_load_lds_dwordx4 v[240:241], off
	s_waitcnt vmcnt(8)
	s_waitcnt lgkmcnt(0)
	s_barrier
; #define STAGE(bufoff, gbase, voff) do { _Pragma("unroll") for (int _i = 0; _i < 2; ++_i) \
;     __builtin_amdgcn_global_load_lds((const unsigned*)((const char*)(gbase) + (voff)[_i]), (LAS unsigned*)(lds + (bufoff) + ldsw + _i * 8192), 16, 0, 0); } while (0)
; #define LDA(dst, b, h) do { _Pragma("unroll") for (int m = 0; m < 4; ++m) _Pragma("unroll") for (int k = 0; k < 2; ++k) dst[m][k] = *(const LAS half8*)(lds + SA(b, h) + aoff + m * 2048 + k * 1024); } while (0)
; #define LDB(dst, b, h) do { _Pragma("unroll") for (int n = 0; n < 2; ++n) _Pragma("unroll") for (int k = 0; k < 2; ++k) dst[n][k] = *(const LAS half8*)(lds + SB(b, h) + boff + n * 2048 + k * 1024); } while (0)
; #define MMA(ai, bj, At_, Bt_) do { __builtin_amdgcn_s_setprio(1); \
;     _Pragma("unroll") for (int m = 0; m < 4; ++m) _Pragma("unroll") for (int n = 0; n < 2; ++n) _Pragma("unroll") for (int k = 0; k < 2; ++k) \
;       acc[ai][bj][m][n] = MFMA16(Bt_[n][k], At_[m][k], acc[ai][bj][m][n]); \
;     __builtin_amdgcn_s_setprio(0); } while (0)
; #define WAIT_V(n) asm volatile("s_waitcnt vmcnt(" #n ")" ::: "memory")
; #define WAIT_L(n) asm volatile("s_waitcnt lgkmcnt(" #n ")" ::: "memory")
; #define BAR __builtin_amdgcn_s_barrier()
; #define SCHED __builtin_amdgcn_sched_barrier(0)
; template <int EPI>
; DI void gemm_phase(const int wid_s, const h16* __restrict__ A, const h16* __restrict__ Bt, const int N, const int K, const EpiArgs ea) {
;     ...
;       LDA(At, 0, 1); STAGE(SB(0, 0), b2, voffB); STAGE(SB(0, 1), b2 + hstep, voffB); STAGE(SA(0, 0), a2, voffA);
;       WAIT_V(8); WAIT_L(0); BAR; MMA(1, 0, At, B0); MMA(1, 1, At, B1); BAR; SCHED;
;       LDB(B0, 1, 0); LDB(B1, 1, 1); SCHED; LDA(At, 1, 0); STAGE(SA(0, 1), a2 + hstep, voffA);
;       WAIT_V(8); WAIT_L(0); BAR; MMA(0, 0, At, B0); MMA(0, 1, At, B1); BAR; SCHED;
	s_waitcnt lgkmcnt(0)
	v_mfma_f32_16x16x32_f16 v[66:69], v[144:147], v[202:205], 0
	v_mfma_f32_16x16x32_f16 v[62:65], v[178:181], v[202:205], 0
	v_mfma_f32_16x16x32_f16 v[50:53], v[144:147], v[210:213], 0
	v_mfma_f32_16x16x32_f16 v[46:49], v[178:181], v[210:213], 0
	v_mfma_f32_16x16x32_f16 v[34:37], v[144:147], v[218:221], 0
	v_mfma_f32_16x16x32_f16 v[30:33], v[178:181], v[218:221], 0
	v_mfma_f32_16x16x32_f16 v[18:21], v[144:147], v[226:229], 0
	v_mfma_f32_16x16x32_f16 v[14:17], v[178:181], v[226:229], 0
	v_mfma_f32_16x16x32_f16 v[66:69], v[152:155], v[206:209], v[66:69]
	v_mfma_f32_16x16x32_f16 v[62:65], v[182:185], v[206:209], v[62:65]
	v_mfma_f32_16x16x32_f16 v[50:53], v[152:155], v[214:217], v[50:53]
	v_mfma_f32_16x16x32_f16 v[46:49], v[182:185], v[214:217], v[46:49]
	v_mfma_f32_16x16x32_f16 v[34:37], v[152:155], v[222:225], v[34:37]
	v_mfma_f32_16x16x32_f16 v[30:33], v[182:185], v[222:225], v[30:33]
	v_mfma_f32_16x16x32_f16 v[18:21], v[152:155], v[230:233], v[18:21]
	v_mfma_f32_16x16x32_f16 v[14:17], v[182:185], v[230:233], v[14:17]
	s_add_i32 s46, 0, 0x18000
	v_add_u32_e32 v177, s46, v148
	s_add_i32 s47, 0, 0x1c000
	v_mfma_f32_16x16x32_f16 v[58:61], v[186:189], v[202:205], 0
	v_mfma_f32_16x16x32_f16 v[54:57], v[194:197], v[202:205], 0
	v_mfma_f32_16x16x32_f16 v[42:45], v[186:189], v[210:213], 0
	v_mfma_f32_16x16x32_f16 v[38:41], v[194:197], v[210:213], 0
	v_mfma_f32_16x16x32_f16 v[26:29], v[186:189], v[218:221], 0
	v_mfma_f32_16x16x32_f16 v[22:25], v[194:197], v[218:221], 0
	v_mfma_f32_16x16x32_f16 v[10:13], v[186:189], v[226:229], 0
	v_mfma_f32_16x16x32_f16 v[6:9], v[194:197], v[226:229], 0
	v_mfma_f32_16x16x32_f16 v[58:61], v[190:193], v[206:209], v[58:61]
	v_mfma_f32_16x16x32_f16 v[54:57], v[198:201], v[206:209], v[54:57]
	v_mfma_f32_16x16x32_f16 v[42:45], v[190:193], v[214:217], v[42:45]
	v_mfma_f32_16x16x32_f16 v[38:41], v[198:201], v[214:217], v[38:41]
	v_mfma_f32_16x16x32_f16 v[26:29], v[190:193], v[222:225], v[26:29]
	v_mfma_f32_16x16x32_f16 v[22:25], v[198:201], v[222:225], v[22:25]
	v_mfma_f32_16x16x32_f16 v[10:13], v[190:193], v[230:233], v[10:13]
	v_mfma_f32_16x16x32_f16 v[6:9], v[198:201], v[230:233], v[6:9]
	s_barrier
	ds_read_b128 v[144:147], v177
	ds_read_b128 v[152:155], v177 offset:1024
	ds_read_b128 v[178:181], v177 offset:2048
	ds_read_b128 v[182:185], v177 offset:3072
	v_add_u32_e32 v177, s47, v148
	ds_read_b128 v[186:189], v177
	ds_read_b128 v[190:193], v177 offset:1024
	ds_read_b128 v[194:197], v177 offset:2048
	ds_read_b128 v[198:201], v177 offset:3072
	s_add_u32 s12, s18, 0xb0000
	s_addc_u32 s13, s19, 0
	s_mov_b32 m0, s24
	v_lshl_add_u64 v[242:243], s[12:13], 0, v[2:3]
	ds_read_b128 v[202:205], v151 offset:32768
	ds_read_b128 v[206:209], v151 offset:33792
	ds_read_b128 v[210:213], v151 offset:34816
	ds_read_b128 v[214:217], v151 offset:35840
	ds_read_b128 v[218:221], v151 offset:36864
	ds_read_b128 v[222:225], v151 offset:37888
	ds_read_b128 v[226:229], v151 offset:38912
	ds_read_b128 v[230:233], v151 offset:39936
	global_load_lds_dwordx4 v[242:243], off
	v_lshl_add_u64 v[242:243], s[12:13], 0, v[134:135]
	s_mov_b32 m0, s26
	s_nop 0
	global_load_lds_dwordx4 v[242:243], off
	s_waitcnt vmcnt(8)
	s_waitcnt lgkmcnt(0)
	s_barrier
	s_waitcnt lgkmcnt(0)
	v_mfma_f32_16x16x32_f16 v[130:133], v[144:147], v[202:205], v[130:133]
	v_mfma_f32_16x16x32_f16 v[126:129], v[178:181], v[202:205], v[126:129]
	v_mfma_f32_16x16x32_f16 v[114:117], v[144:147], v[210:213], v[114:117]
	v_mfma_f32_16x16x32_f16 v[110:113], v[178:181], v[210:213], v[110:113]
	v_mfma_f32_16x16x32_f16 v[98:101], v[144:147], v[218:221], v[98:101]
	v_mfma_f32_16x16x32_f16 v[94:97], v[178:181], v[218:221], v[94:97]
	v_mfma_f32_16x16x32_f16 v[82:85], v[144:147], v[226:229], v[82:85]
	v_mfma_f32_16x16x32_f16 v[78:81], v[178:181], v[226:229], v[78:81]
	v_mfma_f32_16x16x32_f16 v[130:133], v[152:155], v[206:209], v[130:133]
	v_mfma_f32_16x16x32_f16 v[126:129], v[182:185], v[206:209], v[126:129]
	v_mfma_f32_16x16x32_f16 v[114:117], v[152:155], v[214:217], v[114:117]
	v_mfma_f32_16x16x32_f16 v[110:113], v[182:185], v[214:217], v[110:113]
	v_mfma_f32_16x16x32_f16 v[98:101], v[152:155], v[222:225], v[98:101]
	v_mfma_f32_16x16x32_f16 v[94:97], v[182:185], v[222:225], v[94:97]
	v_mfma_f32_16x16x32_f16 v[82:85], v[152:155], v[230:233], v[82:85]
	v_mfma_f32_16x16x32_f16 v[78:81], v[182:185], v[230:233], v[78:81]
	s_add_i32 s12, s46, s21
	v_lshl_add_u64 v[234:235], v[234:235], 0, s[36:37]
	s_mov_b32 m0, s12
	v_mfma_f32_16x16x32_f16 v[122:125], v[186:189], v[202:205], v[122:125]
	v_mfma_f32_16x16x32_f16 v[118:121], v[194:197], v[202:205], v[118:121]
	v_mfma_f32_16x16x32_f16 v[106:109], v[186:189], v[210:213], v[106:109]
	v_mfma_f32_16x16x32_f16 v[102:105], v[194:197], v[210:213], v[102:105]
	v_mfma_f32_16x16x32_f16 v[90:93], v[186:189], v[218:221], v[90:93]
	v_mfma_f32_16x16x32_f16 v[86:89], v[194:197], v[218:221], v[86:89]
	v_mfma_f32_16x16x32_f16 v[74:77], v[186:189], v[226:229], v[74:77]
	v_mfma_f32_16x16x32_f16 v[70:73], v[194:197], v[226:229], v[70:73]
	v_mfma_f32_16x16x32_f16 v[122:125], v[190:193], v[206:209], v[122:125]
	v_mfma_f32_16x16x32_f16 v[118:121], v[198:201], v[206:209], v[118:121]
	v_mfma_f32_16x16x32_f16 v[106:109], v[190:193], v[214:217], v[106:109]
	v_mfma_f32_16x16x32_f16 v[102:105], v[198:201], v[214:217], v[102:105]
	v_mfma_f32_16x16x32_f16 v[90:93], v[190:193], v[222:225], v[90:93]
	v_mfma_f32_16x16x32_f16 v[86:89], v[198:201], v[222:225], v[86:89]
	v_mfma_f32_16x16x32_f16 v[74:77], v[190:193], v[230:233], v[74:77]
	v_mfma_f32_16x16x32_f16 v[70:73], v[198:201], v[230:233], v[70:73]
	s_barrier
; #define STAGE(bufoff, gbase, voff) do { _Pragma("unroll") for (int _i = 0; _i < 2; ++_i) \
;     __builtin_amdgcn_global_load_lds((const unsigned*)((const char*)(gbase) + (voff)[_i]), (LAS unsigned*)(lds + (bufoff) + ldsw + _i * 8192), 16, 0, 0); } while (0)
; #define LDA(dst, b, h) do { _Pragma("unroll") for (int m = 0; m < 4; ++m) _Pragma("unroll") for (int k = 0; k < 2; ++k) dst[m][k] = *(const LAS half8*)(lds + SA(b, h) + aoff + m * 2048 + k * 1024); } while (0)
; #define LDB(dst, b, h) do { _Pragma("unroll") for (int n = 0; n < 2; ++n) _Pragma("unroll") for (int k = 0; k < 2; ++k) dst[n][k] = *(const LAS half8*)(lds + SB(b, h) + boff + n * 2048 + k * 1024); } while (0)
; #define MMA(ai, bj, At_, Bt_) do { __builtin_amdgcn_s_setprio(1); \
;     _Pragma("unroll") for (int m = 0; m < 4; ++m) _Pragma("unroll") for (int n = 0; n < 2; ++n) _Pragma("unroll") for (int k = 0; k < 2; ++k) \
;       acc[ai][bj][m][n] = MFMA16(Bt_[n][k], At_[m][k], acc[ai][bj][m][n]); \
;     __builtin_amdgcn_s_setprio(0); } while (0)
; #define WAIT_V(n) asm volatile("s_waitcnt vmcnt(" #n ")" ::: "memory")
; #define WAIT_L(n) asm volatile("s_waitcnt lgkmcnt(" #n ")" ::: "memory")
; #define BAR __builtin_amdgcn_s_barrier()
; #define SCHED __builtin_amdgcn_sched_barrier(0)
; template <int EPI>
; DI void gemm_phase(const int wid_s, const h16* __restrict__ A, const h16* __restrict__ Bt, const int N, const int K, const EpiArgs ea) {
;     ...
;     for (int t = 0; t < nt; t += 2) {
;       const bool last = (t == nt - 2);
;       const char* a1 = cA + (size_t)(t + 1) * kstep;
;       const char* a2 = last ? nA : cA + (size_t)(t + 2) * kstep; const char* b2 = last ? nB : cB + (size_t)(t + 2) * kstep;
;       const char* a3 = a2 + kstep; const char* b3 = b2 + kstep;
;       LDB(B0, 0, 0); LDB(B1, 0, 1); SCHED; LDA(At, 0, 0); STAGE(SA(1, 1), a1 + hstep, voffA);
;       WAIT_V(8); WAIT_L(0); BAR; MMA(0, 0, At, B0); MMA(0, 1, At, B1); BAR; SCHED;
;     ...
;       LDA(At, 1, 1); STAGE(SB(1, 0), b3, voffB); STAGE(SB(1, 1), b3 + hstep, voffB); STAGE(SA(1, 0), a3, voffA);
;       WAIT_V(8); WAIT_L(0); BAR; MMA(1, 0, At, B0); MMA(1, 1, At, B1); BAR; SCHED;
	ds_read_b128 v[202:205], v151 offset:49152
	ds_read_b128 v[206:209], v151 offset:50176
	ds_read_b128 v[210:213], v151 offset:51200
	ds_read_b128 v[214:217], v151 offset:52224
	ds_read_b128 v[218:221], v151 offset:53248
	ds_read_b128 v[222:225], v151 offset:54272
	ds_read_b128 v[226:229], v151 offset:55296
	ds_read_b128 v[230:233], v151 offset:56320
	global_load_lds_dwordx4 v[234:235], off
	s_add_i32 m0, s12, 0x2000
	s_add_u32 s12, s16, 0xb0080
	v_lshl_add_u64 v[234:235], v[236:237], 0, s[36:37]
	s_addc_u32 s13, s17, 0
	s_add_i32 s16, s47, s21
	global_load_lds_dwordx4 v[234:235], off
	v_lshl_add_u64 v[234:235], s[12:13], 0, v[0:1]
	s_mov_b32 m0, s16
	s_nop 0
	global_load_lds_dwordx4 v[234:235], off
	v_lshl_add_u64 v[234:235], s[12:13], 0, v[138:139]
	s_add_i32 m0, s16, 0x2000
	s_nop 0
	global_load_lds_dwordx4 v[234:235], off
	v_lshl_add_u64 v[234:235], v[238:239], 0, s[36:37]
	s_mov_b32 m0, s27
	s_nop 0
	global_load_lds_dwordx4 v[234:235], off
	v_lshl_add_u64 v[234:235], v[240:241], 0, s[36:37]
	s_mov_b32 m0, s30
	s_nop 0
	global_load_lds_dwordx4 v[234:235], off
	s_waitcnt vmcnt(8)
	s_waitcnt lgkmcnt(0)
	s_barrier
	s_waitcnt lgkmcnt(0)
	v_mfma_f32_16x16x32_f16 v[66:69], v[144:147], v[202:205], v[66:69]
	v_mfma_f32_16x16x32_f16 v[62:65], v[178:181], v[202:205], v[62:65]
	v_mfma_f32_16x16x32_f16 v[50:53], v[144:147], v[210:213], v[50:53]
	v_mfma_f32_16x16x32_f16 v[46:49], v[178:181], v[210:213], v[46:49]
	v_mfma_f32_16x16x32_f16 v[34:37], v[144:147], v[218:221], v[34:37]
	v_mfma_f32_16x16x32_f16 v[30:33], v[178:181], v[218:221], v[30:33]
	v_mfma_f32_16x16x32_f16 v[18:21], v[144:147], v[226:229], v[18:21]
	v_mfma_f32_16x16x32_f16 v[14:17], v[178:181], v[226:229], v[14:17]
	v_mfma_f32_16x16x32_f16 v[66:69], v[152:155], v[206:209], v[66:69]
	v_mfma_f32_16x16x32_f16 v[62:65], v[182:185], v[206:209], v[62:65]
	v_mfma_f32_16x16x32_f16 v[50:53], v[152:155], v[214:217], v[50:53]
	v_mfma_f32_16x16x32_f16 v[46:49], v[182:185], v[214:217], v[46:49]
	v_mfma_f32_16x16x32_f16 v[34:37], v[152:155], v[222:225], v[34:37]
	v_mfma_f32_16x16x32_f16 v[30:33], v[182:185], v[222:225], v[30:33]
	v_mfma_f32_16x16x32_f16 v[18:21], v[152:155], v[230:233], v[18:21]
	v_mfma_f32_16x16x32_f16 v[14:17], v[182:185], v[230:233], v[14:17]
	v_mfma_f32_16x16x32_f16 v[58:61], v[186:189], v[202:205], v[58:61]
	v_mfma_f32_16x16x32_f16 v[54:57], v[194:197], v[202:205], v[54:57]
	v_mfma_f32_16x16x32_f16 v[42:45], v[186:189], v[210:213], v[42:45]
	v_mfma_f32_16x16x32_f16 v[38:41], v[194:197], v[210:213], v[38:41]
	v_mfma_f32_16x16x32_f16 v[26:29], v[186:189], v[218:221], v[26:29]
	v_mfma_f32_16x16x32_f16 v[22:25], v[194:197], v[218:221], v[22:25]
	v_mfma_f32_16x16x32_f16 v[10:13], v[186:189], v[226:229], v[10:13]
	v_mfma_f32_16x16x32_f16 v[6:9], v[194:197], v[226:229], v[6:9]
	v_mfma_f32_16x16x32_f16 v[58:61], v[190:193], v[206:209], v[58:61]
	v_mfma_f32_16x16x32_f16 v[54:57], v[198:201], v[206:209], v[54:57]
	v_mfma_f32_16x16x32_f16 v[42:45], v[190:193], v[214:217], v[42:45]
	v_mfma_f32_16x16x32_f16 v[38:41], v[198:201], v[214:217], v[38:41]
	v_mfma_f32_16x16x32_f16 v[26:29], v[190:193], v[222:225], v[26:29]
	v_mfma_f32_16x16x32_f16 v[22:25], v[198:201], v[222:225], v[22:25]
	v_mfma_f32_16x16x32_f16 v[10:13], v[190:193], v[230:233], v[10:13]
	v_mfma_f32_16x16x32_f16 v[6:9], v[198:201], v[230:233], v[6:9]
	s_barrier
	s_add_i32 s45, s45, 2
	s_add_u32 s43, s43, 0x100
	s_addc_u32 s44, s44, 0
	s_cmp_gt_u32 s45, 41
	s_mov_b64 s[12:13], s[14:15]
.LBB0_122:
	s_add_u32 s14, s12, 0x100
	s_addc_u32 s15, s13, 0
	s_add_i32 s46, 0, 0x10000
	s_cmp_eq_u32 s45, 40
	s_cselect_b32 s19, s9, s15
	s_cselect_b32 s18, s8, s14
	v_add_u32_e32 v177, s46, v148
	s_cselect_b32 s17, s42, s44
	s_cselect_b32 s16, s41, s43
	s_add_i32 s47, 0, 0x14000
	ds_read_b128 v[144:147], v177
	ds_read_b128 v[152:155], v177 offset:1024
	ds_read_b128 v[178:181], v177 offset:2048
	ds_read_b128 v[182:185], v177 offset:3072
	v_add_u32_e32 v177, s47, v148
	ds_read_b128 v[186:189], v177
	ds_read_b128 v[190:193], v177 offset:1024
	ds_read_b128 v[194:197], v177 offset:2048
	ds_read_b128 v[198:201], v177 offset:3072
	v_lshl_add_u64 v[234:235], s[12:13], 0, v[142:143]
	s_add_i32 m0, s22, 0xc000
	ds_read_b128 v[202:205], v151
	ds_read_b128 v[206:209], v151 offset:1024
	ds_read_b128 v[210:213], v151 offset:2048
	ds_read_b128 v[214:217], v151 offset:3072
	ds_read_b128 v[218:221], v151 offset:4096
	ds_read_b128 v[222:225], v151 offset:5120
	ds_read_b128 v[226:229], v151 offset:6144
	ds_read_b128 v[230:233], v151 offset:7168
	global_load_lds_dwordx4 v[234:235], off
	v_lshl_add_u64 v[234:235], s[12:13], 0, v[140:141]
	s_add_i32 m0, s22, 0xe000
	s_nop 0
	global_load_lds_dwordx4 v[234:235], off
	s_waitcnt vmcnt(8)
	s_waitcnt lgkmcnt(0)
	s_barrier
; #define STAGE(bufoff, gbase, voff) do { _Pragma("unroll") for (int _i = 0; _i < 2; ++_i) \
;     __builtin_amdgcn_global_load_lds((const unsigned*)((const char*)(gbase) + (voff)[_i]), (LAS unsigned*)(lds + (bufoff) + ldsw + _i * 8192), 16, 0, 0); } while (0)
; #define LDA(dst, b, h) do { _Pragma("unroll") for (int m = 0; m < 4; ++m) _Pragma("unroll") for (int k = 0; k < 2; ++k) dst[m][k] = *(const LAS half8*)(lds + SA(b, h) + aoff + m * 2048 + k * 1024); } while (0)
; #define LDB(dst, b, h) do { _Pragma("unroll") for (int n = 0; n < 2; ++n) _Pragma("unroll") for (int k = 0; k < 2; ++k) dst[n][k] = *(const LAS half8*)(lds + SB(b, h) + boff + n * 2048 + k * 1024); } while (0)
; #define MMA(ai, bj, At_, Bt_) do { __builtin_amdgcn_s_setprio(1); \
;     _Pragma("unroll") for (int m = 0; m < 4; ++m) _Pragma("unroll") for (int n = 0; n < 2; ++n) _Pragma("unroll") for (int k = 0; k < 2; ++k) \
;       acc[ai][bj][m][n] = MFMA16(Bt_[n][k], At_[m][k], acc[ai][bj][m][n]); \
;     __builtin_amdgcn_s_setprio(0); } while (0)
; #define WAIT_V(n) asm volatile("s_waitcnt vmcnt(" #n ")" ::: "memory")
; #define WAIT_L(n) asm volatile("s_waitcnt lgkmcnt(" #n ")" ::: "memory")
; #define BAR __builtin_amdgcn_s_barrier()
; #define SCHED __builtin_amdgcn_sched_barrier(0)
; template <int EPI>
; DI void gemm_phase(const int wid_s, const h16* __restrict__ A, const h16* __restrict__ Bt, const int N, const int K, const EpiArgs ea) {
;     ...
;       LDB(B0, 0, 0); LDB(B1, 0, 1); SCHED; LDA(At, 0, 0); STAGE(SA(1, 1), a1 + hstep, voffA);
;       WAIT_V(8); WAIT_L(0); BAR; MMA(0, 0, At, B0); MMA(0, 1, At, B1); BAR; SCHED;
;       LDA(At, 0, 1); STAGE(SB(0, 0), b2, voffB); STAGE(SB(0, 1), b2 + hstep, voffB); STAGE(SA(0, 0), a2, voffA);
;       WAIT_V(8); WAIT_L(0); BAR; MMA(1, 0, At, B0); MMA(1, 1, At, B1); BAR; SCHED;
	s_waitcnt lgkmcnt(0)
	v_mfma_f32_16x16x32_f16 v[130:133], v[144:147], v[202:205], v[130:133]
	v_mfma_f32_16x16x32_f16 v[126:129], v[178:181], v[202:205], v[126:129]
	v_mfma_f32_16x16x32_f16 v[114:117], v[144:147], v[210:213], v[114:117]
	v_mfma_f32_16x16x32_f16 v[110:113], v[178:181], v[210:213], v[110:113]
	v_mfma_f32_16x16x32_f16 v[98:101], v[144:147], v[218:221], v[98:101]
	v_mfma_f32_16x16x32_f16 v[94:97], v[178:181], v[218:221], v[94:97]
	v_mfma_f32_16x16x32_f16 v[82:85], v[144:147], v[226:229], v[82:85]
	v_mfma_f32_16x16x32_f16 v[78:81], v[178:181], v[226:229], v[78:81]
	v_mfma_f32_16x16x32_f16 v[130:133], v[152:155], v[206:209], v[130:133]
	v_mfma_f32_16x16x32_f16 v[126:129], v[182:185], v[206:209], v[126:129]
	v_mfma_f32_16x16x32_f16 v[114:117], v[152:155], v[214:217], v[114:117]
	v_mfma_f32_16x16x32_f16 v[110:113], v[182:185], v[214:217], v[110:113]
	v_mfma_f32_16x16x32_f16 v[98:101], v[152:155], v[222:225], v[98:101]
	v_mfma_f32_16x16x32_f16 v[94:97], v[182:185], v[222:225], v[94:97]
	v_mfma_f32_16x16x32_f16 v[82:85], v[152:155], v[230:233], v[82:85]
	v_mfma_f32_16x16x32_f16 v[78:81], v[182:185], v[230:233], v[78:81]
	s_add_i32 s12, s46, s21
	v_lshl_add_u64 v[234:235], s[16:17], 0, v[0:1]
	s_mov_b32 m0, s12
	v_mfma_f32_16x16x32_f16 v[122:125], v[186:189], v[202:205], v[122:125]
	v_mfma_f32_16x16x32_f16 v[118:121], v[194:197], v[202:205], v[118:121]
	v_mfma_f32_16x16x32_f16 v[106:109], v[186:189], v[210:213], v[106:109]
	v_mfma_f32_16x16x32_f16 v[102:105], v[194:197], v[210:213], v[102:105]
	v_mfma_f32_16x16x32_f16 v[90:93], v[186:189], v[218:221], v[90:93]
	v_mfma_f32_16x16x32_f16 v[86:89], v[194:197], v[218:221], v[86:89]
	v_mfma_f32_16x16x32_f16 v[74:77], v[186:189], v[226:229], v[74:77]
	v_mfma_f32_16x16x32_f16 v[70:73], v[194:197], v[226:229], v[70:73]
	v_mfma_f32_16x16x32_f16 v[122:125], v[190:193], v[206:209], v[122:125]
	v_mfma_f32_16x16x32_f16 v[118:121], v[198:201], v[206:209], v[118:121]
	v_mfma_f32_16x16x32_f16 v[106:109], v[190:193], v[214:217], v[106:109]
	v_mfma_f32_16x16x32_f16 v[102:105], v[198:201], v[214:217], v[102:105]
	v_mfma_f32_16x16x32_f16 v[90:93], v[190:193], v[222:225], v[90:93]
	v_mfma_f32_16x16x32_f16 v[86:89], v[198:201], v[222:225], v[86:89]
	v_mfma_f32_16x16x32_f16 v[74:77], v[190:193], v[230:233], v[74:77]
	v_mfma_f32_16x16x32_f16 v[70:73], v[198:201], v[230:233], v[70:73]
	s_barrier
	ds_read_b128 v[202:205], v151 offset:16384
	ds_read_b128 v[206:209], v151 offset:17408
	ds_read_b128 v[210:213], v151 offset:18432
	ds_read_b128 v[214:217], v151 offset:19456
	ds_read_b128 v[218:221], v151 offset:20480
	ds_read_b128 v[222:225], v151 offset:21504
	ds_read_b128 v[226:229], v151 offset:22528
	ds_read_b128 v[230:233], v151 offset:23552
	global_load_lds_dwordx4 v[234:235], off
	s_add_i32 m0, s12, 0x2000
	s_add_u32 s12, s16, 0xb0000
	v_lshl_add_u64 v[236:237], s[16:17], 0, v[138:139]
	s_addc_u32 s13, s17, 0
	s_add_i32 s46, s47, s21
	global_load_lds_dwordx4 v[236:237], off
	v_lshl_add_u64 v[238:239], s[12:13], 0, v[0:1]
	s_mov_b32 m0, s46
	v_lshl_add_u64 v[240:241], s[18:19], 0, v[134:135]
	global_load_lds_dwordx4 v[238:239], off
	v_lshl_add_u64 v[238:239], s[12:13], 0, v[138:139]
	s_add_i32 m0, s46, 0x2000
	s_nop 0
	global_load_lds_dwordx4 v[238:239], off
	v_lshl_add_u64 v[238:239], s[18:19], 0, v[2:3]
	s_mov_b32 m0, s22
	s_nop 0
	global_load_lds_dwordx4 v[238:239], off
	s_mov_b32 m0, s23
	s_nop 0
	global_load_lds_dwordx4 v[240:241], off
	s_waitcnt vmcnt(8)
	s_waitcnt lgkmcnt(0)
	s_barrier
	s_waitcnt lgkmcnt(0)
	v_mfma_f32_16x16x32_f16 v[66:69], v[144:147], v[202:205], v[66:69]
	v_mfma_f32_16x16x32_f16 v[62:65], v[178:181], v[202:205], v[62:65]
	v_mfma_f32_16x16x32_f16 v[50:53], v[144:147], v[210:213], v[50:53]
	v_mfma_f32_16x16x32_f16 v[46:49], v[178:181], v[210:213], v[46:49]
	v_mfma_f32_16x16x32_f16 v[34:37], v[144:147], v[218:221], v[34:37]
	v_mfma_f32_16x16x32_f16 v[30:33], v[178:181], v[218:221], v[30:33]
	v_mfma_f32_16x16x32_f16 v[18:21], v[144:147], v[226:229], v[18:21]
	v_mfma_f32_16x16x32_f16 v[14:17], v[178:181], v[226:229], v[14:17]
	v_mfma_f32_16x16x32_f16 v[66:69], v[152:155], v[206:209], v[66:69]
	v_mfma_f32_16x16x32_f16 v[62:65], v[182:185], v[206:209], v[62:65]
	v_mfma_f32_16x16x32_f16 v[50:53], v[152:155], v[214:217], v[50:53]
	v_mfma_f32_16x16x32_f16 v[46:49], v[182:185], v[214:217], v[46:49]
	v_mfma_f32_16x16x32_f16 v[34:37], v[152:155], v[222:225], v[34:37]
	v_mfma_f32_16x16x32_f16 v[30:33], v[182:185], v[222:225], v[30:33]
	v_mfma_f32_16x16x32_f16 v[18:21], v[152:155], v[230:233], v[18:21]
	v_mfma_f32_16x16x32_f16 v[14:17], v[182:185], v[230:233], v[14:17]
	s_add_i32 s46, 0, 0x18000
	v_add_u32_e32 v177, s46, v148
	s_add_i32 s47, 0, 0x1c000
	v_mfma_f32_16x16x32_f16 v[58:61], v[186:189], v[202:205], v[58:61]
	v_mfma_f32_16x16x32_f16 v[54:57], v[194:197], v[202:205], v[54:57]
	v_mfma_f32_16x16x32_f16 v[42:45], v[186:189], v[210:213], v[42:45]
	v_mfma_f32_16x16x32_f16 v[38:41], v[194:197], v[210:213], v[38:41]
	v_mfma_f32_16x16x32_f16 v[26:29], v[186:189], v[218:221], v[26:29]
	v_mfma_f32_16x16x32_f16 v[22:25], v[194:197], v[218:221], v[22:25]
	v_mfma_f32_16x16x32_f16 v[10:13], v[186:189], v[226:229], v[10:13]
	v_mfma_f32_16x16x32_f16 v[6:9], v[194:197], v[226:229], v[6:9]
	v_mfma_f32_16x16x32_f16 v[58:61], v[190:193], v[206:209], v[58:61]
	v_mfma_f32_16x16x32_f16 v[54:57], v[198:201], v[206:209], v[54:57]
	v_mfma_f32_16x16x32_f16 v[42:45], v[190:193], v[214:217], v[42:45]
	v_mfma_f32_16x16x32_f16 v[38:41], v[198:201], v[214:217], v[38:41]
	v_mfma_f32_16x16x32_f16 v[26:29], v[190:193], v[222:225], v[26:29]
	v_mfma_f32_16x16x32_f16 v[22:25], v[198:201], v[222:225], v[22:25]
	v_mfma_f32_16x16x32_f16 v[10:13], v[190:193], v[230:233], v[10:13]
	v_mfma_f32_16x16x32_f16 v[6:9], v[198:201], v[230:233], v[6:9]
	s_barrier
; #define STAGE(bufoff, gbase, voff) do { _Pragma("unroll") for (int _i = 0; _i < 2; ++_i) \
;     __builtin_amdgcn_global_load_lds((const unsigned*)((const char*)(gbase) + (voff)[_i]), (LAS unsigned*)(lds + (bufoff) + ldsw + _i * 8192), 16, 0, 0); } while (0)
; #define LDA(dst, b, h) do { _Pragma("unroll") for (int m = 0; m < 4; ++m) _Pragma("unroll") for (int k = 0; k < 2; ++k) dst[m][k] = *(const LAS half8*)(lds + SA(b, h) + aoff + m * 2048 + k * 1024); } while (0)
; #define LDB(dst, b, h) do { _Pragma("unroll") for (int n = 0; n < 2; ++n) _Pragma("unroll") for (int k = 0; k < 2; ++k) dst[n][k] = *(const LAS half8*)(lds + SB(b, h) + boff + n * 2048 + k * 1024); } while (0)
; #define MMA(ai, bj, At_, Bt_) do { __builtin_amdgcn_s_setprio(1); \
;     _Pragma("unroll") for (int m = 0; m < 4; ++m) _Pragma("unroll") for (int n = 0; n < 2; ++n) _Pragma("unroll") for (int k = 0; k < 2; ++k) \
;       acc[ai][bj][m][n] = MFMA16(Bt_[n][k], At_[m][k], acc[ai][bj][m][n]); \
;     __builtin_amdgcn_s_setprio(0); } while (0)
; #define WAIT_V(n) asm volatile("s_waitcnt vmcnt(" #n ")" ::: "memory")
; #define WAIT_L(n) asm volatile("s_waitcnt lgkmcnt(" #n ")" ::: "memory")
; #define BAR __builtin_amdgcn_s_barrier()
; #define SCHED __builtin_amdgcn_sched_barrier(0)
; template <int EPI>
; DI void gemm_phase(const int wid_s, const h16* __restrict__ A, const h16* __restrict__ Bt, const int N, const int K, const EpiArgs ea) {
;     ...
;       LDB(B0, 1, 0); LDB(B1, 1, 1); SCHED; LDA(At, 1, 0); STAGE(SA(0, 1), a2 + hstep, voffA);
;       WAIT_V(8); WAIT_L(0); BAR; MMA(0, 0, At, B0); MMA(0, 1, At, B1); BAR; SCHED;
;       LDA(At, 1, 1); STAGE(SB(1, 0), b3, voffB); STAGE(SB(1, 1), b3 + hstep, voffB); STAGE(SA(1, 0), a3, voffA);
;       WAIT_V(8); WAIT_L(0); BAR; MMA(1, 0, At, B0); MMA(1, 1, At, B1); BAR; SCHED;
;     }
;     if (wr == 0) BAR;
	ds_read_b128 v[144:147], v177
	ds_read_b128 v[152:155], v177 offset:1024
	ds_read_b128 v[178:181], v177 offset:2048
	ds_read_b128 v[182:185], v177 offset:3072
	v_add_u32_e32 v177, s47, v148
	ds_read_b128 v[186:189], v177
	ds_read_b128 v[190:193], v177 offset:1024
	ds_read_b128 v[194:197], v177 offset:2048
	ds_read_b128 v[198:201], v177 offset:3072
	s_add_u32 s12, s18, 0xb0000
	s_addc_u32 s13, s19, 0
	s_mov_b32 m0, s24
	v_lshl_add_u64 v[242:243], s[12:13], 0, v[2:3]
	ds_read_b128 v[202:205], v151 offset:32768
	ds_read_b128 v[206:209], v151 offset:33792
	ds_read_b128 v[210:213], v151 offset:34816
	ds_read_b128 v[214:217], v151 offset:35840
	ds_read_b128 v[218:221], v151 offset:36864
	ds_read_b128 v[222:225], v151 offset:37888
	ds_read_b128 v[226:229], v151 offset:38912
	ds_read_b128 v[230:233], v151 offset:39936
	global_load_lds_dwordx4 v[242:243], off
	v_lshl_add_u64 v[242:243], s[12:13], 0, v[134:135]
	s_mov_b32 m0, s26
	s_nop 0
	global_load_lds_dwordx4 v[242:243], off
	s_waitcnt vmcnt(8)
	s_waitcnt lgkmcnt(0)
	s_barrier
	s_waitcnt lgkmcnt(0)
	v_mfma_f32_16x16x32_f16 v[130:133], v[144:147], v[202:205], v[130:133]
	v_mfma_f32_16x16x32_f16 v[126:129], v[178:181], v[202:205], v[126:129]
	v_mfma_f32_16x16x32_f16 v[114:117], v[144:147], v[210:213], v[114:117]
	v_mfma_f32_16x16x32_f16 v[110:113], v[178:181], v[210:213], v[110:113]
	v_mfma_f32_16x16x32_f16 v[98:101], v[144:147], v[218:221], v[98:101]
	v_mfma_f32_16x16x32_f16 v[94:97], v[178:181], v[218:221], v[94:97]
	v_mfma_f32_16x16x32_f16 v[82:85], v[144:147], v[226:229], v[82:85]
	v_mfma_f32_16x16x32_f16 v[78:81], v[178:181], v[226:229], v[78:81]
	v_mfma_f32_16x16x32_f16 v[130:133], v[152:155], v[206:209], v[130:133]
	v_mfma_f32_16x16x32_f16 v[126:129], v[182:185], v[206:209], v[126:129]
	v_mfma_f32_16x16x32_f16 v[114:117], v[152:155], v[214:217], v[114:117]
	v_mfma_f32_16x16x32_f16 v[110:113], v[182:185], v[214:217], v[110:113]
	v_mfma_f32_16x16x32_f16 v[98:101], v[152:155], v[222:225], v[98:101]
	v_mfma_f32_16x16x32_f16 v[94:97], v[182:185], v[222:225], v[94:97]
	v_mfma_f32_16x16x32_f16 v[82:85], v[152:155], v[230:233], v[82:85]
	v_mfma_f32_16x16x32_f16 v[78:81], v[182:185], v[230:233], v[78:81]
	s_add_i32 s12, s46, s21
	v_lshl_add_u64 v[234:235], v[234:235], 0, s[36:37]
	s_mov_b32 m0, s12
	v_mfma_f32_16x16x32_f16 v[122:125], v[186:189], v[202:205], v[122:125]
	v_mfma_f32_16x16x32_f16 v[118:121], v[194:197], v[202:205], v[118:121]
	v_mfma_f32_16x16x32_f16 v[106:109], v[186:189], v[210:213], v[106:109]
	v_mfma_f32_16x16x32_f16 v[102:105], v[194:197], v[210:213], v[102:105]
	v_mfma_f32_16x16x32_f16 v[90:93], v[186:189], v[218:221], v[90:93]
	v_mfma_f32_16x16x32_f16 v[86:89], v[194:197], v[218:221], v[86:89]
	v_mfma_f32_16x16x32_f16 v[74:77], v[186:189], v[226:229], v[74:77]
	v_mfma_f32_16x16x32_f16 v[70:73], v[194:197], v[226:229], v[70:73]
	v_mfma_f32_16x16x32_f16 v[122:125], v[190:193], v[206:209], v[122:125]
	v_mfma_f32_16x16x32_f16 v[118:121], v[198:201], v[206:209], v[118:121]
	v_mfma_f32_16x16x32_f16 v[106:109], v[190:193], v[214:217], v[106:109]
	v_mfma_f32_16x16x32_f16 v[102:105], v[198:201], v[214:217], v[102:105]
	v_mfma_f32_16x16x32_f16 v[90:93], v[190:193], v[222:225], v[90:93]
	v_mfma_f32_16x16x32_f16 v[86:89], v[198:201], v[222:225], v[86:89]
	v_mfma_f32_16x16x32_f16 v[74:77], v[190:193], v[230:233], v[74:77]
	v_mfma_f32_16x16x32_f16 v[70:73], v[198:201], v[230:233], v[70:73]
	s_barrier
	ds_read_b128 v[202:205], v151 offset:49152
	ds_read_b128 v[206:209], v151 offset:50176
	ds_read_b128 v[210:213], v151 offset:51200
	ds_read_b128 v[214:217], v151 offset:52224
	ds_read_b128 v[218:221], v151 offset:53248
	ds_read_b128 v[222:225], v151 offset:54272
	ds_read_b128 v[226:229], v151 offset:55296
	ds_read_b128 v[230:233], v151 offset:56320
	global_load_lds_dwordx4 v[234:235], off
	s_add_i32 m0, s12, 0x2000
	s_add_u32 s12, s16, 0xb0080
	v_lshl_add_u64 v[234:235], v[236:237], 0, s[36:37]
	s_addc_u32 s13, s17, 0
	s_add_i32 s16, s47, s21
	global_load_lds_dwordx4 v[234:235], off
	v_lshl_add_u64 v[234:235], s[12:13], 0, v[0:1]
	s_mov_b32 m0, s16
	s_nop 0
	global_load_lds_dwordx4 v[234:235], off
	v_lshl_add_u64 v[234:235], s[12:13], 0, v[138:139]
	s_add_i32 m0, s16, 0x2000
	s_nop 0
	global_load_lds_dwordx4 v[234:235], off
	v_lshl_add_u64 v[234:235], v[238:239], 0, s[36:37]
	s_mov_b32 m0, s27
	s_nop 0
	global_load_lds_dwordx4 v[234:235], off
	v_lshl_add_u64 v[234:235], v[240:241], 0, s[36:37]
	s_mov_b32 m0, s30
	s_nop 0
	global_load_lds_dwordx4 v[234:235], off
	s_waitcnt vmcnt(8)
	s_waitcnt lgkmcnt(0)
	s_barrier
	s_waitcnt lgkmcnt(0)
	v_mfma_f32_16x16x32_f16 v[66:69], v[144:147], v[202:205], v[66:69]
	v_mfma_f32_16x16x32_f16 v[62:65], v[178:181], v[202:205], v[62:65]
	v_mfma_f32_16x16x32_f16 v[50:53], v[144:147], v[210:213], v[50:53]
	v_mfma_f32_16x16x32_f16 v[46:49], v[178:181], v[210:213], v[46:49]
	v_mfma_f32_16x16x32_f16 v[34:37], v[144:147], v[218:221], v[34:37]
	v_mfma_f32_16x16x32_f16 v[30:33], v[178:181], v[218:221], v[30:33]
	v_mfma_f32_16x16x32_f16 v[18:21], v[144:147], v[226:229], v[18:21]
	v_mfma_f32_16x16x32_f16 v[14:17], v[178:181], v[226:229], v[14:17]
	v_mfma_f32_16x16x32_f16 v[66:69], v[152:155], v[206:209], v[66:69]
	v_mfma_f32_16x16x32_f16 v[62:65], v[182:185], v[206:209], v[62:65]
	v_mfma_f32_16x16x32_f16 v[50:53], v[152:155], v[214:217], v[50:53]
	v_mfma_f32_16x16x32_f16 v[46:49], v[182:185], v[214:217], v[46:49]
	v_mfma_f32_16x16x32_f16 v[34:37], v[152:155], v[222:225], v[34:37]
	v_mfma_f32_16x16x32_f16 v[30:33], v[182:185], v[222:225], v[30:33]
	v_mfma_f32_16x16x32_f16 v[18:21], v[152:155], v[230:233], v[18:21]
	v_mfma_f32_16x16x32_f16 v[14:17], v[182:185], v[230:233], v[14:17]
	v_mfma_f32_16x16x32_f16 v[58:61], v[186:189], v[202:205], v[58:61]
	v_mfma_f32_16x16x32_f16 v[54:57], v[194:197], v[202:205], v[54:57]
	v_mfma_f32_16x16x32_f16 v[42:45], v[186:189], v[210:213], v[42:45]
	v_mfma_f32_16x16x32_f16 v[38:41], v[194:197], v[210:213], v[38:41]
	v_mfma_f32_16x16x32_f16 v[26:29], v[186:189], v[218:221], v[26:29]
	v_mfma_f32_16x16x32_f16 v[22:25], v[194:197], v[218:221], v[22:25]
	v_mfma_f32_16x16x32_f16 v[10:13], v[186:189], v[226:229], v[10:13]
	v_mfma_f32_16x16x32_f16 v[6:9], v[194:197], v[226:229], v[6:9]
	v_mfma_f32_16x16x32_f16 v[58:61], v[190:193], v[206:209], v[58:61]
	v_mfma_f32_16x16x32_f16 v[54:57], v[198:201], v[206:209], v[54:57]
	v_mfma_f32_16x16x32_f16 v[42:45], v[190:193], v[214:217], v[42:45]
	v_mfma_f32_16x16x32_f16 v[38:41], v[198:201], v[214:217], v[38:41]
	v_mfma_f32_16x16x32_f16 v[26:29], v[190:193], v[222:225], v[26:29]
	v_mfma_f32_16x16x32_f16 v[22:25], v[198:201], v[222:225], v[22:25]
	v_mfma_f32_16x16x32_f16 v[10:13], v[190:193], v[230:233], v[10:13]
	v_mfma_f32_16x16x32_f16 v[6:9], v[198:201], v[230:233], v[6:9]
	s_barrier
	s_add_i32 s45, s45, 2
	s_add_u32 s43, s43, 0x100
	s_addc_u32 s44, s44, 0
	s_cmp_gt_u32 s45, 41
	s_mov_b64 s[12:13], s[14:15]
	s_cbranch_scc0 .LBB0_122
	s_and_b64 vcc, exec, s[4:5]
	s_cbranch_vccz .LBB0_125
	s_barrier

; #define STAGE(bufoff, gbase, voff) do { _Pragma("unroll") for (int _i = 0; _i < 2; ++_i) \
;     __builtin_amdgcn_global_load_lds((const unsigned*)((const char*)(gbase) + (voff)[_i]), (LAS unsigned*)(lds + (bufoff) + ldsw + _i * 8192), 16, 0, 0); } while (0)
; #define LDA(dst, b, h) do { _Pragma("unroll") for (int m = 0; m < 4; ++m) _Pragma("unroll") for (int k = 0; k < 2; ++k) dst[m][k] = *(const LAS half8*)(lds + SA(b, h) + aoff + m * 2048 + k * 1024); } while (0)
; #define LDB(dst, b, h) do { _Pragma("unroll") for (int n = 0; n < 2; ++n) _Pragma("unroll") for (int k = 0; k < 2; ++k) dst[n][k] = *(const LAS half8*)(lds + SB(b, h) + boff + n * 2048 + k * 1024); } while (0)
; #define MMA(ai, bj, At_, Bt_) do { __builtin_amdgcn_s_setprio(1); \
;     _Pragma("unroll") for (int m = 0; m < 4; ++m) _Pragma("unroll") for (int n = 0; n < 2; ++n) _Pragma("unroll") for (int k = 0; k < 2; ++k) \
;       acc[ai][bj][m][n] = MFMA16(Bt_[n][k], At_[m][k], acc[ai][bj][m][n]); \
;     __builtin_amdgcn_s_setprio(0); } while (0)
; #define WAIT_V(n) asm volatile("s_waitcnt vmcnt(" #n ")" ::: "memory")
; #define WAIT_L(n) asm volatile("s_waitcnt lgkmcnt(" #n ")" ::: "memory")
; #define BAR __builtin_amdgcn_s_barrier()
; #define SCHED __builtin_amdgcn_sched_barrier(0)
; template <int EPI>
; DI void gemm_phase(const int wid_s, const h16* __restrict__ A, const h16* __restrict__ Bt, const int N, const int K, const EpiArgs ea) {
;     ...
;     const char* nA = (const char*)A + (size_t)nbrow * K * 2;
;     const char* nB = (const char*)Bt + (size_t)nbcol * K * 2;
;     for (int t = 0; t < nt; t += 2) {
;       const bool last = (t == nt - 2);
;       const char* a1 = cA + (size_t)(t + 1) * kstep;
;       const char* a2 = last ? nA : cA + (size_t)(t + 2) * kstep; const char* b2 = last ? nB : cB + (size_t)(t + 2) * kstep;
;       const char* a3 = a2 + kstep; const char* b3 = b2 + kstep;
;       LDB(B0, 0, 0); LDB(B1, 0, 1); SCHED; LDA(At, 0, 0); STAGE(SA(1, 1), a1 + hstep, voffA);
;       WAIT_V(8); WAIT_L(0); BAR; MMA(0, 0, At, B0); MMA(0, 1, At, B1); BAR; SCHED;
;       LDA(At, 0, 1); STAGE(SB(0, 0), b2, voffB); STAGE(SB(0, 1), b2 + hstep, voffB); STAGE(SA(0, 0), a2, voffA);
.LBB0_140:
	s_ashr_i32 s9, s8, 31
	s_lshl_b64 s[12:13], s[8:9], 11
	s_add_u32 s9, s92, s12
	s_addc_u32 s42, s93, s13
	s_ashr_i32 s11, s10, 31
	s_lshl_b64 s[14:15], s[10:11], 11
	v_readlane_b32 s11, v250, 62
	s_add_u32 s11, s11, s14
	v_readlane_b32 s26, v249, 1
	s_addc_u32 s43, s26, s15
	v_readlane_b32 s26, v249, 23
	s_add_u32 s44, s26, s22
	v_readlane_b32 s22, v249, 24
	s_addc_u32 s45, s22, s23
	s_add_u32 s46, s86, s20
	v_mov_b32_e32 v6, 0
	v_lshl_add_u64 v[144:145], v[140:141], 0, s[20:21]
	v_lshl_add_u64 v[146:147], v[142:143], 0, s[20:21]
	s_addc_u32 s47, s87, s21
	s_mov_b32 s48, -2
	s_mov_b64 s[20:21], 0
	s_add_u32 s22, s46, s20
	s_addc_u32 s23, s47, s21
	s_add_u32 s22, s22, 0x520e100
	s_addc_u32 s23, s23, 0
	s_add_u32 s49, s44, s20
	s_addc_u32 s50, s45, s21
	s_add_i32 s51, 0, 0x10000
	s_cmpk_eq_i32 s20, 0x700
	s_cselect_b32 s27, s42, s23
	s_cselect_b32 s26, s9, s22
	v_add_u32_e32 v177, s51, v148
	s_cselect_b32 s23, s43, s50
	s_cselect_b32 s22, s11, s49
	s_add_i32 s49, 0, 0x14000
	ds_read_b128 v[152:155], v177
	ds_read_b128 v[178:181], v177 offset:1024
	ds_read_b128 v[182:185], v177 offset:2048
	ds_read_b128 v[186:189], v177 offset:3072
	v_add_u32_e32 v177, s49, v148
	ds_read_b128 v[190:193], v177
	ds_read_b128 v[194:197], v177 offset:1024
	ds_read_b128 v[198:201], v177 offset:2048
	ds_read_b128 v[202:205], v177 offset:3072
	v_lshl_add_u64 v[238:239], v[146:147], 0, s[20:21]
	s_add_i32 m0, s17, 0xc000
	ds_read_b128 v[206:209], v151
	ds_read_b128 v[210:213], v151 offset:1024
	ds_read_b128 v[214:217], v151 offset:2048
	ds_read_b128 v[218:221], v151 offset:3072
	ds_read_b128 v[222:225], v151 offset:4096
	ds_read_b128 v[226:229], v151 offset:5120
	ds_read_b128 v[230:233], v151 offset:6144
	ds_read_b128 v[234:237], v151 offset:7168
	global_load_lds_dwordx4 v[238:239], off
	v_lshl_add_u64 v[238:239], v[144:145], 0, s[20:21]
	s_add_i32 m0, s17, 0xe000
	s_nop 0
	global_load_lds_dwordx4 v[238:239], off
	s_waitcnt vmcnt(8)
	s_waitcnt lgkmcnt(0)
	s_barrier
	s_waitcnt lgkmcnt(0)
	v_mfma_f32_16x16x32_f16 v[130:133], v[152:155], v[206:209], 0
	v_mfma_f32_16x16x32_f16 v[126:129], v[182:185], v[206:209], 0
	v_mfma_f32_16x16x32_f16 v[114:117], v[152:155], v[214:217], 0
	v_mfma_f32_16x16x32_f16 v[110:113], v[182:185], v[214:217], 0
	v_mfma_f32_16x16x32_f16 v[98:101], v[152:155], v[222:225], 0
	v_mfma_f32_16x16x32_f16 v[94:97], v[182:185], v[222:225], 0
	v_mfma_f32_16x16x32_f16 v[82:85], v[152:155], v[230:233], 0
	v_mfma_f32_16x16x32_f16 v[78:81], v[182:185], v[230:233], 0
	v_mfma_f32_16x16x32_f16 v[130:133], v[178:181], v[210:213], v[130:133]
	v_mfma_f32_16x16x32_f16 v[126:129], v[186:189], v[210:213], v[126:129]
	v_mfma_f32_16x16x32_f16 v[114:117], v[178:181], v[218:221], v[114:117]
	v_mfma_f32_16x16x32_f16 v[110:113], v[186:189], v[218:221], v[110:113]
	v_mfma_f32_16x16x32_f16 v[98:101], v[178:181], v[226:229], v[98:101]
	v_mfma_f32_16x16x32_f16 v[94:97], v[186:189], v[226:229], v[94:97]
	v_mfma_f32_16x16x32_f16 v[82:85], v[178:181], v[234:237], v[82:85]
	v_mfma_f32_16x16x32_f16 v[78:81], v[186:189], v[234:237], v[78:81]
	s_add_i32 s50, s51, s30
	v_lshl_add_u64 v[238:239], s[22:23], 0, v[0:1]
	s_mov_b32 m0, s50
	v_mfma_f32_16x16x32_f16 v[122:125], v[190:193], v[206:209], 0
	v_mfma_f32_16x16x32_f16 v[118:121], v[198:201], v[206:209], 0
	v_mfma_f32_16x16x32_f16 v[106:109], v[190:193], v[214:217], 0
	v_mfma_f32_16x16x32_f16 v[102:105], v[198:201], v[214:217], 0
	v_mfma_f32_16x16x32_f16 v[90:93], v[190:193], v[222:225], 0
	v_mfma_f32_16x16x32_f16 v[86:89], v[198:201], v[222:225], 0
	v_mfma_f32_16x16x32_f16 v[74:77], v[190:193], v[230:233], 0
	v_mfma_f32_16x16x32_f16 v[70:73], v[198:201], v[230:233], 0
	v_mfma_f32_16x16x32_f16 v[122:125], v[194:197], v[210:213], v[122:125]
	v_mfma_f32_16x16x32_f16 v[118:121], v[202:205], v[210:213], v[118:121]
	v_mfma_f32_16x16x32_f16 v[106:109], v[194:197], v[218:221], v[106:109]
	v_mfma_f32_16x16x32_f16 v[102:105], v[202:205], v[218:221], v[102:105]
	v_mfma_f32_16x16x32_f16 v[90:93], v[194:197], v[226:229], v[90:93]
	v_mfma_f32_16x16x32_f16 v[86:89], v[202:205], v[226:229], v[86:89]
	v_mfma_f32_16x16x32_f16 v[74:77], v[194:197], v[234:237], v[74:77]
	v_mfma_f32_16x16x32_f16 v[70:73], v[202:205], v[234:237], v[70:73]
	s_barrier
	ds_read_b128 v[206:209], v151 offset:16384
	ds_read_b128 v[210:213], v151 offset:17408
	ds_read_b128 v[214:217], v151 offset:18432
	ds_read_b128 v[218:221], v151 offset:19456
	ds_read_b128 v[222:225], v151 offset:20480
	ds_read_b128 v[226:229], v151 offset:21504
	ds_read_b128 v[230:233], v151 offset:22528
	ds_read_b128 v[234:237], v151 offset:23552
	global_load_lds_dwordx4 v[238:239], off
	s_add_i32 m0, s50, 0x2000
	s_add_u32 s50, s22, 0x40000
	v_lshl_add_u64 v[240:241], s[22:23], 0, v[2:3]
	s_addc_u32 s51, s23, 0
	s_add_i32 s49, s49, s30
	global_load_lds_dwordx4 v[240:241], off
	v_lshl_add_u64 v[242:243], s[50:51], 0, v[0:1]
	s_mov_b32 m0, s49
	v_lshl_add_u64 v[244:245], s[26:27], 0, v[134:135]
	global_load_lds_dwordx4 v[242:243], off
	v_lshl_add_u64 v[242:243], s[50:51], 0, v[2:3]
	s_add_i32 m0, s49, 0x2000
	s_nop 0
	global_load_lds_dwordx4 v[242:243], off
	v_lshl_add_u64 v[242:243], s[26:27], 0, v[138:139]
	s_mov_b32 m0, s17
	s_nop 0
	global_load_lds_dwordx4 v[242:243], off
	s_mov_b32 m0, s19
	s_nop 0
	global_load_lds_dwordx4 v[244:245], off
	s_waitcnt vmcnt(8)
	s_waitcnt lgkmcnt(0)
	s_barrier
; #define STAGE(bufoff, gbase, voff) do { _Pragma("unroll") for (int _i = 0; _i < 2; ++_i) \
;     __builtin_amdgcn_global_load_lds((const unsigned*)((const char*)(gbase) + (voff)[_i]), (LAS unsigned*)(lds + (bufoff) + ldsw + _i * 8192), 16, 0, 0); } while (0)
; #define LDA(dst, b, h) do { _Pragma("unroll") for (int m = 0; m < 4; ++m) _Pragma("unroll") for (int k = 0; k < 2; ++k) dst[m][k] = *(const LAS half8*)(lds + SA(b, h) + aoff + m * 2048 + k * 1024); } while (0)
; #define LDB(dst, b, h) do { _Pragma("unroll") for (int n = 0; n < 2; ++n) _Pragma("unroll") for (int k = 0; k < 2; ++k) dst[n][k] = *(const LAS half8*)(lds + SB(b, h) + boff + n * 2048 + k * 1024); } while (0)
; #define MMA(ai, bj, At_, Bt_) do { __builtin_amdgcn_s_setprio(1); \
;     _Pragma("unroll") for (int m = 0; m < 4; ++m) _Pragma("unroll") for (int n = 0; n < 2; ++n) _Pragma("unroll") for (int k = 0; k < 2; ++k) \
;       acc[ai][bj][m][n] = MFMA16(Bt_[n][k], At_[m][k], acc[ai][bj][m][n]); \
;     __builtin_amdgcn_s_setprio(0); } while (0)
; #define WAIT_V(n) asm volatile("s_waitcnt vmcnt(" #n ")" ::: "memory")
; #define WAIT_L(n) asm volatile("s_waitcnt lgkmcnt(" #n ")" ::: "memory")
; #define BAR __builtin_amdgcn_s_barrier()
; #define SCHED __builtin_amdgcn_sched_barrier(0)
; template <int EPI>
; DI void gemm_phase(const int wid_s, const h16* __restrict__ A, const h16* __restrict__ Bt, const int N, const int K, const EpiArgs ea) {
;     ...
;       LDA(At, 0, 1); STAGE(SB(0, 0), b2, voffB); STAGE(SB(0, 1), b2 + hstep, voffB); STAGE(SA(0, 0), a2, voffA);
;       WAIT_V(8); WAIT_L(0); BAR; MMA(1, 0, At, B0); MMA(1, 1, At, B1); BAR; SCHED;
;       LDB(B0, 1, 0); LDB(B1, 1, 1); SCHED; LDA(At, 1, 0); STAGE(SA(0, 1), a2 + hstep, voffA);
;       WAIT_V(8); WAIT_L(0); BAR; MMA(0, 0, At, B0); MMA(0, 1, At, B1); BAR; SCHED;
	s_waitcnt lgkmcnt(0)
	v_mfma_f32_16x16x32_f16 v[66:69], v[152:155], v[206:209], 0
	v_mfma_f32_16x16x32_f16 v[62:65], v[182:185], v[206:209], 0
	v_mfma_f32_16x16x32_f16 v[50:53], v[152:155], v[214:217], 0
	v_mfma_f32_16x16x32_f16 v[46:49], v[182:185], v[214:217], 0
	v_mfma_f32_16x16x32_f16 v[34:37], v[152:155], v[222:225], 0
	v_mfma_f32_16x16x32_f16 v[30:33], v[182:185], v[222:225], 0
	v_mfma_f32_16x16x32_f16 v[18:21], v[152:155], v[230:233], 0
	v_mfma_f32_16x16x32_f16 v[14:17], v[182:185], v[230:233], 0
	v_mfma_f32_16x16x32_f16 v[66:69], v[178:181], v[210:213], v[66:69]
	v_mfma_f32_16x16x32_f16 v[62:65], v[186:189], v[210:213], v[62:65]
	v_mfma_f32_16x16x32_f16 v[50:53], v[178:181], v[218:221], v[50:53]
	v_mfma_f32_16x16x32_f16 v[46:49], v[186:189], v[218:221], v[46:49]
	v_mfma_f32_16x16x32_f16 v[34:37], v[178:181], v[226:229], v[34:37]
	v_mfma_f32_16x16x32_f16 v[30:33], v[186:189], v[226:229], v[30:33]
	v_mfma_f32_16x16x32_f16 v[18:21], v[178:181], v[234:237], v[18:21]
	v_mfma_f32_16x16x32_f16 v[14:17], v[186:189], v[234:237], v[14:17]
	s_add_i32 s49, 0, 0x18000
	v_add_u32_e32 v177, s49, v148
	s_add_i32 s50, 0, 0x1c000
	v_mfma_f32_16x16x32_f16 v[58:61], v[190:193], v[206:209], 0
	v_mfma_f32_16x16x32_f16 v[54:57], v[198:201], v[206:209], 0
	v_mfma_f32_16x16x32_f16 v[42:45], v[190:193], v[214:217], 0
	v_mfma_f32_16x16x32_f16 v[38:41], v[198:201], v[214:217], 0
	v_mfma_f32_16x16x32_f16 v[26:29], v[190:193], v[222:225], 0
	v_mfma_f32_16x16x32_f16 v[22:25], v[198:201], v[222:225], 0
	v_mfma_f32_16x16x32_f16 v[10:13], v[190:193], v[230:233], 0
	v_mfma_f32_16x16x32_f16 v[6:9], v[198:201], v[230:233], 0
	v_mfma_f32_16x16x32_f16 v[58:61], v[194:197], v[210:213], v[58:61]
	v_mfma_f32_16x16x32_f16 v[54:57], v[202:205], v[210:213], v[54:57]
	v_mfma_f32_16x16x32_f16 v[42:45], v[194:197], v[218:221], v[42:45]
	v_mfma_f32_16x16x32_f16 v[38:41], v[202:205], v[218:221], v[38:41]
	v_mfma_f32_16x16x32_f16 v[26:29], v[194:197], v[226:229], v[26:29]
	v_mfma_f32_16x16x32_f16 v[22:25], v[202:205], v[226:229], v[22:25]
	v_mfma_f32_16x16x32_f16 v[10:13], v[194:197], v[234:237], v[10:13]
	v_mfma_f32_16x16x32_f16 v[6:9], v[202:205], v[234:237], v[6:9]
	s_barrier
	ds_read_b128 v[152:155], v177
	ds_read_b128 v[178:181], v177 offset:1024
	ds_read_b128 v[182:185], v177 offset:2048
	ds_read_b128 v[186:189], v177 offset:3072
	v_add_u32_e32 v177, s50, v148
	ds_read_b128 v[190:193], v177
	ds_read_b128 v[194:197], v177 offset:1024
	ds_read_b128 v[198:201], v177 offset:2048
	ds_read_b128 v[202:205], v177 offset:3072
	s_add_u32 s26, s26, 0x40000
	s_addc_u32 s27, s27, 0
	s_mov_b32 m0, s31
	v_lshl_add_u64 v[246:247], s[26:27], 0, v[138:139]
	ds_read_b128 v[206:209], v151 offset:32768
	ds_read_b128 v[210:213], v151 offset:33792
	ds_read_b128 v[214:217], v151 offset:34816
	ds_read_b128 v[218:221], v151 offset:35840
	ds_read_b128 v[222:225], v151 offset:36864
	ds_read_b128 v[226:229], v151 offset:37888
	ds_read_b128 v[230:233], v151 offset:38912
	ds_read_b128 v[234:237], v151 offset:39936
	global_load_lds_dwordx4 v[246:247], off
	v_lshl_add_u64 v[246:247], s[26:27], 0, v[134:135]
	s_mov_b32 m0, s38
	s_nop 0
	global_load_lds_dwordx4 v[246:247], off
	s_waitcnt vmcnt(8)
	s_waitcnt lgkmcnt(0)
	s_barrier
	s_waitcnt lgkmcnt(0)
	v_mfma_f32_16x16x32_f16 v[130:133], v[152:155], v[206:209], v[130:133]
	v_mfma_f32_16x16x32_f16 v[126:129], v[182:185], v[206:209], v[126:129]
	v_mfma_f32_16x16x32_f16 v[114:117], v[152:155], v[214:217], v[114:117]
	v_mfma_f32_16x16x32_f16 v[110:113], v[182:185], v[214:217], v[110:113]
	v_mfma_f32_16x16x32_f16 v[98:101], v[152:155], v[222:225], v[98:101]
	v_mfma_f32_16x16x32_f16 v[94:97], v[182:185], v[222:225], v[94:97]
	v_mfma_f32_16x16x32_f16 v[82:85], v[152:155], v[230:233], v[82:85]
	v_mfma_f32_16x16x32_f16 v[78:81], v[182:185], v[230:233], v[78:81]
	v_mfma_f32_16x16x32_f16 v[130:133], v[178:181], v[210:213], v[130:133]
	v_mfma_f32_16x16x32_f16 v[126:129], v[186:189], v[210:213], v[126:129]
	v_mfma_f32_16x16x32_f16 v[114:117], v[178:181], v[218:221], v[114:117]
	v_mfma_f32_16x16x32_f16 v[110:113], v[186:189], v[218:221], v[110:113]
	v_mfma_f32_16x16x32_f16 v[98:101], v[178:181], v[226:229], v[98:101]
	v_mfma_f32_16x16x32_f16 v[94:97], v[186:189], v[226:229], v[94:97]
	v_mfma_f32_16x16x32_f16 v[82:85], v[178:181], v[234:237], v[82:85]
	v_mfma_f32_16x16x32_f16 v[78:81], v[186:189], v[234:237], v[78:81]
	s_add_i32 s26, s49, s30
	v_lshl_add_u64 v[238:239], v[238:239], 0, s[36:37]
	s_mov_b32 m0, s26
	v_mfma_f32_16x16x32_f16 v[122:125], v[190:193], v[206:209], v[122:125]
	v_mfma_f32_16x16x32_f16 v[118:121], v[198:201], v[206:209], v[118:121]
	v_mfma_f32_16x16x32_f16 v[106:109], v[190:193], v[214:217], v[106:109]
	v_mfma_f32_16x16x32_f16 v[102:105], v[198:201], v[214:217], v[102:105]
	v_mfma_f32_16x16x32_f16 v[90:93], v[190:193], v[222:225], v[90:93]
	v_mfma_f32_16x16x32_f16 v[86:89], v[198:201], v[222:225], v[86:89]
	v_mfma_f32_16x16x32_f16 v[74:77], v[190:193], v[230:233], v[74:77]
	v_mfma_f32_16x16x32_f16 v[70:73], v[198:201], v[230:233], v[70:73]
	v_mfma_f32_16x16x32_f16 v[122:125], v[194:197], v[210:213], v[122:125]
	v_mfma_f32_16x16x32_f16 v[118:121], v[202:205], v[210:213], v[118:121]
	v_mfma_f32_16x16x32_f16 v[106:109], v[194:197], v[218:221], v[106:109]
	v_mfma_f32_16x16x32_f16 v[102:105], v[202:205], v[218:221], v[102:105]
	v_mfma_f32_16x16x32_f16 v[90:93], v[194:197], v[226:229], v[90:93]
	v_mfma_f32_16x16x32_f16 v[86:89], v[202:205], v[226:229], v[86:89]
	v_mfma_f32_16x16x32_f16 v[74:77], v[194:197], v[234:237], v[74:77]
	v_mfma_f32_16x16x32_f16 v[70:73], v[202:205], v[234:237], v[70:73]
	s_barrier
; #define STAGE(bufoff, gbase, voff) do { _Pragma("unroll") for (int _i = 0; _i < 2; ++_i) \
;     __builtin_amdgcn_global_load_lds((const unsigned*)((const char*)(gbase) + (voff)[_i]), (LAS unsigned*)(lds + (bufoff) + ldsw + _i * 8192), 16, 0, 0); } while (0)
; #define LDA(dst, b, h) do { _Pragma("unroll") for (int m = 0; m < 4; ++m) _Pragma("unroll") for (int k = 0; k < 2; ++k) dst[m][k] = *(const LAS half8*)(lds + SA(b, h) + aoff + m * 2048 + k * 1024); } while (0)
; #define LDB(dst, b, h) do { _Pragma("unroll") for (int n = 0; n < 2; ++n) _Pragma("unroll") for (int k = 0; k < 2; ++k) dst[n][k] = *(const LAS half8*)(lds + SB(b, h) + boff + n * 2048 + k * 1024); } while (0)
; #define MMA(ai, bj, At_, Bt_) do { __builtin_amdgcn_s_setprio(1); \
;     _Pragma("unroll") for (int m = 0; m < 4; ++m) _Pragma("unroll") for (int n = 0; n < 2; ++n) _Pragma("unroll") for (int k = 0; k < 2; ++k) \
;       acc[ai][bj][m][n] = MFMA16(Bt_[n][k], At_[m][k], acc[ai][bj][m][n]); \
;     __builtin_amdgcn_s_setprio(0); } while (0)
; #define WAIT_V(n) asm volatile("s_waitcnt vmcnt(" #n ")" ::: "memory")
; #define WAIT_L(n) asm volatile("s_waitcnt lgkmcnt(" #n ")" ::: "memory")
; #define BAR __builtin_amdgcn_s_barrier()
; #define SCHED __builtin_amdgcn_sched_barrier(0)
; template <int EPI>
; DI void gemm_phase(const int wid_s, const h16* __restrict__ A, const h16* __restrict__ Bt, const int N, const int K, const EpiArgs ea) {
;     ...
;     for (int t = 0; t < nt; t += 2) {
;       const bool last = (t == nt - 2);
;       const char* a1 = cA + (size_t)(t + 1) * kstep;
;       const char* a2 = last ? nA : cA + (size_t)(t + 2) * kstep; const char* b2 = last ? nB : cB + (size_t)(t + 2) * kstep;
;       const char* a3 = a2 + kstep; const char* b3 = b2 + kstep;
;       LDB(B0, 0, 0); LDB(B1, 0, 1); SCHED; LDA(At, 0, 0); STAGE(SA(1, 1), a1 + hstep, voffA);
;       WAIT_V(8); WAIT_L(0); BAR; MMA(0, 0, At, B0); MMA(0, 1, At, B1); BAR; SCHED;
;     ...
;       LDA(At, 1, 1); STAGE(SB(1, 0), b3, voffB); STAGE(SB(1, 1), b3 + hstep, voffB); STAGE(SA(1, 0), a3, voffA);
;       WAIT_V(8); WAIT_L(0); BAR; MMA(1, 0, At, B0); MMA(1, 1, At, B1); BAR; SCHED;
	ds_read_b128 v[206:209], v151 offset:49152
	ds_read_b128 v[210:213], v151 offset:50176
	ds_read_b128 v[214:217], v151 offset:51200
	ds_read_b128 v[218:221], v151 offset:52224
	ds_read_b128 v[222:225], v151 offset:53248
	ds_read_b128 v[226:229], v151 offset:54272
	ds_read_b128 v[230:233], v151 offset:55296
	ds_read_b128 v[234:237], v151 offset:56320
	global_load_lds_dwordx4 v[238:239], off
	s_add_i32 m0, s26, 0x2000
	s_add_u32 s22, s22, 0x40080
	v_lshl_add_u64 v[238:239], v[240:241], 0, s[36:37]
	s_addc_u32 s23, s23, 0
	s_add_i32 s26, s50, s30
	global_load_lds_dwordx4 v[238:239], off
	v_lshl_add_u64 v[238:239], s[22:23], 0, v[0:1]
	s_mov_b32 m0, s26
	s_nop 0
	global_load_lds_dwordx4 v[238:239], off
	v_lshl_add_u64 v[238:239], s[22:23], 0, v[2:3]
	s_add_i32 m0, s26, 0x2000
	s_nop 0
	global_load_lds_dwordx4 v[238:239], off
	v_lshl_add_u64 v[238:239], v[242:243], 0, s[36:37]
	s_mov_b32 m0, s40
	s_nop 0
	global_load_lds_dwordx4 v[238:239], off
	v_lshl_add_u64 v[238:239], v[244:245], 0, s[36:37]
	s_mov_b32 m0, s41
	s_nop 0
	global_load_lds_dwordx4 v[238:239], off
	s_waitcnt vmcnt(8)
	s_waitcnt lgkmcnt(0)
	s_barrier
	s_waitcnt lgkmcnt(0)
	v_mfma_f32_16x16x32_f16 v[66:69], v[152:155], v[206:209], v[66:69]
	v_mfma_f32_16x16x32_f16 v[62:65], v[182:185], v[206:209], v[62:65]
	v_mfma_f32_16x16x32_f16 v[50:53], v[152:155], v[214:217], v[50:53]
	v_mfma_f32_16x16x32_f16 v[46:49], v[182:185], v[214:217], v[46:49]
	v_mfma_f32_16x16x32_f16 v[34:37], v[152:155], v[222:225], v[34:37]
	v_mfma_f32_16x16x32_f16 v[30:33], v[182:185], v[222:225], v[30:33]
	v_mfma_f32_16x16x32_f16 v[18:21], v[152:155], v[230:233], v[18:21]
	v_mfma_f32_16x16x32_f16 v[14:17], v[182:185], v[230:233], v[14:17]
	v_mfma_f32_16x16x32_f16 v[66:69], v[178:181], v[210:213], v[66:69]
	v_mfma_f32_16x16x32_f16 v[62:65], v[186:189], v[210:213], v[62:65]
	v_mfma_f32_16x16x32_f16 v[50:53], v[178:181], v[218:221], v[50:53]
	v_mfma_f32_16x16x32_f16 v[46:49], v[186:189], v[218:221], v[46:49]
	v_mfma_f32_16x16x32_f16 v[34:37], v[178:181], v[226:229], v[34:37]
	v_mfma_f32_16x16x32_f16 v[30:33], v[186:189], v[226:229], v[30:33]
	v_mfma_f32_16x16x32_f16 v[18:21], v[178:181], v[234:237], v[18:21]
	v_mfma_f32_16x16x32_f16 v[14:17], v[186:189], v[234:237], v[14:17]
	v_mfma_f32_16x16x32_f16 v[58:61], v[190:193], v[206:209], v[58:61]
	v_mfma_f32_16x16x32_f16 v[54:57], v[198:201], v[206:209], v[54:57]
	v_mfma_f32_16x16x32_f16 v[42:45], v[190:193], v[214:217], v[42:45]
	v_mfma_f32_16x16x32_f16 v[38:41], v[198:201], v[214:217], v[38:41]
	v_mfma_f32_16x16x32_f16 v[26:29], v[190:193], v[222:225], v[26:29]
	v_mfma_f32_16x16x32_f16 v[22:25], v[198:201], v[222:225], v[22:25]
	v_mfma_f32_16x16x32_f16 v[10:13], v[190:193], v[230:233], v[10:13]
	v_mfma_f32_16x16x32_f16 v[6:9], v[198:201], v[230:233], v[6:9]
	v_mfma_f32_16x16x32_f16 v[58:61], v[194:197], v[210:213], v[58:61]
	v_mfma_f32_16x16x32_f16 v[54:57], v[202:205], v[210:213], v[54:57]
	v_mfma_f32_16x16x32_f16 v[42:45], v[194:197], v[218:221], v[42:45]
	v_mfma_f32_16x16x32_f16 v[38:41], v[202:205], v[218:221], v[38:41]
	v_mfma_f32_16x16x32_f16 v[26:29], v[194:197], v[226:229], v[26:29]
	v_mfma_f32_16x16x32_f16 v[22:25], v[202:205], v[226:229], v[22:25]
	v_mfma_f32_16x16x32_f16 v[10:13], v[194:197], v[234:237], v[10:13]
	v_mfma_f32_16x16x32_f16 v[6:9], v[202:205], v[234:237], v[6:9]
	s_barrier
	s_add_i32 s48, s48, 2
	s_add_u32 s20, s20, 0x100
	s_addc_u32 s21, s21, 0
	s_cmp_gt_u32 s48, 13
.LBB0_141:
	s_add_u32 s22, s46, s20
	s_addc_u32 s23, s47, s21
	s_add_u32 s22, s22, 0x520e100
	s_addc_u32 s23, s23, 0
	s_add_u32 s49, s44, s20
	s_addc_u32 s50, s45, s21
	s_add_i32 s51, 0, 0x10000
	s_cmpk_eq_i32 s20, 0x700
	s_cselect_b32 s27, s42, s23
	s_cselect_b32 s26, s9, s22
	v_add_u32_e32 v177, s51, v148
	s_cselect_b32 s23, s43, s50
	s_cselect_b32 s22, s11, s49
	s_add_i32 s49, 0, 0x14000
	ds_read_b128 v[152:155], v177
	ds_read_b128 v[178:181], v177 offset:1024
	ds_read_b128 v[182:185], v177 offset:2048
	ds_read_b128 v[186:189], v177 offset:3072
	v_add_u32_e32 v177, s49, v148
	ds_read_b128 v[190:193], v177
	ds_read_b128 v[194:197], v177 offset:1024
	ds_read_b128 v[198:201], v177 offset:2048
	ds_read_b128 v[202:205], v177 offset:3072
	v_lshl_add_u64 v[238:239], v[146:147], 0, s[20:21]
	s_add_i32 m0, s17, 0xc000
	ds_read_b128 v[206:209], v151
	ds_read_b128 v[210:213], v151 offset:1024
	ds_read_b128 v[214:217], v151 offset:2048
	ds_read_b128 v[218:221], v151 offset:3072
	ds_read_b128 v[222:225], v151 offset:4096
	ds_read_b128 v[226:229], v151 offset:5120
	ds_read_b128 v[230:233], v151 offset:6144
	ds_read_b128 v[234:237], v151 offset:7168
	global_load_lds_dwordx4 v[238:239], off
	v_lshl_add_u64 v[238:239], v[144:145], 0, s[20:21]
	s_add_i32 m0, s17, 0xe000
	s_nop 0
	global_load_lds_dwordx4 v[238:239], off
	s_waitcnt vmcnt(8)
	s_waitcnt lgkmcnt(0)
	s_barrier
; #define STAGE(bufoff, gbase, voff) do { _Pragma("unroll") for (int _i = 0; _i < 2; ++_i) \
;     __builtin_amdgcn_global_load_lds((const unsigned*)((const char*)(gbase) + (voff)[_i]), (LAS unsigned*)(lds + (bufoff) + ldsw + _i * 8192), 16, 0, 0); } while (0)
; #define LDA(dst, b, h) do { _Pragma("unroll") for (int m = 0; m < 4; ++m) _Pragma("unroll") for (int k = 0; k < 2; ++k) dst[m][k] = *(const LAS half8*)(lds + SA(b, h) + aoff + m * 2048 + k * 1024); } while (0)
; #define LDB(dst, b, h) do { _Pragma("unroll") for (int n = 0; n < 2; ++n) _Pragma("unroll") for (int k = 0; k < 2; ++k) dst[n][k] = *(const LAS half8*)(lds + SB(b, h) + boff + n * 2048 + k * 1024); } while (0)
; #define MMA(ai, bj, At_, Bt_) do { __builtin_amdgcn_s_setprio(1); \
;     _Pragma("unroll") for (int m = 0; m < 4; ++m) _Pragma("unroll") for (int n = 0; n < 2; ++n) _Pragma("unroll") for (int k = 0; k < 2; ++k) \
;       acc[ai][bj][m][n] = MFMA16(Bt_[n][k], At_[m][k], acc[ai][bj][m][n]); \
;     __builtin_amdgcn_s_setprio(0); } while (0)
; #define WAIT_V(n) asm volatile("s_waitcnt vmcnt(" #n ")" ::: "memory")
; #define WAIT_L(n) asm volatile("s_waitcnt lgkmcnt(" #n ")" ::: "memory")
; #define BAR __builtin_amdgcn_s_barrier()
; #define SCHED __builtin_amdgcn_sched_barrier(0)
; template <int EPI>
; DI void gemm_phase(const int wid_s, const h16* __restrict__ A, const h16* __restrict__ Bt, const int N, const int K, const EpiArgs ea) {
;     ...
;       LDB(B0, 0, 0); LDB(B1, 0, 1); SCHED; LDA(At, 0, 0); STAGE(SA(1, 1), a1 + hstep, voffA);
;       WAIT_V(8); WAIT_L(0); BAR; MMA(0, 0, At, B0); MMA(0, 1, At, B1); BAR; SCHED;
;       LDA(At, 0, 1); STAGE(SB(0, 0), b2, voffB); STAGE(SB(0, 1), b2 + hstep, voffB); STAGE(SA(0, 0), a2, voffA);
;       WAIT_V(8); WAIT_L(0); BAR; MMA(1, 0, At, B0); MMA(1, 1, At, B1); BAR; SCHED;
	s_waitcnt lgkmcnt(0)
	v_mfma_f32_16x16x32_f16 v[130:133], v[152:155], v[206:209], v[130:133]
	v_mfma_f32_16x16x32_f16 v[126:129], v[182:185], v[206:209], v[126:129]
	v_mfma_f32_16x16x32_f16 v[114:117], v[152:155], v[214:217], v[114:117]
	v_mfma_f32_16x16x32_f16 v[110:113], v[182:185], v[214:217], v[110:113]
	v_mfma_f32_16x16x32_f16 v[98:101], v[152:155], v[222:225], v[98:101]
	v_mfma_f32_16x16x32_f16 v[94:97], v[182:185], v[222:225], v[94:97]
	v_mfma_f32_16x16x32_f16 v[82:85], v[152:155], v[230:233], v[82:85]
	v_mfma_f32_16x16x32_f16 v[78:81], v[182:185], v[230:233], v[78:81]
	v_mfma_f32_16x16x32_f16 v[130:133], v[178:181], v[210:213], v[130:133]
	v_mfma_f32_16x16x32_f16 v[126:129], v[186:189], v[210:213], v[126:129]
	v_mfma_f32_16x16x32_f16 v[114:117], v[178:181], v[218:221], v[114:117]
	v_mfma_f32_16x16x32_f16 v[110:113], v[186:189], v[218:221], v[110:113]
	v_mfma_f32_16x16x32_f16 v[98:101], v[178:181], v[226:229], v[98:101]
	v_mfma_f32_16x16x32_f16 v[94:97], v[186:189], v[226:229], v[94:97]
	v_mfma_f32_16x16x32_f16 v[82:85], v[178:181], v[234:237], v[82:85]
	v_mfma_f32_16x16x32_f16 v[78:81], v[186:189], v[234:237], v[78:81]
	s_add_i32 s50, s51, s30
	v_lshl_add_u64 v[238:239], s[22:23], 0, v[0:1]
	s_mov_b32 m0, s50
	v_mfma_f32_16x16x32_f16 v[122:125], v[190:193], v[206:209], v[122:125]
	v_mfma_f32_16x16x32_f16 v[118:121], v[198:201], v[206:209], v[118:121]
	v_mfma_f32_16x16x32_f16 v[106:109], v[190:193], v[214:217], v[106:109]
	v_mfma_f32_16x16x32_f16 v[102:105], v[198:201], v[214:217], v[102:105]
	v_mfma_f32_16x16x32_f16 v[90:93], v[190:193], v[222:225], v[90:93]
	v_mfma_f32_16x16x32_f16 v[86:89], v[198:201], v[222:225], v[86:89]
	v_mfma_f32_16x16x32_f16 v[74:77], v[190:193], v[230:233], v[74:77]
	v_mfma_f32_16x16x32_f16 v[70:73], v[198:201], v[230:233], v[70:73]
	v_mfma_f32_16x16x32_f16 v[122:125], v[194:197], v[210:213], v[122:125]
	v_mfma_f32_16x16x32_f16 v[118:121], v[202:205], v[210:213], v[118:121]
	v_mfma_f32_16x16x32_f16 v[106:109], v[194:197], v[218:221], v[106:109]
	v_mfma_f32_16x16x32_f16 v[102:105], v[202:205], v[218:221], v[102:105]
	v_mfma_f32_16x16x32_f16 v[90:93], v[194:197], v[226:229], v[90:93]
	v_mfma_f32_16x16x32_f16 v[86:89], v[202:205], v[226:229], v[86:89]
	v_mfma_f32_16x16x32_f16 v[74:77], v[194:197], v[234:237], v[74:77]
	v_mfma_f32_16x16x32_f16 v[70:73], v[202:205], v[234:237], v[70:73]
	s_barrier
	ds_read_b128 v[206:209], v151 offset:16384
	ds_read_b128 v[210:213], v151 offset:17408
	ds_read_b128 v[214:217], v151 offset:18432
	ds_read_b128 v[218:221], v151 offset:19456
	ds_read_b128 v[222:225], v151 offset:20480
	ds_read_b128 v[226:229], v151 offset:21504
	ds_read_b128 v[230:233], v151 offset:22528
	ds_read_b128 v[234:237], v151 offset:23552
	global_load_lds_dwordx4 v[238:239], off
	s_add_i32 m0, s50, 0x2000
	s_add_u32 s50, s22, 0x40000
	v_lshl_add_u64 v[240:241], s[22:23], 0, v[2:3]
	s_addc_u32 s51, s23, 0
	s_add_i32 s49, s49, s30
	global_load_lds_dwordx4 v[240:241], off
	v_lshl_add_u64 v[242:243], s[50:51], 0, v[0:1]
	s_mov_b32 m0, s49
	v_lshl_add_u64 v[244:245], s[26:27], 0, v[134:135]
	global_load_lds_dwordx4 v[242:243], off
	v_lshl_add_u64 v[242:243], s[50:51], 0, v[2:3]
	s_add_i32 m0, s49, 0x2000
	s_nop 0
	global_load_lds_dwordx4 v[242:243], off
	v_lshl_add_u64 v[242:243], s[26:27], 0, v[138:139]
	s_mov_b32 m0, s17
	s_nop 0
	global_load_lds_dwordx4 v[242:243], off
	s_mov_b32 m0, s19
	s_nop 0
	global_load_lds_dwordx4 v[244:245], off
	s_waitcnt vmcnt(8)
	s_waitcnt lgkmcnt(0)
	s_barrier
	s_waitcnt lgkmcnt(0)
	v_mfma_f32_16x16x32_f16 v[66:69], v[152:155], v[206:209], v[66:69]
	v_mfma_f32_16x16x32_f16 v[62:65], v[182:185], v[206:209], v[62:65]
	v_mfma_f32_16x16x32_f16 v[50:53], v[152:155], v[214:217], v[50:53]
	v_mfma_f32_16x16x32_f16 v[46:49], v[182:185], v[214:217], v[46:49]
	v_mfma_f32_16x16x32_f16 v[34:37], v[152:155], v[222:225], v[34:37]
	v_mfma_f32_16x16x32_f16 v[30:33], v[182:185], v[222:225], v[30:33]
	v_mfma_f32_16x16x32_f16 v[18:21], v[152:155], v[230:233], v[18:21]
	v_mfma_f32_16x16x32_f16 v[14:17], v[182:185], v[230:233], v[14:17]
	v_mfma_f32_16x16x32_f16 v[66:69], v[178:181], v[210:213], v[66:69]
	v_mfma_f32_16x16x32_f16 v[62:65], v[186:189], v[210:213], v[62:65]
	v_mfma_f32_16x16x32_f16 v[50:53], v[178:181], v[218:221], v[50:53]
	v_mfma_f32_16x16x32_f16 v[46:49], v[186:189], v[218:221], v[46:49]
	v_mfma_f32_16x16x32_f16 v[34:37], v[178:181], v[226:229], v[34:37]
	v_mfma_f32_16x16x32_f16 v[30:33], v[186:189], v[226:229], v[30:33]
	v_mfma_f32_16x16x32_f16 v[18:21], v[178:181], v[234:237], v[18:21]
	v_mfma_f32_16x16x32_f16 v[14:17], v[186:189], v[234:237], v[14:17]
	s_add_i32 s49, 0, 0x18000
	v_add_u32_e32 v177, s49, v148
	s_add_i32 s50, 0, 0x1c000
	v_mfma_f32_16x16x32_f16 v[58:61], v[190:193], v[206:209], v[58:61]
	v_mfma_f32_16x16x32_f16 v[54:57], v[198:201], v[206:209], v[54:57]
	v_mfma_f32_16x16x32_f16 v[42:45], v[190:193], v[214:217], v[42:45]
	v_mfma_f32_16x16x32_f16 v[38:41], v[198:201], v[214:217], v[38:41]
	v_mfma_f32_16x16x32_f16 v[26:29], v[190:193], v[222:225], v[26:29]
	v_mfma_f32_16x16x32_f16 v[22:25], v[198:201], v[222:225], v[22:25]
	v_mfma_f32_16x16x32_f16 v[10:13], v[190:193], v[230:233], v[10:13]
	v_mfma_f32_16x16x32_f16 v[6:9], v[198:201], v[230:233], v[6:9]
	v_mfma_f32_16x16x32_f16 v[58:61], v[194:197], v[210:213], v[58:61]
	v_mfma_f32_16x16x32_f16 v[54:57], v[202:205], v[210:213], v[54:57]
	v_mfma_f32_16x16x32_f16 v[42:45], v[194:197], v[218:221], v[42:45]
	v_mfma_f32_16x16x32_f16 v[38:41], v[202:205], v[218:221], v[38:41]
	v_mfma_f32_16x16x32_f16 v[26:29], v[194:197], v[226:229], v[26:29]
	v_mfma_f32_16x16x32_f16 v[22:25], v[202:205], v[226:229], v[22:25]
	v_mfma_f32_16x16x32_f16 v[10:13], v[194:197], v[234:237], v[10:13]
	v_mfma_f32_16x16x32_f16 v[6:9], v[202:205], v[234:237], v[6:9]
	s_barrier
; #define STAGE(bufoff, gbase, voff) do { _Pragma("unroll") for (int _i = 0; _i < 2; ++_i) \
;     __builtin_amdgcn_global_load_lds((const unsigned*)((const char*)(gbase) + (voff)[_i]), (LAS unsigned*)(lds + (bufoff) + ldsw + _i * 8192), 16, 0, 0); } while (0)
; #define LDA(dst, b, h) do { _Pragma("unroll") for (int m = 0; m < 4; ++m) _Pragma("unroll") for (int k = 0; k < 2; ++k) dst[m][k] = *(const LAS half8*)(lds + SA(b, h) + aoff + m * 2048 + k * 1024); } while (0)
; #define LDB(dst, b, h) do { _Pragma("unroll") for (int n = 0; n < 2; ++n) _Pragma("unroll") for (int k = 0; k < 2; ++k) dst[n][k] = *(const LAS half8*)(lds + SB(b, h) + boff + n * 2048 + k * 1024); } while (0)
; #define MMA(ai, bj, At_, Bt_) do { __builtin_amdgcn_s_setprio(1); \
;     _Pragma("unroll") for (int m = 0; m < 4; ++m) _Pragma("unroll") for (int n = 0; n < 2; ++n) _Pragma("unroll") for (int k = 0; k < 2; ++k) \
;       acc[ai][bj][m][n] = MFMA16(Bt_[n][k], At_[m][k], acc[ai][bj][m][n]); \
;     __builtin_amdgcn_s_setprio(0); } while (0)
; #define WAIT_V(n) asm volatile("s_waitcnt vmcnt(" #n ")" ::: "memory")
; #define WAIT_L(n) asm volatile("s_waitcnt lgkmcnt(" #n ")" ::: "memory")
; #define BAR __builtin_amdgcn_s_barrier()
; #define SCHED __builtin_amdgcn_sched_barrier(0)
; template <int EPI>
; DI void gemm_phase(const int wid_s, const h16* __restrict__ A, const h16* __restrict__ Bt, const int N, const int K, const EpiArgs ea) {
;     ...
;       LDB(B0, 1, 0); LDB(B1, 1, 1); SCHED; LDA(At, 1, 0); STAGE(SA(0, 1), a2 + hstep, voffA);
;       WAIT_V(8); WAIT_L(0); BAR; MMA(0, 0, At, B0); MMA(0, 1, At, B1); BAR; SCHED;
;       LDA(At, 1, 1); STAGE(SB(1, 0), b3, voffB); STAGE(SB(1, 1), b3 + hstep, voffB); STAGE(SA(1, 0), a3, voffA);
;       WAIT_V(8); WAIT_L(0); BAR; MMA(1, 0, At, B0); MMA(1, 1, At, B1); BAR; SCHED;
;     }
;     if (wr == 0) BAR;
	ds_read_b128 v[152:155], v177
	ds_read_b128 v[178:181], v177 offset:1024
	ds_read_b128 v[182:185], v177 offset:2048
	ds_read_b128 v[186:189], v177 offset:3072
	v_add_u32_e32 v177, s50, v148
	ds_read_b128 v[190:193], v177
	ds_read_b128 v[194:197], v177 offset:1024
	ds_read_b128 v[198:201], v177 offset:2048
	ds_read_b128 v[202:205], v177 offset:3072
	s_add_u32 s26, s26, 0x40000
	s_addc_u32 s27, s27, 0
	s_mov_b32 m0, s31
	v_lshl_add_u64 v[246:247], s[26:27], 0, v[138:139]
	ds_read_b128 v[206:209], v151 offset:32768
	ds_read_b128 v[210:213], v151 offset:33792
	ds_read_b128 v[214:217], v151 offset:34816
	ds_read_b128 v[218:221], v151 offset:35840
	ds_read_b128 v[222:225], v151 offset:36864
	ds_read_b128 v[226:229], v151 offset:37888
	ds_read_b128 v[230:233], v151 offset:38912
	ds_read_b128 v[234:237], v151 offset:39936
	global_load_lds_dwordx4 v[246:247], off
	v_lshl_add_u64 v[246:247], s[26:27], 0, v[134:135]
	s_mov_b32 m0, s38
	s_nop 0
	global_load_lds_dwordx4 v[246:247], off
	s_waitcnt vmcnt(8)
	s_waitcnt lgkmcnt(0)
	s_barrier
	s_waitcnt lgkmcnt(0)
	v_mfma_f32_16x16x32_f16 v[130:133], v[152:155], v[206:209], v[130:133]
	v_mfma_f32_16x16x32_f16 v[126:129], v[182:185], v[206:209], v[126:129]
	v_mfma_f32_16x16x32_f16 v[114:117], v[152:155], v[214:217], v[114:117]
	v_mfma_f32_16x16x32_f16 v[110:113], v[182:185], v[214:217], v[110:113]
	v_mfma_f32_16x16x32_f16 v[98:101], v[152:155], v[222:225], v[98:101]
	v_mfma_f32_16x16x32_f16 v[94:97], v[182:185], v[222:225], v[94:97]
	v_mfma_f32_16x16x32_f16 v[82:85], v[152:155], v[230:233], v[82:85]
	v_mfma_f32_16x16x32_f16 v[78:81], v[182:185], v[230:233], v[78:81]
	v_mfma_f32_16x16x32_f16 v[130:133], v[178:181], v[210:213], v[130:133]
	v_mfma_f32_16x16x32_f16 v[126:129], v[186:189], v[210:213], v[126:129]
	v_mfma_f32_16x16x32_f16 v[114:117], v[178:181], v[218:221], v[114:117]
	v_mfma_f32_16x16x32_f16 v[110:113], v[186:189], v[218:221], v[110:113]
	v_mfma_f32_16x16x32_f16 v[98:101], v[178:181], v[226:229], v[98:101]
	v_mfma_f32_16x16x32_f16 v[94:97], v[186:189], v[226:229], v[94:97]
	v_mfma_f32_16x16x32_f16 v[82:85], v[178:181], v[234:237], v[82:85]
	v_mfma_f32_16x16x32_f16 v[78:81], v[186:189], v[234:237], v[78:81]
	s_add_i32 s26, s49, s30
	v_lshl_add_u64 v[238:239], v[238:239], 0, s[36:37]
	s_mov_b32 m0, s26
	v_mfma_f32_16x16x32_f16 v[122:125], v[190:193], v[206:209], v[122:125]
	v_mfma_f32_16x16x32_f16 v[118:121], v[198:201], v[206:209], v[118:121]
	v_mfma_f32_16x16x32_f16 v[106:109], v[190:193], v[214:217], v[106:109]
	v_mfma_f32_16x16x32_f16 v[102:105], v[198:201], v[214:217], v[102:105]
	v_mfma_f32_16x16x32_f16 v[90:93], v[190:193], v[222:225], v[90:93]
	v_mfma_f32_16x16x32_f16 v[86:89], v[198:201], v[222:225], v[86:89]
	v_mfma_f32_16x16x32_f16 v[74:77], v[190:193], v[230:233], v[74:77]
	v_mfma_f32_16x16x32_f16 v[70:73], v[198:201], v[230:233], v[70:73]
	v_mfma_f32_16x16x32_f16 v[122:125], v[194:197], v[210:213], v[122:125]
	v_mfma_f32_16x16x32_f16 v[118:121], v[202:205], v[210:213], v[118:121]
	v_mfma_f32_16x16x32_f16 v[106:109], v[194:197], v[218:221], v[106:109]
	v_mfma_f32_16x16x32_f16 v[102:105], v[202:205], v[218:221], v[102:105]
	v_mfma_f32_16x16x32_f16 v[90:93], v[194:197], v[226:229], v[90:93]
	v_mfma_f32_16x16x32_f16 v[86:89], v[202:205], v[226:229], v[86:89]
	v_mfma_f32_16x16x32_f16 v[74:77], v[194:197], v[234:237], v[74:77]
	v_mfma_f32_16x16x32_f16 v[70:73], v[202:205], v[234:237], v[70:73]
	s_barrier
	ds_read_b128 v[206:209], v151 offset:49152
	ds_read_b128 v[210:213], v151 offset:50176
	ds_read_b128 v[214:217], v151 offset:51200
	ds_read_b128 v[218:221], v151 offset:52224
	ds_read_b128 v[222:225], v151 offset:53248
	ds_read_b128 v[226:229], v151 offset:54272
	ds_read_b128 v[230:233], v151 offset:55296
	ds_read_b128 v[234:237], v151 offset:56320
	global_load_lds_dwordx4 v[238:239], off
	s_add_i32 m0, s26, 0x2000
	s_add_u32 s22, s22, 0x40080
	v_lshl_add_u64 v[238:239], v[240:241], 0, s[36:37]
	s_addc_u32 s23, s23, 0
	s_add_i32 s26, s50, s30
	global_load_lds_dwordx4 v[238:239], off
	v_lshl_add_u64 v[238:239], s[22:23], 0, v[0:1]
	s_mov_b32 m0, s26
	s_nop 0
	global_load_lds_dwordx4 v[238:239], off
	v_lshl_add_u64 v[238:239], s[22:23], 0, v[2:3]
	s_add_i32 m0, s26, 0x2000
	s_nop 0
	global_load_lds_dwordx4 v[238:239], off
	v_lshl_add_u64 v[238:239], v[242:243], 0, s[36:37]
	s_mov_b32 m0, s40
	s_nop 0
	global_load_lds_dwordx4 v[238:239], off
	v_lshl_add_u64 v[238:239], v[244:245], 0, s[36:37]
	s_mov_b32 m0, s41
	s_nop 0
	global_load_lds_dwordx4 v[238:239], off
	s_waitcnt vmcnt(8)
	s_waitcnt lgkmcnt(0)
	s_barrier
	s_waitcnt lgkmcnt(0)
	v_mfma_f32_16x16x32_f16 v[66:69], v[152:155], v[206:209], v[66:69]
	v_mfma_f32_16x16x32_f16 v[62:65], v[182:185], v[206:209], v[62:65]
	v_mfma_f32_16x16x32_f16 v[50:53], v[152:155], v[214:217], v[50:53]
	v_mfma_f32_16x16x32_f16 v[46:49], v[182:185], v[214:217], v[46:49]
	v_mfma_f32_16x16x32_f16 v[34:37], v[152:155], v[222:225], v[34:37]
	v_mfma_f32_16x16x32_f16 v[30:33], v[182:185], v[222:225], v[30:33]
	v_mfma_f32_16x16x32_f16 v[18:21], v[152:155], v[230:233], v[18:21]
	v_mfma_f32_16x16x32_f16 v[14:17], v[182:185], v[230:233], v[14:17]
	v_mfma_f32_16x16x32_f16 v[66:69], v[178:181], v[210:213], v[66:69]
	v_mfma_f32_16x16x32_f16 v[62:65], v[186:189], v[210:213], v[62:65]
	v_mfma_f32_16x16x32_f16 v[50:53], v[178:181], v[218:221], v[50:53]
	v_mfma_f32_16x16x32_f16 v[46:49], v[186:189], v[218:221], v[46:49]
	v_mfma_f32_16x16x32_f16 v[34:37], v[178:181], v[226:229], v[34:37]
	v_mfma_f32_16x16x32_f16 v[30:33], v[186:189], v[226:229], v[30:33]
	v_mfma_f32_16x16x32_f16 v[18:21], v[178:181], v[234:237], v[18:21]
	v_mfma_f32_16x16x32_f16 v[14:17], v[186:189], v[234:237], v[14:17]
	v_mfma_f32_16x16x32_f16 v[58:61], v[190:193], v[206:209], v[58:61]
	v_mfma_f32_16x16x32_f16 v[54:57], v[198:201], v[206:209], v[54:57]
	v_mfma_f32_16x16x32_f16 v[42:45], v[190:193], v[214:217], v[42:45]
	v_mfma_f32_16x16x32_f16 v[38:41], v[198:201], v[214:217], v[38:41]
	v_mfma_f32_16x16x32_f16 v[26:29], v[190:193], v[222:225], v[26:29]
	v_mfma_f32_16x16x32_f16 v[22:25], v[198:201], v[222:225], v[22:25]
	v_mfma_f32_16x16x32_f16 v[10:13], v[190:193], v[230:233], v[10:13]
	v_mfma_f32_16x16x32_f16 v[6:9], v[198:201], v[230:233], v[6:9]
	v_mfma_f32_16x16x32_f16 v[58:61], v[194:197], v[210:213], v[58:61]
	v_mfma_f32_16x16x32_f16 v[54:57], v[202:205], v[210:213], v[54:57]
	v_mfma_f32_16x16x32_f16 v[42:45], v[194:197], v[218:221], v[42:45]
	v_mfma_f32_16x16x32_f16 v[38:41], v[202:205], v[218:221], v[38:41]
	v_mfma_f32_16x16x32_f16 v[26:29], v[194:197], v[226:229], v[26:29]
	v_mfma_f32_16x16x32_f16 v[22:25], v[202:205], v[226:229], v[22:25]
	v_mfma_f32_16x16x32_f16 v[10:13], v[194:197], v[234:237], v[10:13]
	v_mfma_f32_16x16x32_f16 v[6:9], v[202:205], v[234:237], v[6:9]
	s_barrier
	s_add_i32 s48, s48, 2
	s_add_u32 s20, s20, 0x100
	s_addc_u32 s21, s21, 0
	s_cmp_gt_u32 s48, 13
	s_cbranch_scc0 .LBB0_141
	s_and_b64 vcc, exec, s[4:5]
	s_cbranch_vccz .LBB0_144
	s_barrier

; #define STAGE(bufoff, gbase, voff) do { _Pragma("unroll") for (int _i = 0; _i < 2; ++_i) \
;     __builtin_amdgcn_global_load_lds((const unsigned*)((const char*)(gbase) + (voff)[_i]), (LAS unsigned*)(lds + (bufoff) + ldsw + _i * 8192), 16, 0, 0); } while (0)
; #define LDA(dst, b, h) do { _Pragma("unroll") for (int m = 0; m < 4; ++m) _Pragma("unroll") for (int k = 0; k < 2; ++k) dst[m][k] = *(const LAS half8*)(lds + SA(b, h) + aoff + m * 2048 + k * 1024); } while (0)
; #define LDB(dst, b, h) do { _Pragma("unroll") for (int n = 0; n < 2; ++n) _Pragma("unroll") for (int k = 0; k < 2; ++k) dst[n][k] = *(const LAS half8*)(lds + SB(b, h) + boff + n * 2048 + k * 1024); } while (0)
; #define MMA(ai, bj, At_, Bt_) do { __builtin_amdgcn_s_setprio(1); \
;     _Pragma("unroll") for (int m = 0; m < 4; ++m) _Pragma("unroll") for (int n = 0; n < 2; ++n) _Pragma("unroll") for (int k = 0; k < 2; ++k) \
;       acc[ai][bj][m][n] = MFMA16(Bt_[n][k], At_[m][k], acc[ai][bj][m][n]); \
;     __builtin_amdgcn_s_setprio(0); } while (0)
; #define WAIT_V(n) asm volatile("s_waitcnt vmcnt(" #n ")" ::: "memory")
; #define WAIT_L(n) asm volatile("s_waitcnt lgkmcnt(" #n ")" ::: "memory")
; #define BAR __builtin_amdgcn_s_barrier()
; #define SCHED __builtin_amdgcn_sched_barrier(0)
; template <int EPI>
; DI void gemm_phase(const int wid_s, const h16* __restrict__ A, const h16* __restrict__ Bt, const int N, const int K, const EpiArgs ea) {
;     ...
;     const char* nA = (const char*)A + (size_t)nbrow * K * 2;
;     const char* nB = (const char*)Bt + (size_t)nbcol * K * 2;
;     for (int t = 0; t < nt; t += 2) {
;       const bool last = (t == nt - 2);
;       const char* a1 = cA + (size_t)(t + 1) * kstep;
;       const char* a2 = last ? nA : cA + (size_t)(t + 2) * kstep; const char* b2 = last ? nB : cB + (size_t)(t + 2) * kstep;
;       const char* a3 = a2 + kstep; const char* b3 = b2 + kstep;
;       LDB(B0, 0, 0); LDB(B1, 0, 1); SCHED; LDA(At, 0, 0); STAGE(SA(1, 1), a1 + hstep, voffA);
;       WAIT_V(8); WAIT_L(0); BAR; MMA(0, 0, At, B0); MMA(0, 1, At, B1); BAR; SCHED;
;       LDA(At, 0, 1); STAGE(SB(0, 0), b2, voffB); STAGE(SB(0, 1), b2 + hstep, voffB); STAGE(SA(0, 0), a2, voffA);
.LBB0_174:
	s_ashr_i32 s9, s8, 31
	s_lshl_b64 s[12:13], s[8:9], 11
	v_readlane_b32 s14, v250, 46
	v_readlane_b32 s15, v250, 47
	s_add_u32 s12, s14, s12
	s_addc_u32 s13, s15, s13
	s_ashr_i32 s11, s10, 31
	s_lshl_b64 s[14:15], s[10:11], 11
	v_readlane_b32 s9, v249, 6
	s_add_u32 s9, s9, s14
	v_readlane_b32 s11, v249, 7
	s_addc_u32 s11, s11, s15
	v_readlane_b32 s26, v249, 27
	s_add_u32 s41, s26, s20
	v_readlane_b32 s20, v249, 28
	s_addc_u32 s42, s20, s21
	s_add_u32 s20, s22, 0x40080
	v_mov_b32_e32 v6, 0
	s_addc_u32 s21, s23, 0
	s_mov_b32 s43, -2
	s_add_u32 s22, s20, 0xfffc0080
	s_addc_u32 s23, s21, -1
	s_add_i32 s44, 0, 0x10000
	s_cmp_eq_u32 s43, 12
	s_cselect_b32 s27, s13, s23
	s_cselect_b32 s26, s12, s22
	v_add_u32_e32 v177, s44, v148
	s_cselect_b32 s23, s11, s42
	s_cselect_b32 s22, s9, s41
	s_add_i32 s46, 0, 0x14000
	ds_read_b128 v[144:147], v177
	ds_read_b128 v[152:155], v177 offset:1024
	ds_read_b128 v[178:181], v177 offset:2048
	ds_read_b128 v[182:185], v177 offset:3072
	v_add_u32_e32 v177, s46, v148
	ds_read_b128 v[186:189], v177
	ds_read_b128 v[190:193], v177 offset:1024
	ds_read_b128 v[194:197], v177 offset:2048
	ds_read_b128 v[198:201], v177 offset:3072
	v_lshl_add_u64 v[234:235], s[20:21], 0, v[142:143]
	s_add_i32 m0, s17, 0xc000
	ds_read_b128 v[202:205], v151
	ds_read_b128 v[206:209], v151 offset:1024
	ds_read_b128 v[210:213], v151 offset:2048
	ds_read_b128 v[214:217], v151 offset:3072
	ds_read_b128 v[218:221], v151 offset:4096
	ds_read_b128 v[222:225], v151 offset:5120
	ds_read_b128 v[226:229], v151 offset:6144
	ds_read_b128 v[230:233], v151 offset:7168
	global_load_lds_dwordx4 v[234:235], off
	v_lshl_add_u64 v[234:235], s[20:21], 0, v[140:141]
	s_add_i32 m0, s17, 0xe000
	s_nop 0
	global_load_lds_dwordx4 v[234:235], off
	s_waitcnt vmcnt(8)
	s_waitcnt lgkmcnt(0)
	s_barrier
	s_waitcnt lgkmcnt(0)
	v_mfma_f32_16x16x32_f16 v[130:133], v[144:147], v[202:205], 0
	v_mfma_f32_16x16x32_f16 v[126:129], v[178:181], v[202:205], 0
	v_mfma_f32_16x16x32_f16 v[114:117], v[144:147], v[210:213], 0
	v_mfma_f32_16x16x32_f16 v[110:113], v[178:181], v[210:213], 0
	v_mfma_f32_16x16x32_f16 v[98:101], v[144:147], v[218:221], 0
	v_mfma_f32_16x16x32_f16 v[94:97], v[178:181], v[218:221], 0
	v_mfma_f32_16x16x32_f16 v[82:85], v[144:147], v[226:229], 0
	v_mfma_f32_16x16x32_f16 v[78:81], v[178:181], v[226:229], 0
	v_mfma_f32_16x16x32_f16 v[130:133], v[152:155], v[206:209], v[130:133]
	v_mfma_f32_16x16x32_f16 v[126:129], v[182:185], v[206:209], v[126:129]
	v_mfma_f32_16x16x32_f16 v[114:117], v[152:155], v[214:217], v[114:117]
	v_mfma_f32_16x16x32_f16 v[110:113], v[182:185], v[214:217], v[110:113]
	v_mfma_f32_16x16x32_f16 v[98:101], v[152:155], v[222:225], v[98:101]
	v_mfma_f32_16x16x32_f16 v[94:97], v[182:185], v[222:225], v[94:97]
	v_mfma_f32_16x16x32_f16 v[82:85], v[152:155], v[230:233], v[82:85]
	v_mfma_f32_16x16x32_f16 v[78:81], v[182:185], v[230:233], v[78:81]
	s_add_i32 s44, s44, s30
	v_lshl_add_u64 v[234:235], s[22:23], 0, v[0:1]
	s_mov_b32 m0, s44
	v_mfma_f32_16x16x32_f16 v[122:125], v[186:189], v[202:205], 0
	v_mfma_f32_16x16x32_f16 v[118:121], v[194:197], v[202:205], 0
	v_mfma_f32_16x16x32_f16 v[106:109], v[186:189], v[210:213], 0
	v_mfma_f32_16x16x32_f16 v[102:105], v[194:197], v[210:213], 0
	v_mfma_f32_16x16x32_f16 v[90:93], v[186:189], v[218:221], 0
	v_mfma_f32_16x16x32_f16 v[86:89], v[194:197], v[218:221], 0
	v_mfma_f32_16x16x32_f16 v[74:77], v[186:189], v[226:229], 0
	v_mfma_f32_16x16x32_f16 v[70:73], v[194:197], v[226:229], 0
	v_mfma_f32_16x16x32_f16 v[122:125], v[190:193], v[206:209], v[122:125]
	v_mfma_f32_16x16x32_f16 v[118:121], v[198:201], v[206:209], v[118:121]
	v_mfma_f32_16x16x32_f16 v[106:109], v[190:193], v[214:217], v[106:109]
	v_mfma_f32_16x16x32_f16 v[102:105], v[198:201], v[214:217], v[102:105]
	v_mfma_f32_16x16x32_f16 v[90:93], v[190:193], v[222:225], v[90:93]
	v_mfma_f32_16x16x32_f16 v[86:89], v[198:201], v[222:225], v[86:89]
	v_mfma_f32_16x16x32_f16 v[74:77], v[190:193], v[230:233], v[74:77]
	v_mfma_f32_16x16x32_f16 v[70:73], v[198:201], v[230:233], v[70:73]
	s_barrier
	ds_read_b128 v[202:205], v151 offset:16384
	ds_read_b128 v[206:209], v151 offset:17408
	ds_read_b128 v[210:213], v151 offset:18432
	ds_read_b128 v[214:217], v151 offset:19456
	ds_read_b128 v[218:221], v151 offset:20480
	ds_read_b128 v[222:225], v151 offset:21504
	ds_read_b128 v[226:229], v151 offset:22528
	ds_read_b128 v[230:233], v151 offset:23552
	global_load_lds_dwordx4 v[234:235], off
	s_add_i32 m0, s44, 0x2000
	s_add_u32 s44, s22, 0x40000
	v_lshl_add_u64 v[236:237], s[22:23], 0, v[138:139]
	s_addc_u32 s45, s23, 0
	s_add_i32 s46, s46, s30
	global_load_lds_dwordx4 v[236:237], off
	v_lshl_add_u64 v[238:239], s[44:45], 0, v[0:1]
	s_mov_b32 m0, s46
	v_lshl_add_u64 v[240:241], s[26:27], 0, v[134:135]
	global_load_lds_dwordx4 v[238:239], off
	v_lshl_add_u64 v[238:239], s[44:45], 0, v[138:139]
	s_add_i32 m0, s46, 0x2000
	s_nop 0
	global_load_lds_dwordx4 v[238:239], off
	v_lshl_add_u64 v[238:239], s[26:27], 0, v[2:3]
	s_mov_b32 m0, s17
	s_nop 0
	global_load_lds_dwordx4 v[238:239], off
	s_mov_b32 m0, s19
	s_nop 0
	global_load_lds_dwordx4 v[240:241], off
	s_waitcnt vmcnt(8)
	s_waitcnt lgkmcnt(0)
	s_barrier
; #define STAGE(bufoff, gbase, voff) do { _Pragma("unroll") for (int _i = 0; _i < 2; ++_i) \
;     __builtin_amdgcn_global_load_lds((const unsigned*)((const char*)(gbase) + (voff)[_i]), (LAS unsigned*)(lds + (bufoff) + ldsw + _i * 8192), 16, 0, 0); } while (0)
; #define LDA(dst, b, h) do { _Pragma("unroll") for (int m = 0; m < 4; ++m) _Pragma("unroll") for (int k = 0; k < 2; ++k) dst[m][k] = *(const LAS half8*)(lds + SA(b, h) + aoff + m * 2048 + k * 1024); } while (0)
; #define LDB(dst, b, h) do { _Pragma("unroll") for (int n = 0; n < 2; ++n) _Pragma("unroll") for (int k = 0; k < 2; ++k) dst[n][k] = *(const LAS half8*)(lds + SB(b, h) + boff + n * 2048 + k * 1024); } while (0)
; #define MMA(ai, bj, At_, Bt_) do { __builtin_amdgcn_s_setprio(1); \
;     _Pragma("unroll") for (int m = 0; m < 4; ++m) _Pragma("unroll") for (int n = 0; n < 2; ++n) _Pragma("unroll") for (int k = 0; k < 2; ++k) \
;       acc[ai][bj][m][n] = MFMA16(Bt_[n][k], At_[m][k], acc[ai][bj][m][n]); \
;     __builtin_amdgcn_s_setprio(0); } while (0)
; #define WAIT_V(n) asm volatile("s_waitcnt vmcnt(" #n ")" ::: "memory")
; #define WAIT_L(n) asm volatile("s_waitcnt lgkmcnt(" #n ")" ::: "memory")
; #define BAR __builtin_amdgcn_s_barrier()
; #define SCHED __builtin_amdgcn_sched_barrier(0)
; template <int EPI>
; DI void gemm_phase(const int wid_s, const h16* __restrict__ A, const h16* __restrict__ Bt, const int N, const int K, const EpiArgs ea) {
;     ...
;       LDA(At, 0, 1); STAGE(SB(0, 0), b2, voffB); STAGE(SB(0, 1), b2 + hstep, voffB); STAGE(SA(0, 0), a2, voffA);
;       WAIT_V(8); WAIT_L(0); BAR; MMA(1, 0, At, B0); MMA(1, 1, At, B1); BAR; SCHED;
;       LDB(B0, 1, 0); LDB(B1, 1, 1); SCHED; LDA(At, 1, 0); STAGE(SA(0, 1), a2 + hstep, voffA);
;       WAIT_V(8); WAIT_L(0); BAR; MMA(0, 0, At, B0); MMA(0, 1, At, B1); BAR; SCHED;
	s_waitcnt lgkmcnt(0)
	v_mfma_f32_16x16x32_f16 v[66:69], v[144:147], v[202:205], 0
	v_mfma_f32_16x16x32_f16 v[62:65], v[178:181], v[202:205], 0
	v_mfma_f32_16x16x32_f16 v[50:53], v[144:147], v[210:213], 0
	v_mfma_f32_16x16x32_f16 v[46:49], v[178:181], v[210:213], 0
	v_mfma_f32_16x16x32_f16 v[34:37], v[144:147], v[218:221], 0
	v_mfma_f32_16x16x32_f16 v[30:33], v[178:181], v[218:221], 0
	v_mfma_f32_16x16x32_f16 v[18:21], v[144:147], v[226:229], 0
	v_mfma_f32_16x16x32_f16 v[14:17], v[178:181], v[226:229], 0
	v_mfma_f32_16x16x32_f16 v[66:69], v[152:155], v[206:209], v[66:69]
	v_mfma_f32_16x16x32_f16 v[62:65], v[182:185], v[206:209], v[62:65]
	v_mfma_f32_16x16x32_f16 v[50:53], v[152:155], v[214:217], v[50:53]
	v_mfma_f32_16x16x32_f16 v[46:49], v[182:185], v[214:217], v[46:49]
	v_mfma_f32_16x16x32_f16 v[34:37], v[152:155], v[222:225], v[34:37]
	v_mfma_f32_16x16x32_f16 v[30:33], v[182:185], v[222:225], v[30:33]
	v_mfma_f32_16x16x32_f16 v[18:21], v[152:155], v[230:233], v[18:21]
	v_mfma_f32_16x16x32_f16 v[14:17], v[182:185], v[230:233], v[14:17]
	s_add_i32 s44, 0, 0x18000
	v_add_u32_e32 v177, s44, v148
	s_add_i32 s45, 0, 0x1c000
	v_mfma_f32_16x16x32_f16 v[58:61], v[186:189], v[202:205], 0
	v_mfma_f32_16x16x32_f16 v[54:57], v[194:197], v[202:205], 0
	v_mfma_f32_16x16x32_f16 v[42:45], v[186:189], v[210:213], 0
	v_mfma_f32_16x16x32_f16 v[38:41], v[194:197], v[210:213], 0
	v_mfma_f32_16x16x32_f16 v[26:29], v[186:189], v[218:221], 0
	v_mfma_f32_16x16x32_f16 v[22:25], v[194:197], v[218:221], 0
	v_mfma_f32_16x16x32_f16 v[10:13], v[186:189], v[226:229], 0
	v_mfma_f32_16x16x32_f16 v[6:9], v[194:197], v[226:229], 0
	v_mfma_f32_16x16x32_f16 v[58:61], v[190:193], v[206:209], v[58:61]
	v_mfma_f32_16x16x32_f16 v[54:57], v[198:201], v[206:209], v[54:57]
	v_mfma_f32_16x16x32_f16 v[42:45], v[190:193], v[214:217], v[42:45]
	v_mfma_f32_16x16x32_f16 v[38:41], v[198:201], v[214:217], v[38:41]
	v_mfma_f32_16x16x32_f16 v[26:29], v[190:193], v[222:225], v[26:29]
	v_mfma_f32_16x16x32_f16 v[22:25], v[198:201], v[222:225], v[22:25]
	v_mfma_f32_16x16x32_f16 v[10:13], v[190:193], v[230:233], v[10:13]
	v_mfma_f32_16x16x32_f16 v[6:9], v[198:201], v[230:233], v[6:9]
	s_barrier
	ds_read_b128 v[144:147], v177
	ds_read_b128 v[152:155], v177 offset:1024
	ds_read_b128 v[178:181], v177 offset:2048
	ds_read_b128 v[182:185], v177 offset:3072
	v_add_u32_e32 v177, s45, v148
	ds_read_b128 v[186:189], v177
	ds_read_b128 v[190:193], v177 offset:1024
	ds_read_b128 v[194:197], v177 offset:2048
	ds_read_b128 v[198:201], v177 offset:3072
	s_add_u32 s26, s26, 0x40000
	s_addc_u32 s27, s27, 0
	s_mov_b32 m0, s31
	v_lshl_add_u64 v[242:243], s[26:27], 0, v[2:3]
	ds_read_b128 v[202:205], v151 offset:32768
	ds_read_b128 v[206:209], v151 offset:33792
	ds_read_b128 v[210:213], v151 offset:34816
	ds_read_b128 v[214:217], v151 offset:35840
	ds_read_b128 v[218:221], v151 offset:36864
	ds_read_b128 v[222:225], v151 offset:37888
	ds_read_b128 v[226:229], v151 offset:38912
	ds_read_b128 v[230:233], v151 offset:39936
	global_load_lds_dwordx4 v[242:243], off
	v_lshl_add_u64 v[242:243], s[26:27], 0, v[134:135]
	s_mov_b32 m0, s38
	s_nop 0
	global_load_lds_dwordx4 v[242:243], off
	s_waitcnt vmcnt(8)
	s_waitcnt lgkmcnt(0)
	s_barrier
	s_waitcnt lgkmcnt(0)
	v_mfma_f32_16x16x32_f16 v[130:133], v[144:147], v[202:205], v[130:133]
	v_mfma_f32_16x16x32_f16 v[126:129], v[178:181], v[202:205], v[126:129]
	v_mfma_f32_16x16x32_f16 v[114:117], v[144:147], v[210:213], v[114:117]
	v_mfma_f32_16x16x32_f16 v[110:113], v[178:181], v[210:213], v[110:113]
	v_mfma_f32_16x16x32_f16 v[98:101], v[144:147], v[218:221], v[98:101]
	v_mfma_f32_16x16x32_f16 v[94:97], v[178:181], v[218:221], v[94:97]
	v_mfma_f32_16x16x32_f16 v[82:85], v[144:147], v[226:229], v[82:85]
	v_mfma_f32_16x16x32_f16 v[78:81], v[178:181], v[226:229], v[78:81]
	v_mfma_f32_16x16x32_f16 v[130:133], v[152:155], v[206:209], v[130:133]
	v_mfma_f32_16x16x32_f16 v[126:129], v[182:185], v[206:209], v[126:129]
	v_mfma_f32_16x16x32_f16 v[114:117], v[152:155], v[214:217], v[114:117]
	v_mfma_f32_16x16x32_f16 v[110:113], v[182:185], v[214:217], v[110:113]
	v_mfma_f32_16x16x32_f16 v[98:101], v[152:155], v[222:225], v[98:101]
	v_mfma_f32_16x16x32_f16 v[94:97], v[182:185], v[222:225], v[94:97]
	v_mfma_f32_16x16x32_f16 v[82:85], v[152:155], v[230:233], v[82:85]
	v_mfma_f32_16x16x32_f16 v[78:81], v[182:185], v[230:233], v[78:81]
	s_add_i32 s26, s44, s30
	v_lshl_add_u64 v[234:235], v[234:235], 0, s[36:37]
	s_mov_b32 m0, s26
	v_mfma_f32_16x16x32_f16 v[122:125], v[186:189], v[202:205], v[122:125]
	v_mfma_f32_16x16x32_f16 v[118:121], v[194:197], v[202:205], v[118:121]
	v_mfma_f32_16x16x32_f16 v[106:109], v[186:189], v[210:213], v[106:109]
	v_mfma_f32_16x16x32_f16 v[102:105], v[194:197], v[210:213], v[102:105]
	v_mfma_f32_16x16x32_f16 v[90:93], v[186:189], v[218:221], v[90:93]
	v_mfma_f32_16x16x32_f16 v[86:89], v[194:197], v[218:221], v[86:89]
	v_mfma_f32_16x16x32_f16 v[74:77], v[186:189], v[226:229], v[74:77]
	v_mfma_f32_16x16x32_f16 v[70:73], v[194:197], v[226:229], v[70:73]
	v_mfma_f32_16x16x32_f16 v[122:125], v[190:193], v[206:209], v[122:125]
	v_mfma_f32_16x16x32_f16 v[118:121], v[198:201], v[206:209], v[118:121]
	v_mfma_f32_16x16x32_f16 v[106:109], v[190:193], v[214:217], v[106:109]
	v_mfma_f32_16x16x32_f16 v[102:105], v[198:201], v[214:217], v[102:105]
	v_mfma_f32_16x16x32_f16 v[90:93], v[190:193], v[222:225], v[90:93]
	v_mfma_f32_16x16x32_f16 v[86:89], v[198:201], v[222:225], v[86:89]
	v_mfma_f32_16x16x32_f16 v[74:77], v[190:193], v[230:233], v[74:77]
	v_mfma_f32_16x16x32_f16 v[70:73], v[198:201], v[230:233], v[70:73]
	s_barrier
; #define STAGE(bufoff, gbase, voff) do { _Pragma("unroll") for (int _i = 0; _i < 2; ++_i) \
;     __builtin_amdgcn_global_load_lds((const unsigned*)((const char*)(gbase) + (voff)[_i]), (LAS unsigned*)(lds + (bufoff) + ldsw + _i * 8192), 16, 0, 0); } while (0)
; #define LDA(dst, b, h) do { _Pragma("unroll") for (int m = 0; m < 4; ++m) _Pragma("unroll") for (int k = 0; k < 2; ++k) dst[m][k] = *(const LAS half8*)(lds + SA(b, h) + aoff + m * 2048 + k * 1024); } while (0)
; #define LDB(dst, b, h) do { _Pragma("unroll") for (int n = 0; n < 2; ++n) _Pragma("unroll") for (int k = 0; k < 2; ++k) dst[n][k] = *(const LAS half8*)(lds + SB(b, h) + boff + n * 2048 + k * 1024); } while (0)
; #define MMA(ai, bj, At_, Bt_) do { __builtin_amdgcn_s_setprio(1); \
;     _Pragma("unroll") for (int m = 0; m < 4; ++m) _Pragma("unroll") for (int n = 0; n < 2; ++n) _Pragma("unroll") for (int k = 0; k < 2; ++k) \
;       acc[ai][bj][m][n] = MFMA16(Bt_[n][k], At_[m][k], acc[ai][bj][m][n]); \
;     __builtin_amdgcn_s_setprio(0); } while (0)
; #define WAIT_V(n) asm volatile("s_waitcnt vmcnt(" #n ")" ::: "memory")
; #define WAIT_L(n) asm volatile("s_waitcnt lgkmcnt(" #n ")" ::: "memory")
; #define BAR __builtin_amdgcn_s_barrier()
; #define SCHED __builtin_amdgcn_sched_barrier(0)
; template <int EPI>
; DI void gemm_phase(const int wid_s, const h16* __restrict__ A, const h16* __restrict__ Bt, const int N, const int K, const EpiArgs ea) {
;     ...
;     for (int t = 0; t < nt; t += 2) {
;       const bool last = (t == nt - 2);
;       const char* a1 = cA + (size_t)(t + 1) * kstep;
;       const char* a2 = last ? nA : cA + (size_t)(t + 2) * kstep; const char* b2 = last ? nB : cB + (size_t)(t + 2) * kstep;
;       const char* a3 = a2 + kstep; const char* b3 = b2 + kstep;
;       LDB(B0, 0, 0); LDB(B1, 0, 1); SCHED; LDA(At, 0, 0); STAGE(SA(1, 1), a1 + hstep, voffA);
;       WAIT_V(8); WAIT_L(0); BAR; MMA(0, 0, At, B0); MMA(0, 1, At, B1); BAR; SCHED;
;     ...
;       LDA(At, 1, 1); STAGE(SB(1, 0), b3, voffB); STAGE(SB(1, 1), b3 + hstep, voffB); STAGE(SA(1, 0), a3, voffA);
;       WAIT_V(8); WAIT_L(0); BAR; MMA(1, 0, At, B0); MMA(1, 1, At, B1); BAR; SCHED;
	ds_read_b128 v[202:205], v151 offset:49152
	ds_read_b128 v[206:209], v151 offset:50176
	ds_read_b128 v[210:213], v151 offset:51200
	ds_read_b128 v[214:217], v151 offset:52224
	ds_read_b128 v[218:221], v151 offset:53248
	ds_read_b128 v[222:225], v151 offset:54272
	ds_read_b128 v[226:229], v151 offset:55296
	ds_read_b128 v[230:233], v151 offset:56320
	global_load_lds_dwordx4 v[234:235], off
	s_add_i32 m0, s26, 0x2000
	s_add_u32 s22, s22, 0x40080
	v_lshl_add_u64 v[234:235], v[236:237], 0, s[36:37]
	s_addc_u32 s23, s23, 0
	s_add_i32 s26, s45, s30
	global_load_lds_dwordx4 v[234:235], off
	v_lshl_add_u64 v[234:235], s[22:23], 0, v[0:1]
	s_mov_b32 m0, s26
	s_nop 0
	global_load_lds_dwordx4 v[234:235], off
	v_lshl_add_u64 v[234:235], s[22:23], 0, v[138:139]
	s_add_i32 m0, s26, 0x2000
	s_nop 0
	global_load_lds_dwordx4 v[234:235], off
	v_lshl_add_u64 v[234:235], v[238:239], 0, s[36:37]
	s_mov_b32 m0, s39
	s_nop 0
	global_load_lds_dwordx4 v[234:235], off
	v_lshl_add_u64 v[234:235], v[240:241], 0, s[36:37]
	s_mov_b32 m0, s40
	s_nop 0
	global_load_lds_dwordx4 v[234:235], off
	s_waitcnt vmcnt(8)
	s_waitcnt lgkmcnt(0)
	s_barrier
	s_waitcnt lgkmcnt(0)
	v_mfma_f32_16x16x32_f16 v[66:69], v[144:147], v[202:205], v[66:69]
	v_mfma_f32_16x16x32_f16 v[62:65], v[178:181], v[202:205], v[62:65]
	v_mfma_f32_16x16x32_f16 v[50:53], v[144:147], v[210:213], v[50:53]
	v_mfma_f32_16x16x32_f16 v[46:49], v[178:181], v[210:213], v[46:49]
	v_mfma_f32_16x16x32_f16 v[34:37], v[144:147], v[218:221], v[34:37]
	v_mfma_f32_16x16x32_f16 v[30:33], v[178:181], v[218:221], v[30:33]
	v_mfma_f32_16x16x32_f16 v[18:21], v[144:147], v[226:229], v[18:21]
	v_mfma_f32_16x16x32_f16 v[14:17], v[178:181], v[226:229], v[14:17]
	v_mfma_f32_16x16x32_f16 v[66:69], v[152:155], v[206:209], v[66:69]
	v_mfma_f32_16x16x32_f16 v[62:65], v[182:185], v[206:209], v[62:65]
	v_mfma_f32_16x16x32_f16 v[50:53], v[152:155], v[214:217], v[50:53]
	v_mfma_f32_16x16x32_f16 v[46:49], v[182:185], v[214:217], v[46:49]
	v_mfma_f32_16x16x32_f16 v[34:37], v[152:155], v[222:225], v[34:37]
	v_mfma_f32_16x16x32_f16 v[30:33], v[182:185], v[222:225], v[30:33]
	v_mfma_f32_16x16x32_f16 v[18:21], v[152:155], v[230:233], v[18:21]
	v_mfma_f32_16x16x32_f16 v[14:17], v[182:185], v[230:233], v[14:17]
	v_mfma_f32_16x16x32_f16 v[58:61], v[186:189], v[202:205], v[58:61]
	v_mfma_f32_16x16x32_f16 v[54:57], v[194:197], v[202:205], v[54:57]
	v_mfma_f32_16x16x32_f16 v[42:45], v[186:189], v[210:213], v[42:45]
	v_mfma_f32_16x16x32_f16 v[38:41], v[194:197], v[210:213], v[38:41]
	v_mfma_f32_16x16x32_f16 v[26:29], v[186:189], v[218:221], v[26:29]
	v_mfma_f32_16x16x32_f16 v[22:25], v[194:197], v[218:221], v[22:25]
	v_mfma_f32_16x16x32_f16 v[10:13], v[186:189], v[226:229], v[10:13]
	v_mfma_f32_16x16x32_f16 v[6:9], v[194:197], v[226:229], v[6:9]
	v_mfma_f32_16x16x32_f16 v[58:61], v[190:193], v[206:209], v[58:61]
	v_mfma_f32_16x16x32_f16 v[54:57], v[198:201], v[206:209], v[54:57]
	v_mfma_f32_16x16x32_f16 v[42:45], v[190:193], v[214:217], v[42:45]
	v_mfma_f32_16x16x32_f16 v[38:41], v[198:201], v[214:217], v[38:41]
	v_mfma_f32_16x16x32_f16 v[26:29], v[190:193], v[222:225], v[26:29]
	v_mfma_f32_16x16x32_f16 v[22:25], v[198:201], v[222:225], v[22:25]
	v_mfma_f32_16x16x32_f16 v[10:13], v[190:193], v[230:233], v[10:13]
	v_mfma_f32_16x16x32_f16 v[6:9], v[198:201], v[230:233], v[6:9]
	s_barrier
	s_add_i32 s43, s43, 2
	s_add_u32 s41, s41, 0x100
	s_addc_u32 s42, s42, 0
	s_add_u32 s20, s20, 0x100
	s_addc_u32 s21, s21, 0
	s_cmp_gt_u32 s43, 13
.LBB0_175:
	s_add_u32 s22, s20, 0xfffc0080
	s_addc_u32 s23, s21, -1
	s_add_i32 s44, 0, 0x10000
	s_cmp_eq_u32 s43, 12
	s_cselect_b32 s27, s13, s23
	s_cselect_b32 s26, s12, s22
	v_add_u32_e32 v177, s44, v148
	s_cselect_b32 s23, s11, s42
	s_cselect_b32 s22, s9, s41
	s_add_i32 s46, 0, 0x14000
	ds_read_b128 v[144:147], v177
	ds_read_b128 v[152:155], v177 offset:1024
	ds_read_b128 v[178:181], v177 offset:2048
	ds_read_b128 v[182:185], v177 offset:3072
	v_add_u32_e32 v177, s46, v148
	ds_read_b128 v[186:189], v177
	ds_read_b128 v[190:193], v177 offset:1024
	ds_read_b128 v[194:197], v177 offset:2048
	ds_read_b128 v[198:201], v177 offset:3072
	v_lshl_add_u64 v[234:235], s[20:21], 0, v[142:143]
	s_add_i32 m0, s17, 0xc000
	ds_read_b128 v[202:205], v151
	ds_read_b128 v[206:209], v151 offset:1024
	ds_read_b128 v[210:213], v151 offset:2048
	ds_read_b128 v[214:217], v151 offset:3072
	ds_read_b128 v[218:221], v151 offset:4096
	ds_read_b128 v[222:225], v151 offset:5120
	ds_read_b128 v[226:229], v151 offset:6144
	ds_read_b128 v[230:233], v151 offset:7168
	global_load_lds_dwordx4 v[234:235], off
	v_lshl_add_u64 v[234:235], s[20:21], 0, v[140:141]
	s_add_i32 m0, s17, 0xe000
	s_nop 0
	global_load_lds_dwordx4 v[234:235], off
	s_waitcnt vmcnt(8)
	s_waitcnt lgkmcnt(0)
	s_barrier
; #define STAGE(bufoff, gbase, voff) do { _Pragma("unroll") for (int _i = 0; _i < 2; ++_i) \
;     __builtin_amdgcn_global_load_lds((const unsigned*)((const char*)(gbase) + (voff)[_i]), (LAS unsigned*)(lds + (bufoff) + ldsw + _i * 8192), 16, 0, 0); } while (0)
; #define LDA(dst, b, h) do { _Pragma("unroll") for (int m = 0; m < 4; ++m) _Pragma("unroll") for (int k = 0; k < 2; ++k) dst[m][k] = *(const LAS half8*)(lds + SA(b, h) + aoff + m * 2048 + k * 1024); } while (0)
; #define LDB(dst, b, h) do { _Pragma("unroll") for (int n = 0; n < 2; ++n) _Pragma("unroll") for (int k = 0; k < 2; ++k) dst[n][k] = *(const LAS half8*)(lds + SB(b, h) + boff + n * 2048 + k * 1024); } while (0)
; #define MMA(ai, bj, At_, Bt_) do { __builtin_amdgcn_s_setprio(1); \
;     _Pragma("unroll") for (int m = 0; m < 4; ++m) _Pragma("unroll") for (int n = 0; n < 2; ++n) _Pragma("unroll") for (int k = 0; k < 2; ++k) \
;       acc[ai][bj][m][n] = MFMA16(Bt_[n][k], At_[m][k], acc[ai][bj][m][n]); \
;     __builtin_amdgcn_s_setprio(0); } while (0)
; #define WAIT_V(n) asm volatile("s_waitcnt vmcnt(" #n ")" ::: "memory")
; #define WAIT_L(n) asm volatile("s_waitcnt lgkmcnt(" #n ")" ::: "memory")
; #define BAR __builtin_amdgcn_s_barrier()
; #define SCHED __builtin_amdgcn_sched_barrier(0)
; template <int EPI>
; DI void gemm_phase(const int wid_s, const h16* __restrict__ A, const h16* __restrict__ Bt, const int N, const int K, const EpiArgs ea) {
;     ...
;       LDB(B0, 0, 0); LDB(B1, 0, 1); SCHED; LDA(At, 0, 0); STAGE(SA(1, 1), a1 + hstep, voffA);
;       WAIT_V(8); WAIT_L(0); BAR; MMA(0, 0, At, B0); MMA(0, 1, At, B1); BAR; SCHED;
;       LDA(At, 0, 1); STAGE(SB(0, 0), b2, voffB); STAGE(SB(0, 1), b2 + hstep, voffB); STAGE(SA(0, 0), a2, voffA);
;       WAIT_V(8); WAIT_L(0); BAR; MMA(1, 0, At, B0); MMA(1, 1, At, B1); BAR; SCHED;
	s_waitcnt lgkmcnt(0)
	v_mfma_f32_16x16x32_f16 v[130:133], v[144:147], v[202:205], v[130:133]
	v_mfma_f32_16x16x32_f16 v[126:129], v[178:181], v[202:205], v[126:129]
	v_mfma_f32_16x16x32_f16 v[114:117], v[144:147], v[210:213], v[114:117]
	v_mfma_f32_16x16x32_f16 v[110:113], v[178:181], v[210:213], v[110:113]
	v_mfma_f32_16x16x32_f16 v[98:101], v[144:147], v[218:221], v[98:101]
	v_mfma_f32_16x16x32_f16 v[94:97], v[178:181], v[218:221], v[94:97]
	v_mfma_f32_16x16x32_f16 v[82:85], v[144:147], v[226:229], v[82:85]
	v_mfma_f32_16x16x32_f16 v[78:81], v[178:181], v[226:229], v[78:81]
	v_mfma_f32_16x16x32_f16 v[130:133], v[152:155], v[206:209], v[130:133]
	v_mfma_f32_16x16x32_f16 v[126:129], v[182:185], v[206:209], v[126:129]
	v_mfma_f32_16x16x32_f16 v[114:117], v[152:155], v[214:217], v[114:117]
	v_mfma_f32_16x16x32_f16 v[110:113], v[182:185], v[214:217], v[110:113]
	v_mfma_f32_16x16x32_f16 v[98:101], v[152:155], v[222:225], v[98:101]
	v_mfma_f32_16x16x32_f16 v[94:97], v[182:185], v[222:225], v[94:97]
	v_mfma_f32_16x16x32_f16 v[82:85], v[152:155], v[230:233], v[82:85]
	v_mfma_f32_16x16x32_f16 v[78:81], v[182:185], v[230:233], v[78:81]
	s_add_i32 s44, s44, s30
	v_lshl_add_u64 v[234:235], s[22:23], 0, v[0:1]
	s_mov_b32 m0, s44
	v_mfma_f32_16x16x32_f16 v[122:125], v[186:189], v[202:205], v[122:125]
	v_mfma_f32_16x16x32_f16 v[118:121], v[194:197], v[202:205], v[118:121]
	v_mfma_f32_16x16x32_f16 v[106:109], v[186:189], v[210:213], v[106:109]
	v_mfma_f32_16x16x32_f16 v[102:105], v[194:197], v[210:213], v[102:105]
	v_mfma_f32_16x16x32_f16 v[90:93], v[186:189], v[218:221], v[90:93]
	v_mfma_f32_16x16x32_f16 v[86:89], v[194:197], v[218:221], v[86:89]
	v_mfma_f32_16x16x32_f16 v[74:77], v[186:189], v[226:229], v[74:77]
	v_mfma_f32_16x16x32_f16 v[70:73], v[194:197], v[226:229], v[70:73]
	v_mfma_f32_16x16x32_f16 v[122:125], v[190:193], v[206:209], v[122:125]
	v_mfma_f32_16x16x32_f16 v[118:121], v[198:201], v[206:209], v[118:121]
	v_mfma_f32_16x16x32_f16 v[106:109], v[190:193], v[214:217], v[106:109]
	v_mfma_f32_16x16x32_f16 v[102:105], v[198:201], v[214:217], v[102:105]
	v_mfma_f32_16x16x32_f16 v[90:93], v[190:193], v[222:225], v[90:93]
	v_mfma_f32_16x16x32_f16 v[86:89], v[198:201], v[222:225], v[86:89]
	v_mfma_f32_16x16x32_f16 v[74:77], v[190:193], v[230:233], v[74:77]
	v_mfma_f32_16x16x32_f16 v[70:73], v[198:201], v[230:233], v[70:73]
	s_barrier
	ds_read_b128 v[202:205], v151 offset:16384
	ds_read_b128 v[206:209], v151 offset:17408
	ds_read_b128 v[210:213], v151 offset:18432
	ds_read_b128 v[214:217], v151 offset:19456
	ds_read_b128 v[218:221], v151 offset:20480
	ds_read_b128 v[222:225], v151 offset:21504
	ds_read_b128 v[226:229], v151 offset:22528
	ds_read_b128 v[230:233], v151 offset:23552
	global_load_lds_dwordx4 v[234:235], off
	s_add_i32 m0, s44, 0x2000
	s_add_u32 s44, s22, 0x40000
	v_lshl_add_u64 v[236:237], s[22:23], 0, v[138:139]
	s_addc_u32 s45, s23, 0
	s_add_i32 s46, s46, s30
	global_load_lds_dwordx4 v[236:237], off
	v_lshl_add_u64 v[238:239], s[44:45], 0, v[0:1]
	s_mov_b32 m0, s46
	v_lshl_add_u64 v[240:241], s[26:27], 0, v[134:135]
	global_load_lds_dwordx4 v[238:239], off
	v_lshl_add_u64 v[238:239], s[44:45], 0, v[138:139]
	s_add_i32 m0, s46, 0x2000
	s_nop 0
	global_load_lds_dwordx4 v[238:239], off
	v_lshl_add_u64 v[238:239], s[26:27], 0, v[2:3]
	s_mov_b32 m0, s17
	s_nop 0
	global_load_lds_dwordx4 v[238:239], off
	s_mov_b32 m0, s19
	s_nop 0
	global_load_lds_dwordx4 v[240:241], off
	s_waitcnt vmcnt(8)
	s_waitcnt lgkmcnt(0)
	s_barrier
	s_waitcnt lgkmcnt(0)
	v_mfma_f32_16x16x32_f16 v[66:69], v[144:147], v[202:205], v[66:69]
	v_mfma_f32_16x16x32_f16 v[62:65], v[178:181], v[202:205], v[62:65]
	v_mfma_f32_16x16x32_f16 v[50:53], v[144:147], v[210:213], v[50:53]
	v_mfma_f32_16x16x32_f16 v[46:49], v[178:181], v[210:213], v[46:49]
	v_mfma_f32_16x16x32_f16 v[34:37], v[144:147], v[218:221], v[34:37]
	v_mfma_f32_16x16x32_f16 v[30:33], v[178:181], v[218:221], v[30:33]
	v_mfma_f32_16x16x32_f16 v[18:21], v[144:147], v[226:229], v[18:21]
	v_mfma_f32_16x16x32_f16 v[14:17], v[178:181], v[226:229], v[14:17]
	v_mfma_f32_16x16x32_f16 v[66:69], v[152:155], v[206:209], v[66:69]
	v_mfma_f32_16x16x32_f16 v[62:65], v[182:185], v[206:209], v[62:65]
	v_mfma_f32_16x16x32_f16 v[50:53], v[152:155], v[214:217], v[50:53]
	v_mfma_f32_16x16x32_f16 v[46:49], v[182:185], v[214:217], v[46:49]
	v_mfma_f32_16x16x32_f16 v[34:37], v[152:155], v[222:225], v[34:37]
	v_mfma_f32_16x16x32_f16 v[30:33], v[182:185], v[222:225], v[30:33]
	v_mfma_f32_16x16x32_f16 v[18:21], v[152:155], v[230:233], v[18:21]
	v_mfma_f32_16x16x32_f16 v[14:17], v[182:185], v[230:233], v[14:17]
	s_add_i32 s44, 0, 0x18000
	v_add_u32_e32 v177, s44, v148
	s_add_i32 s45, 0, 0x1c000
	v_mfma_f32_16x16x32_f16 v[58:61], v[186:189], v[202:205], v[58:61]
	v_mfma_f32_16x16x32_f16 v[54:57], v[194:197], v[202:205], v[54:57]
	v_mfma_f32_16x16x32_f16 v[42:45], v[186:189], v[210:213], v[42:45]
	v_mfma_f32_16x16x32_f16 v[38:41], v[194:197], v[210:213], v[38:41]
	v_mfma_f32_16x16x32_f16 v[26:29], v[186:189], v[218:221], v[26:29]
	v_mfma_f32_16x16x32_f16 v[22:25], v[194:197], v[218:221], v[22:25]
	v_mfma_f32_16x16x32_f16 v[10:13], v[186:189], v[226:229], v[10:13]
	v_mfma_f32_16x16x32_f16 v[6:9], v[194:197], v[226:229], v[6:9]
	v_mfma_f32_16x16x32_f16 v[58:61], v[190:193], v[206:209], v[58:61]
	v_mfma_f32_16x16x32_f16 v[54:57], v[198:201], v[206:209], v[54:57]
	v_mfma_f32_16x16x32_f16 v[42:45], v[190:193], v[214:217], v[42:45]
	v_mfma_f32_16x16x32_f16 v[38:41], v[198:201], v[214:217], v[38:41]
	v_mfma_f32_16x16x32_f16 v[26:29], v[190:193], v[222:225], v[26:29]
	v_mfma_f32_16x16x32_f16 v[22:25], v[198:201], v[222:225], v[22:25]
	v_mfma_f32_16x16x32_f16 v[10:13], v[190:193], v[230:233], v[10:13]
	v_mfma_f32_16x16x32_f16 v[6:9], v[198:201], v[230:233], v[6:9]
	s_barrier
; #define STAGE(bufoff, gbase, voff) do { _Pragma("unroll") for (int _i = 0; _i < 2; ++_i) \
;     __builtin_amdgcn_global_load_lds((const unsigned*)((const char*)(gbase) + (voff)[_i]), (LAS unsigned*)(lds + (bufoff) + ldsw + _i * 8192), 16, 0, 0); } while (0)
; #define LDA(dst, b, h) do { _Pragma("unroll") for (int m = 0; m < 4; ++m) _Pragma("unroll") for (int k = 0; k < 2; ++k) dst[m][k] = *(const LAS half8*)(lds + SA(b, h) + aoff + m * 2048 + k * 1024); } while (0)
; #define LDB(dst, b, h) do { _Pragma("unroll") for (int n = 0; n < 2; ++n) _Pragma("unroll") for (int k = 0; k < 2; ++k) dst[n][k] = *(const LAS half8*)(lds + SB(b, h) + boff + n * 2048 + k * 1024); } while (0)
; #define MMA(ai, bj, At_, Bt_) do { __builtin_amdgcn_s_setprio(1); \
;     _Pragma("unroll") for (int m = 0; m < 4; ++m) _Pragma("unroll") for (int n = 0; n < 2; ++n) _Pragma("unroll") for (int k = 0; k < 2; ++k) \
;       acc[ai][bj][m][n] = MFMA16(Bt_[n][k], At_[m][k], acc[ai][bj][m][n]); \
;     __builtin_amdgcn_s_setprio(0); } while (0)
; #define WAIT_V(n) asm volatile("s_waitcnt vmcnt(" #n ")" ::: "memory")
; #define WAIT_L(n) asm volatile("s_waitcnt lgkmcnt(" #n ")" ::: "memory")
; #define BAR __builtin_amdgcn_s_barrier()
; #define SCHED __builtin_amdgcn_sched_barrier(0)
; template <int EPI>
; DI void gemm_phase(const int wid_s, const h16* __restrict__ A, const h16* __restrict__ Bt, const int N, const int K, const EpiArgs ea) {
;     ...
;       LDB(B0, 1, 0); LDB(B1, 1, 1); SCHED; LDA(At, 1, 0); STAGE(SA(0, 1), a2 + hstep, voffA);
;       WAIT_V(8); WAIT_L(0); BAR; MMA(0, 0, At, B0); MMA(0, 1, At, B1); BAR; SCHED;
;       LDA(At, 1, 1); STAGE(SB(1, 0), b3, voffB); STAGE(SB(1, 1), b3 + hstep, voffB); STAGE(SA(1, 0), a3, voffA);
;       WAIT_V(8); WAIT_L(0); BAR; MMA(1, 0, At, B0); MMA(1, 1, At, B1); BAR; SCHED;
;     }
;     if (wr == 0) BAR;
	ds_read_b128 v[144:147], v177
	ds_read_b128 v[152:155], v177 offset:1024
	ds_read_b128 v[178:181], v177 offset:2048
	ds_read_b128 v[182:185], v177 offset:3072
	v_add_u32_e32 v177, s45, v148
	ds_read_b128 v[186:189], v177
	ds_read_b128 v[190:193], v177 offset:1024
	ds_read_b128 v[194:197], v177 offset:2048
	ds_read_b128 v[198:201], v177 offset:3072
	s_add_u32 s26, s26, 0x40000
	s_addc_u32 s27, s27, 0
	s_mov_b32 m0, s31
	v_lshl_add_u64 v[242:243], s[26:27], 0, v[2:3]
	ds_read_b128 v[202:205], v151 offset:32768
	ds_read_b128 v[206:209], v151 offset:33792
	ds_read_b128 v[210:213], v151 offset:34816
	ds_read_b128 v[214:217], v151 offset:35840
	ds_read_b128 v[218:221], v151 offset:36864
	ds_read_b128 v[222:225], v151 offset:37888
	ds_read_b128 v[226:229], v151 offset:38912
	ds_read_b128 v[230:233], v151 offset:39936
	global_load_lds_dwordx4 v[242:243], off
	v_lshl_add_u64 v[242:243], s[26:27], 0, v[134:135]
	s_mov_b32 m0, s38
	s_nop 0
	global_load_lds_dwordx4 v[242:243], off
	s_waitcnt vmcnt(8)
	s_waitcnt lgkmcnt(0)
	s_barrier
	s_waitcnt lgkmcnt(0)
	v_mfma_f32_16x16x32_f16 v[130:133], v[144:147], v[202:205], v[130:133]
	v_mfma_f32_16x16x32_f16 v[126:129], v[178:181], v[202:205], v[126:129]
	v_mfma_f32_16x16x32_f16 v[114:117], v[144:147], v[210:213], v[114:117]
	v_mfma_f32_16x16x32_f16 v[110:113], v[178:181], v[210:213], v[110:113]
	v_mfma_f32_16x16x32_f16 v[98:101], v[144:147], v[218:221], v[98:101]
	v_mfma_f32_16x16x32_f16 v[94:97], v[178:181], v[218:221], v[94:97]
	v_mfma_f32_16x16x32_f16 v[82:85], v[144:147], v[226:229], v[82:85]
	v_mfma_f32_16x16x32_f16 v[78:81], v[178:181], v[226:229], v[78:81]
	v_mfma_f32_16x16x32_f16 v[130:133], v[152:155], v[206:209], v[130:133]
	v_mfma_f32_16x16x32_f16 v[126:129], v[182:185], v[206:209], v[126:129]
	v_mfma_f32_16x16x32_f16 v[114:117], v[152:155], v[214:217], v[114:117]
	v_mfma_f32_16x16x32_f16 v[110:113], v[182:185], v[214:217], v[110:113]
	v_mfma_f32_16x16x32_f16 v[98:101], v[152:155], v[222:225], v[98:101]
	v_mfma_f32_16x16x32_f16 v[94:97], v[182:185], v[222:225], v[94:97]
	v_mfma_f32_16x16x32_f16 v[82:85], v[152:155], v[230:233], v[82:85]
	v_mfma_f32_16x16x32_f16 v[78:81], v[182:185], v[230:233], v[78:81]
	s_add_i32 s26, s44, s30
	v_lshl_add_u64 v[234:235], v[234:235], 0, s[36:37]
	s_mov_b32 m0, s26
	v_mfma_f32_16x16x32_f16 v[122:125], v[186:189], v[202:205], v[122:125]
	v_mfma_f32_16x16x32_f16 v[118:121], v[194:197], v[202:205], v[118:121]
	v_mfma_f32_16x16x32_f16 v[106:109], v[186:189], v[210:213], v[106:109]
	v_mfma_f32_16x16x32_f16 v[102:105], v[194:197], v[210:213], v[102:105]
	v_mfma_f32_16x16x32_f16 v[90:93], v[186:189], v[218:221], v[90:93]
	v_mfma_f32_16x16x32_f16 v[86:89], v[194:197], v[218:221], v[86:89]
	v_mfma_f32_16x16x32_f16 v[74:77], v[186:189], v[226:229], v[74:77]
	v_mfma_f32_16x16x32_f16 v[70:73], v[194:197], v[226:229], v[70:73]
	v_mfma_f32_16x16x32_f16 v[122:125], v[190:193], v[206:209], v[122:125]
	v_mfma_f32_16x16x32_f16 v[118:121], v[198:201], v[206:209], v[118:121]
	v_mfma_f32_16x16x32_f16 v[106:109], v[190:193], v[214:217], v[106:109]
	v_mfma_f32_16x16x32_f16 v[102:105], v[198:201], v[214:217], v[102:105]
	v_mfma_f32_16x16x32_f16 v[90:93], v[190:193], v[222:225], v[90:93]
	v_mfma_f32_16x16x32_f16 v[86:89], v[198:201], v[222:225], v[86:89]
	v_mfma_f32_16x16x32_f16 v[74:77], v[190:193], v[230:233], v[74:77]
	v_mfma_f32_16x16x32_f16 v[70:73], v[198:201], v[230:233], v[70:73]
	s_barrier
	ds_read_b128 v[202:205], v151 offset:49152
	ds_read_b128 v[206:209], v151 offset:50176
	ds_read_b128 v[210:213], v151 offset:51200
	ds_read_b128 v[214:217], v151 offset:52224
	ds_read_b128 v[218:221], v151 offset:53248
	ds_read_b128 v[222:225], v151 offset:54272
	ds_read_b128 v[226:229], v151 offset:55296
	ds_read_b128 v[230:233], v151 offset:56320
	global_load_lds_dwordx4 v[234:235], off
	s_add_i32 m0, s26, 0x2000
	s_add_u32 s22, s22, 0x40080
	v_lshl_add_u64 v[234:235], v[236:237], 0, s[36:37]
	s_addc_u32 s23, s23, 0
	s_add_i32 s26, s45, s30
	global_load_lds_dwordx4 v[234:235], off
	v_lshl_add_u64 v[234:235], s[22:23], 0, v[0:1]
	s_mov_b32 m0, s26
	s_nop 0
	global_load_lds_dwordx4 v[234:235], off
	v_lshl_add_u64 v[234:235], s[22:23], 0, v[138:139]
	s_add_i32 m0, s26, 0x2000
	s_nop 0
	global_load_lds_dwordx4 v[234:235], off
	v_lshl_add_u64 v[234:235], v[238:239], 0, s[36:37]
	s_mov_b32 m0, s39
	s_nop 0
	global_load_lds_dwordx4 v[234:235], off
	v_lshl_add_u64 v[234:235], v[240:241], 0, s[36:37]
	s_mov_b32 m0, s40
	s_nop 0
	global_load_lds_dwordx4 v[234:235], off
	s_waitcnt vmcnt(8)
	s_waitcnt lgkmcnt(0)
	s_barrier
	s_waitcnt lgkmcnt(0)
	v_mfma_f32_16x16x32_f16 v[66:69], v[144:147], v[202:205], v[66:69]
	v_mfma_f32_16x16x32_f16 v[62:65], v[178:181], v[202:205], v[62:65]
	v_mfma_f32_16x16x32_f16 v[50:53], v[144:147], v[210:213], v[50:53]
	v_mfma_f32_16x16x32_f16 v[46:49], v[178:181], v[210:213], v[46:49]
	v_mfma_f32_16x16x32_f16 v[34:37], v[144:147], v[218:221], v[34:37]
	v_mfma_f32_16x16x32_f16 v[30:33], v[178:181], v[218:221], v[30:33]
	v_mfma_f32_16x16x32_f16 v[18:21], v[144:147], v[226:229], v[18:21]
	v_mfma_f32_16x16x32_f16 v[14:17], v[178:181], v[226:229], v[14:17]
	v_mfma_f32_16x16x32_f16 v[66:69], v[152:155], v[206:209], v[66:69]
	v_mfma_f32_16x16x32_f16 v[62:65], v[182:185], v[206:209], v[62:65]
	v_mfma_f32_16x16x32_f16 v[50:53], v[152:155], v[214:217], v[50:53]
	v_mfma_f32_16x16x32_f16 v[46:49], v[182:185], v[214:217], v[46:49]
	v_mfma_f32_16x16x32_f16 v[34:37], v[152:155], v[222:225], v[34:37]
	v_mfma_f32_16x16x32_f16 v[30:33], v[182:185], v[222:225], v[30:33]
	v_mfma_f32_16x16x32_f16 v[18:21], v[152:155], v[230:233], v[18:21]
	v_mfma_f32_16x16x32_f16 v[14:17], v[182:185], v[230:233], v[14:17]
	v_mfma_f32_16x16x32_f16 v[58:61], v[186:189], v[202:205], v[58:61]
	v_mfma_f32_16x16x32_f16 v[54:57], v[194:197], v[202:205], v[54:57]
	v_mfma_f32_16x16x32_f16 v[42:45], v[186:189], v[210:213], v[42:45]
	v_mfma_f32_16x16x32_f16 v[38:41], v[194:197], v[210:213], v[38:41]
	v_mfma_f32_16x16x32_f16 v[26:29], v[186:189], v[218:221], v[26:29]
	v_mfma_f32_16x16x32_f16 v[22:25], v[194:197], v[218:221], v[22:25]
	v_mfma_f32_16x16x32_f16 v[10:13], v[186:189], v[226:229], v[10:13]
	v_mfma_f32_16x16x32_f16 v[6:9], v[194:197], v[226:229], v[6:9]
	v_mfma_f32_16x16x32_f16 v[58:61], v[190:193], v[206:209], v[58:61]
	v_mfma_f32_16x16x32_f16 v[54:57], v[198:201], v[206:209], v[54:57]
	v_mfma_f32_16x16x32_f16 v[42:45], v[190:193], v[214:217], v[42:45]
	v_mfma_f32_16x16x32_f16 v[38:41], v[198:201], v[214:217], v[38:41]
	v_mfma_f32_16x16x32_f16 v[26:29], v[190:193], v[222:225], v[26:29]
	v_mfma_f32_16x16x32_f16 v[22:25], v[198:201], v[222:225], v[22:25]
	v_mfma_f32_16x16x32_f16 v[10:13], v[190:193], v[230:233], v[10:13]
	v_mfma_f32_16x16x32_f16 v[6:9], v[198:201], v[230:233], v[6:9]
	s_barrier
	s_add_i32 s43, s43, 2
	s_add_u32 s41, s41, 0x100
	s_addc_u32 s42, s42, 0
	s_add_u32 s20, s20, 0x100
	s_addc_u32 s21, s21, 0
	s_cmp_gt_u32 s43, 13
	s_cbranch_scc0 .LBB0_175
	s_and_b64 vcc, exec, s[4:5]
	s_cbranch_vccz .LBB0_178
	s_barrier

; #define STAGE(bufoff, gbase, voff) do { _Pragma("unroll") for (int _i = 0; _i < 2; ++_i) \
;     __builtin_amdgcn_global_load_lds((const unsigned*)((const char*)(gbase) + (voff)[_i]), (LAS unsigned*)(lds + (bufoff) + ldsw + _i * 8192), 16, 0, 0); } while (0)
; #define LDA(dst, b, h) do { _Pragma("unroll") for (int m = 0; m < 4; ++m) _Pragma("unroll") for (int k = 0; k < 2; ++k) dst[m][k] = *(const LAS half8*)(lds + SA(b, h) + aoff + m * 2048 + k * 1024); } while (0)
; #define LDB(dst, b, h) do { _Pragma("unroll") for (int n = 0; n < 2; ++n) _Pragma("unroll") for (int k = 0; k < 2; ++k) dst[n][k] = *(const LAS half8*)(lds + SB(b, h) + boff + n * 2048 + k * 1024); } while (0)
; #define MMA(ai, bj, At_, Bt_) do { __builtin_amdgcn_s_setprio(1); \
;     _Pragma("unroll") for (int m = 0; m < 4; ++m) _Pragma("unroll") for (int n = 0; n < 2; ++n) _Pragma("unroll") for (int k = 0; k < 2; ++k) \
;       acc[ai][bj][m][n] = MFMA16(Bt_[n][k], At_[m][k], acc[ai][bj][m][n]); \
;     __builtin_amdgcn_s_setprio(0); } while (0)
; #define WAIT_V(n) asm volatile("s_waitcnt vmcnt(" #n ")" ::: "memory")
; #define WAIT_L(n) asm volatile("s_waitcnt lgkmcnt(" #n ")" ::: "memory")
; #define BAR __builtin_amdgcn_s_barrier()
; template <int EPI>
; DI void gemm_phase(const int wid_s, const h16* __restrict__ A, const h16* __restrict__ Bt, const int N, const int K, const EpiArgs ea) {
;     ...
;     const int Ln = L + (int)gridDim.x;
;     const bool has_next = Ln < nwg;
;     int nbrow = brow, nbcol = bcol;
;     if (has_next) TILE_RC(Ln, nbrow, nbcol);
;     const char* nA = (const char*)A + (size_t)nbrow * K * 2;
;     const char* nB = (const char*)Bt + (size_t)nbcol * K * 2;
;     for (int t = 0; t < nt; t += 2) {
;       const bool last = (t == nt - 2);
;       const char* a1 = cA + (size_t)(t + 1) * kstep;
;       const char* a2 = last ? nA : cA + (size_t)(t + 2) * kstep; const char* b2 = last ? nB : cB + (size_t)(t + 2) * kstep;
;       const char* a3 = a2 + kstep; const char* b3 = b2 + kstep;
;       LDB(B0, 0, 0); LDB(B1, 0, 1); SCHED; LDA(At, 0, 0); STAGE(SA(1, 1), a1 + hstep, voffA);
;       WAIT_V(8); WAIT_L(0); BAR; MMA(0, 0, At, B0); MMA(0, 1, At, B1); BAR; SCHED;
;       LDA(At, 0, 1); STAGE(SB(0, 0), b2, voffB); STAGE(SB(0, 1), b2 + hstep, voffB); STAGE(SA(0, 0), a2, voffA);
;       WAIT_V(8); WAIT_L(0); BAR; MMA(1, 0, At, B0); MMA(1, 1, At, B1); BAR; SCHED;
.LBB0_385:
	s_ashr_i32 s9, s8, 31
	s_lshl_b64 s[16:17], s[8:9], 11
	s_add_u32 s9, s92, s16
	s_addc_u32 s41, s93, s17
	s_ashr_i32 s11, s10, 31
	s_lshl_b64 s[18:19], s[10:11], 11
	v_readlane_b32 s11, v249, 29
	s_add_u32 s11, s11, s18
	v_readlane_b32 s26, v249, 31
	s_addc_u32 s42, s26, s19
	v_readlane_b32 s26, v249, 30
	s_add_u32 s43, s26, s22
	v_readlane_b32 s22, v249, 32
	s_addc_u32 s44, s22, s23
	s_add_u32 s45, s86, s20
	v_mov_b32_e32 v6, 0
	v_lshl_add_u64 v[144:145], v[140:141], 0, s[20:21]
	v_lshl_add_u64 v[146:147], v[142:143], 0, s[20:21]
	s_addc_u32 s46, s87, s21
	s_mov_b32 s47, -2
	s_mov_b64 s[20:21], 0
	s_add_u32 s22, s45, s20
	s_addc_u32 s23, s46, s21
	s_add_u32 s22, s22, 0x520e100
	s_addc_u32 s23, s23, 0
	s_add_u32 s48, s43, s20
	s_addc_u32 s49, s44, s21
	s_add_i32 s50, 0, 0x10000
	s_cmpk_eq_i32 s20, 0x700
	s_cselect_b32 s27, s41, s23
	s_cselect_b32 s26, s9, s22
	v_add_u32_e32 v177, s50, v148
	s_cselect_b32 s23, s42, s49
	s_cselect_b32 s22, s11, s48
	s_add_i32 s51, 0, 0x14000
	ds_read_b128 v[152:155], v177
	ds_read_b128 v[178:181], v177 offset:1024
	ds_read_b128 v[182:185], v177 offset:2048
	ds_read_b128 v[186:189], v177 offset:3072
	v_add_u32_e32 v177, s51, v148
	ds_read_b128 v[190:193], v177
	ds_read_b128 v[194:197], v177 offset:1024
	ds_read_b128 v[198:201], v177 offset:2048
	ds_read_b128 v[202:205], v177 offset:3072
	v_lshl_add_u64 v[238:239], v[146:147], 0, s[20:21]
	s_add_i32 m0, s13, 0xc000
	ds_read_b128 v[206:209], v151
	ds_read_b128 v[210:213], v151 offset:1024
	ds_read_b128 v[214:217], v151 offset:2048
	ds_read_b128 v[218:221], v151 offset:3072
	ds_read_b128 v[222:225], v151 offset:4096
	ds_read_b128 v[226:229], v151 offset:5120
	ds_read_b128 v[230:233], v151 offset:6144
	ds_read_b128 v[234:237], v151 offset:7168
	global_load_lds_dwordx4 v[238:239], off
	v_lshl_add_u64 v[238:239], v[144:145], 0, s[20:21]
	s_add_i32 m0, s13, 0xe000
	s_nop 0
	global_load_lds_dwordx4 v[238:239], off
	s_waitcnt vmcnt(8)
	s_waitcnt lgkmcnt(0)
	s_barrier
	s_waitcnt lgkmcnt(0)
	v_mfma_f32_16x16x32_f16 v[130:133], v[152:155], v[206:209], 0
	v_mfma_f32_16x16x32_f16 v[126:129], v[182:185], v[206:209], 0
	v_mfma_f32_16x16x32_f16 v[122:125], v[152:155], v[214:217], 0
	v_mfma_f32_16x16x32_f16 v[118:121], v[182:185], v[214:217], 0
	v_mfma_f32_16x16x32_f16 v[106:109], v[152:155], v[222:225], 0
	v_mfma_f32_16x16x32_f16 v[102:105], v[182:185], v[222:225], 0
	v_mfma_f32_16x16x32_f16 v[90:93], v[152:155], v[230:233], 0
	v_mfma_f32_16x16x32_f16 v[86:89], v[182:185], v[230:233], 0
	v_mfma_f32_16x16x32_f16 v[130:133], v[178:181], v[210:213], v[130:133]
	v_mfma_f32_16x16x32_f16 v[126:129], v[186:189], v[210:213], v[126:129]
	v_mfma_f32_16x16x32_f16 v[122:125], v[178:181], v[218:221], v[122:125]
	v_mfma_f32_16x16x32_f16 v[118:121], v[186:189], v[218:221], v[118:121]
	v_mfma_f32_16x16x32_f16 v[106:109], v[178:181], v[226:229], v[106:109]
	v_mfma_f32_16x16x32_f16 v[102:105], v[186:189], v[226:229], v[102:105]
	v_mfma_f32_16x16x32_f16 v[90:93], v[178:181], v[234:237], v[90:93]
	v_mfma_f32_16x16x32_f16 v[86:89], v[186:189], v[234:237], v[86:89]
	s_add_i32 s48, s50, s30
	v_lshl_add_u64 v[238:239], s[22:23], 0, v[0:1]
	s_mov_b32 m0, s48
	v_mfma_f32_16x16x32_f16 v[114:117], v[190:193], v[206:209], 0
	v_mfma_f32_16x16x32_f16 v[110:113], v[198:201], v[206:209], 0
	v_mfma_f32_16x16x32_f16 v[98:101], v[190:193], v[214:217], 0
	v_mfma_f32_16x16x32_f16 v[94:97], v[198:201], v[214:217], 0
	v_mfma_f32_16x16x32_f16 v[82:85], v[190:193], v[222:225], 0
	v_mfma_f32_16x16x32_f16 v[78:81], v[198:201], v[222:225], 0
	v_mfma_f32_16x16x32_f16 v[74:77], v[190:193], v[230:233], 0
	v_mfma_f32_16x16x32_f16 v[70:73], v[198:201], v[230:233], 0
	v_mfma_f32_16x16x32_f16 v[114:117], v[194:197], v[210:213], v[114:117]
	v_mfma_f32_16x16x32_f16 v[110:113], v[202:205], v[210:213], v[110:113]
	v_mfma_f32_16x16x32_f16 v[98:101], v[194:197], v[218:221], v[98:101]
	v_mfma_f32_16x16x32_f16 v[94:97], v[202:205], v[218:221], v[94:97]
	v_mfma_f32_16x16x32_f16 v[82:85], v[194:197], v[226:229], v[82:85]
	v_mfma_f32_16x16x32_f16 v[78:81], v[202:205], v[226:229], v[78:81]
	v_mfma_f32_16x16x32_f16 v[74:77], v[194:197], v[234:237], v[74:77]
	v_mfma_f32_16x16x32_f16 v[70:73], v[202:205], v[234:237], v[70:73]
	s_barrier
	ds_read_b128 v[206:209], v151 offset:16384
	ds_read_b128 v[210:213], v151 offset:17408
	ds_read_b128 v[214:217], v151 offset:18432
	ds_read_b128 v[218:221], v151 offset:19456
	ds_read_b128 v[222:225], v151 offset:20480
	ds_read_b128 v[226:229], v151 offset:21504
	ds_read_b128 v[230:233], v151 offset:22528
	ds_read_b128 v[234:237], v151 offset:23552
	global_load_lds_dwordx4 v[238:239], off
	s_add_i32 m0, s48, 0x2000
	s_add_u32 s48, s22, 0x40000
	v_lshl_add_u64 v[240:241], s[22:23], 0, v[2:3]
	s_addc_u32 s49, s23, 0
	s_add_i32 s50, s51, s30
	global_load_lds_dwordx4 v[240:241], off
	v_lshl_add_u64 v[242:243], s[48:49], 0, v[0:1]
	s_mov_b32 m0, s50
	v_lshl_add_u64 v[244:245], s[26:27], 0, v[134:135]
	global_load_lds_dwordx4 v[242:243], off
	v_lshl_add_u64 v[242:243], s[48:49], 0, v[2:3]
	s_add_i32 m0, s50, 0x2000
	s_nop 0
	global_load_lds_dwordx4 v[242:243], off
	v_lshl_add_u64 v[242:243], s[26:27], 0, v[138:139]
	s_mov_b32 m0, s13
	s_nop 0
	global_load_lds_dwordx4 v[242:243], off
	s_mov_b32 m0, s15
	s_nop 0
	global_load_lds_dwordx4 v[244:245], off
	s_waitcnt vmcnt(8)
	s_waitcnt lgkmcnt(0)
	s_barrier
; #define STAGE(bufoff, gbase, voff) do { _Pragma("unroll") for (int _i = 0; _i < 2; ++_i) \
;     __builtin_amdgcn_global_load_lds((const unsigned*)((const char*)(gbase) + (voff)[_i]), (LAS unsigned*)(lds + (bufoff) + ldsw + _i * 8192), 16, 0, 0); } while (0)
; #define LDA(dst, b, h) do { _Pragma("unroll") for (int m = 0; m < 4; ++m) _Pragma("unroll") for (int k = 0; k < 2; ++k) dst[m][k] = *(const LAS half8*)(lds + SA(b, h) + aoff + m * 2048 + k * 1024); } while (0)
; #define LDB(dst, b, h) do { _Pragma("unroll") for (int n = 0; n < 2; ++n) _Pragma("unroll") for (int k = 0; k < 2; ++k) dst[n][k] = *(const LAS half8*)(lds + SB(b, h) + boff + n * 2048 + k * 1024); } while (0)
; #define MMA(ai, bj, At_, Bt_) do { __builtin_amdgcn_s_setprio(1); \
;     _Pragma("unroll") for (int m = 0; m < 4; ++m) _Pragma("unroll") for (int n = 0; n < 2; ++n) _Pragma("unroll") for (int k = 0; k < 2; ++k) \
;       acc[ai][bj][m][n] = MFMA16(Bt_[n][k], At_[m][k], acc[ai][bj][m][n]); \
;     __builtin_amdgcn_s_setprio(0); } while (0)
; #define WAIT_V(n) asm volatile("s_waitcnt vmcnt(" #n ")" ::: "memory")
; #define WAIT_L(n) asm volatile("s_waitcnt lgkmcnt(" #n ")" ::: "memory")
; #define BAR __builtin_amdgcn_s_barrier()
; #define SCHED __builtin_amdgcn_sched_barrier(0)
; template <int EPI>
; DI void gemm_phase(const int wid_s, const h16* __restrict__ A, const h16* __restrict__ Bt, const int N, const int K, const EpiArgs ea) {
;     ...
;       LDB(B0, 0, 0); LDB(B1, 0, 1); SCHED; LDA(At, 0, 0); STAGE(SA(1, 1), a1 + hstep, voffA);
;       WAIT_V(8); WAIT_L(0); BAR; MMA(0, 0, At, B0); MMA(0, 1, At, B1); BAR; SCHED;
;       LDA(At, 0, 1); STAGE(SB(0, 0), b2, voffB); STAGE(SB(0, 1), b2 + hstep, voffB); STAGE(SA(0, 0), a2, voffA);
;       WAIT_V(8); WAIT_L(0); BAR; MMA(1, 0, At, B0); MMA(1, 1, At, B1); BAR; SCHED;
;       LDB(B0, 1, 0); LDB(B1, 1, 1); SCHED; LDA(At, 1, 0); STAGE(SA(0, 1), a2 + hstep, voffA);
;       WAIT_V(8); WAIT_L(0); BAR; MMA(0, 0, At, B0); MMA(0, 1, At, B1); BAR; SCHED;
	s_waitcnt lgkmcnt(0)
	v_mfma_f32_16x16x32_f16 v[66:69], v[152:155], v[206:209], 0
	v_mfma_f32_16x16x32_f16 v[62:65], v[182:185], v[206:209], 0
	v_mfma_f32_16x16x32_f16 v[58:61], v[152:155], v[214:217], 0
	v_mfma_f32_16x16x32_f16 v[54:57], v[182:185], v[214:217], 0
	v_mfma_f32_16x16x32_f16 v[42:45], v[152:155], v[222:225], 0
	v_mfma_f32_16x16x32_f16 v[38:41], v[182:185], v[222:225], 0
	v_mfma_f32_16x16x32_f16 v[26:29], v[152:155], v[230:233], 0
	v_mfma_f32_16x16x32_f16 v[22:25], v[182:185], v[230:233], 0
	v_mfma_f32_16x16x32_f16 v[66:69], v[178:181], v[210:213], v[66:69]
	v_mfma_f32_16x16x32_f16 v[62:65], v[186:189], v[210:213], v[62:65]
	v_mfma_f32_16x16x32_f16 v[58:61], v[178:181], v[218:221], v[58:61]
	v_mfma_f32_16x16x32_f16 v[54:57], v[186:189], v[218:221], v[54:57]
	v_mfma_f32_16x16x32_f16 v[42:45], v[178:181], v[226:229], v[42:45]
	v_mfma_f32_16x16x32_f16 v[38:41], v[186:189], v[226:229], v[38:41]
	v_mfma_f32_16x16x32_f16 v[26:29], v[178:181], v[234:237], v[26:29]
	v_mfma_f32_16x16x32_f16 v[22:25], v[186:189], v[234:237], v[22:25]
	s_add_i32 s48, 0, 0x18000
	v_add_u32_e32 v177, s48, v148
	s_add_i32 s49, 0, 0x1c000
	v_mfma_f32_16x16x32_f16 v[50:53], v[190:193], v[206:209], 0
	v_mfma_f32_16x16x32_f16 v[46:49], v[198:201], v[206:209], 0
	v_mfma_f32_16x16x32_f16 v[34:37], v[190:193], v[214:217], 0
	v_mfma_f32_16x16x32_f16 v[30:33], v[198:201], v[214:217], 0
	v_mfma_f32_16x16x32_f16 v[18:21], v[190:193], v[222:225], 0
	v_mfma_f32_16x16x32_f16 v[14:17], v[198:201], v[222:225], 0
	v_mfma_f32_16x16x32_f16 v[10:13], v[190:193], v[230:233], 0
	v_mfma_f32_16x16x32_f16 v[6:9], v[198:201], v[230:233], 0
	v_mfma_f32_16x16x32_f16 v[50:53], v[194:197], v[210:213], v[50:53]
	v_mfma_f32_16x16x32_f16 v[46:49], v[202:205], v[210:213], v[46:49]
	v_mfma_f32_16x16x32_f16 v[34:37], v[194:197], v[218:221], v[34:37]
	v_mfma_f32_16x16x32_f16 v[30:33], v[202:205], v[218:221], v[30:33]
	v_mfma_f32_16x16x32_f16 v[18:21], v[194:197], v[226:229], v[18:21]
	v_mfma_f32_16x16x32_f16 v[14:17], v[202:205], v[226:229], v[14:17]
	v_mfma_f32_16x16x32_f16 v[10:13], v[194:197], v[234:237], v[10:13]
	v_mfma_f32_16x16x32_f16 v[6:9], v[202:205], v[234:237], v[6:9]
	s_barrier
	ds_read_b128 v[152:155], v177
	ds_read_b128 v[178:181], v177 offset:1024
	ds_read_b128 v[182:185], v177 offset:2048
	ds_read_b128 v[186:189], v177 offset:3072
	v_add_u32_e32 v177, s49, v148
	ds_read_b128 v[190:193], v177
	ds_read_b128 v[194:197], v177 offset:1024
	ds_read_b128 v[198:201], v177 offset:2048
	ds_read_b128 v[202:205], v177 offset:3072
	s_add_u32 s26, s26, 0x40000
	s_addc_u32 s27, s27, 0
	s_mov_b32 m0, s31
	v_lshl_add_u64 v[246:247], s[26:27], 0, v[138:139]
	ds_read_b128 v[206:209], v151 offset:32768
	ds_read_b128 v[210:213], v151 offset:33792
	ds_read_b128 v[214:217], v151 offset:34816
	ds_read_b128 v[218:221], v151 offset:35840
	ds_read_b128 v[222:225], v151 offset:36864
	ds_read_b128 v[226:229], v151 offset:37888
	ds_read_b128 v[230:233], v151 offset:38912
	ds_read_b128 v[234:237], v151 offset:39936
	global_load_lds_dwordx4 v[246:247], off
	v_lshl_add_u64 v[246:247], s[26:27], 0, v[134:135]
	s_mov_b32 m0, s38
	s_nop 0
	global_load_lds_dwordx4 v[246:247], off
	s_waitcnt vmcnt(8)
	s_waitcnt lgkmcnt(0)
	s_barrier
	s_waitcnt lgkmcnt(0)
	v_mfma_f32_16x16x32_f16 v[130:133], v[152:155], v[206:209], v[130:133]
	v_mfma_f32_16x16x32_f16 v[126:129], v[182:185], v[206:209], v[126:129]
	v_mfma_f32_16x16x32_f16 v[122:125], v[152:155], v[214:217], v[122:125]
	v_mfma_f32_16x16x32_f16 v[118:121], v[182:185], v[214:217], v[118:121]
	v_mfma_f32_16x16x32_f16 v[106:109], v[152:155], v[222:225], v[106:109]
	v_mfma_f32_16x16x32_f16 v[102:105], v[182:185], v[222:225], v[102:105]
	v_mfma_f32_16x16x32_f16 v[90:93], v[152:155], v[230:233], v[90:93]
	v_mfma_f32_16x16x32_f16 v[86:89], v[182:185], v[230:233], v[86:89]
	v_mfma_f32_16x16x32_f16 v[130:133], v[178:181], v[210:213], v[130:133]
	v_mfma_f32_16x16x32_f16 v[126:129], v[186:189], v[210:213], v[126:129]
	v_mfma_f32_16x16x32_f16 v[122:125], v[178:181], v[218:221], v[122:125]
	v_mfma_f32_16x16x32_f16 v[118:121], v[186:189], v[218:221], v[118:121]
	v_mfma_f32_16x16x32_f16 v[106:109], v[178:181], v[226:229], v[106:109]
	v_mfma_f32_16x16x32_f16 v[102:105], v[186:189], v[226:229], v[102:105]
	v_mfma_f32_16x16x32_f16 v[90:93], v[178:181], v[234:237], v[90:93]
	v_mfma_f32_16x16x32_f16 v[86:89], v[186:189], v[234:237], v[86:89]
	s_add_i32 s26, s48, s30
	v_lshl_add_u64 v[238:239], v[238:239], 0, s[36:37]
	s_mov_b32 m0, s26
	v_mfma_f32_16x16x32_f16 v[114:117], v[190:193], v[206:209], v[114:117]
	v_mfma_f32_16x16x32_f16 v[110:113], v[198:201], v[206:209], v[110:113]
	v_mfma_f32_16x16x32_f16 v[98:101], v[190:193], v[214:217], v[98:101]
	v_mfma_f32_16x16x32_f16 v[94:97], v[198:201], v[214:217], v[94:97]
	v_mfma_f32_16x16x32_f16 v[82:85], v[190:193], v[222:225], v[82:85]
	v_mfma_f32_16x16x32_f16 v[78:81], v[198:201], v[222:225], v[78:81]
	v_mfma_f32_16x16x32_f16 v[74:77], v[190:193], v[230:233], v[74:77]
	v_mfma_f32_16x16x32_f16 v[70:73], v[198:201], v[230:233], v[70:73]
	v_mfma_f32_16x16x32_f16 v[114:117], v[194:197], v[210:213], v[114:117]
	v_mfma_f32_16x16x32_f16 v[110:113], v[202:205], v[210:213], v[110:113]
	v_mfma_f32_16x16x32_f16 v[98:101], v[194:197], v[218:221], v[98:101]
	v_mfma_f32_16x16x32_f16 v[94:97], v[202:205], v[218:221], v[94:97]
	v_mfma_f32_16x16x32_f16 v[82:85], v[194:197], v[226:229], v[82:85]
	v_mfma_f32_16x16x32_f16 v[78:81], v[202:205], v[226:229], v[78:81]
	v_mfma_f32_16x16x32_f16 v[74:77], v[194:197], v[234:237], v[74:77]
	v_mfma_f32_16x16x32_f16 v[70:73], v[202:205], v[234:237], v[70:73]
	s_barrier
; #define STAGE(bufoff, gbase, voff) do { _Pragma("unroll") for (int _i = 0; _i < 2; ++_i) \
;     __builtin_amdgcn_global_load_lds((const unsigned*)((const char*)(gbase) + (voff)[_i]), (LAS unsigned*)(lds + (bufoff) + ldsw + _i * 8192), 16, 0, 0); } while (0)
; #define LDA(dst, b, h) do { _Pragma("unroll") for (int m = 0; m < 4; ++m) _Pragma("unroll") for (int k = 0; k < 2; ++k) dst[m][k] = *(const LAS half8*)(lds + SA(b, h) + aoff + m * 2048 + k * 1024); } while (0)
; #define LDB(dst, b, h) do { _Pragma("unroll") for (int n = 0; n < 2; ++n) _Pragma("unroll") for (int k = 0; k < 2; ++k) dst[n][k] = *(const LAS half8*)(lds + SB(b, h) + boff + n * 2048 + k * 1024); } while (0)
; #define MMA(ai, bj, At_, Bt_) do { __builtin_amdgcn_s_setprio(1); \
;     _Pragma("unroll") for (int m = 0; m < 4; ++m) _Pragma("unroll") for (int n = 0; n < 2; ++n) _Pragma("unroll") for (int k = 0; k < 2; ++k) \
;       acc[ai][bj][m][n] = MFMA16(Bt_[n][k], At_[m][k], acc[ai][bj][m][n]); \
;     __builtin_amdgcn_s_setprio(0); } while (0)
; #define WAIT_V(n) asm volatile("s_waitcnt vmcnt(" #n ")" ::: "memory")
; #define BAR __builtin_amdgcn_s_barrier()
; template <int EPI>
; DI void gemm_phase(const int wid_s, const h16* __restrict__ A, const h16* __restrict__ Bt, const int N, const int K, const EpiArgs ea) {
;     ...
;     for (int t = 0; t < nt; t += 2) {
;       const bool last = (t == nt - 2);
;       const char* a1 = cA + (size_t)(t + 1) * kstep;
;       const char* a2 = last ? nA : cA + (size_t)(t + 2) * kstep; const char* b2 = last ? nB : cB + (size_t)(t + 2) * kstep;
;       const char* a3 = a2 + kstep; const char* b3 = b2 + kstep;
;       LDB(B0, 0, 0); LDB(B1, 0, 1); SCHED; LDA(At, 0, 0); STAGE(SA(1, 1), a1 + hstep, voffA);
;       WAIT_V(8); WAIT_L(0); BAR; MMA(0, 0, At, B0); MMA(0, 1, At, B1); BAR; SCHED;
;       LDA(At, 0, 1); STAGE(SB(0, 0), b2, voffB); STAGE(SB(0, 1), b2 + hstep, voffB); STAGE(SA(0, 0), a2, voffA);
;       WAIT_V(8); WAIT_L(0); BAR; MMA(1, 0, At, B0); MMA(1, 1, At, B1); BAR; SCHED;
;       LDB(B0, 1, 0); LDB(B1, 1, 1); SCHED; LDA(At, 1, 0); STAGE(SA(0, 1), a2 + hstep, voffA);
;       WAIT_V(8); WAIT_L(0); BAR; MMA(0, 0, At, B0); MMA(0, 1, At, B1); BAR; SCHED;
;       LDA(At, 1, 1); STAGE(SB(1, 0), b3, voffB); STAGE(SB(1, 1), b3 + hstep, voffB); STAGE(SA(1, 0), a3, voffA);
;       WAIT_V(8); WAIT_L(0); BAR; MMA(1, 0, At, B0); MMA(1, 1, At, B1); BAR; SCHED;
	ds_read_b128 v[206:209], v151 offset:49152
	ds_read_b128 v[210:213], v151 offset:50176
	ds_read_b128 v[214:217], v151 offset:51200
	ds_read_b128 v[218:221], v151 offset:52224
	ds_read_b128 v[222:225], v151 offset:53248
	ds_read_b128 v[226:229], v151 offset:54272
	ds_read_b128 v[230:233], v151 offset:55296
	ds_read_b128 v[234:237], v151 offset:56320
	global_load_lds_dwordx4 v[238:239], off
	s_add_i32 m0, s26, 0x2000
	s_add_u32 s22, s22, 0x40080
	v_lshl_add_u64 v[238:239], v[240:241], 0, s[36:37]
	s_addc_u32 s23, s23, 0
	s_add_i32 s26, s49, s30
	global_load_lds_dwordx4 v[238:239], off
	v_lshl_add_u64 v[238:239], s[22:23], 0, v[0:1]
	s_mov_b32 m0, s26
	s_nop 0
	global_load_lds_dwordx4 v[238:239], off
	v_lshl_add_u64 v[238:239], s[22:23], 0, v[2:3]
	s_add_i32 m0, s26, 0x2000
	s_nop 0
	global_load_lds_dwordx4 v[238:239], off
	v_lshl_add_u64 v[238:239], v[242:243], 0, s[36:37]
	s_mov_b32 m0, s39
	s_nop 0
	global_load_lds_dwordx4 v[238:239], off
	v_lshl_add_u64 v[238:239], v[244:245], 0, s[36:37]
	s_mov_b32 m0, s40
	s_nop 0
	global_load_lds_dwordx4 v[238:239], off
	s_waitcnt vmcnt(8)
	s_waitcnt lgkmcnt(0)
	s_barrier
	s_waitcnt lgkmcnt(0)
	v_mfma_f32_16x16x32_f16 v[66:69], v[152:155], v[206:209], v[66:69]
	v_mfma_f32_16x16x32_f16 v[62:65], v[182:185], v[206:209], v[62:65]
	v_mfma_f32_16x16x32_f16 v[58:61], v[152:155], v[214:217], v[58:61]
	v_mfma_f32_16x16x32_f16 v[54:57], v[182:185], v[214:217], v[54:57]
	v_mfma_f32_16x16x32_f16 v[42:45], v[152:155], v[222:225], v[42:45]
	v_mfma_f32_16x16x32_f16 v[38:41], v[182:185], v[222:225], v[38:41]
	v_mfma_f32_16x16x32_f16 v[26:29], v[152:155], v[230:233], v[26:29]
	v_mfma_f32_16x16x32_f16 v[22:25], v[182:185], v[230:233], v[22:25]
	v_mfma_f32_16x16x32_f16 v[66:69], v[178:181], v[210:213], v[66:69]
	v_mfma_f32_16x16x32_f16 v[62:65], v[186:189], v[210:213], v[62:65]
	v_mfma_f32_16x16x32_f16 v[58:61], v[178:181], v[218:221], v[58:61]
	v_mfma_f32_16x16x32_f16 v[54:57], v[186:189], v[218:221], v[54:57]
	v_mfma_f32_16x16x32_f16 v[42:45], v[178:181], v[226:229], v[42:45]
	v_mfma_f32_16x16x32_f16 v[38:41], v[186:189], v[226:229], v[38:41]
	v_mfma_f32_16x16x32_f16 v[26:29], v[178:181], v[234:237], v[26:29]
	v_mfma_f32_16x16x32_f16 v[22:25], v[186:189], v[234:237], v[22:25]
	v_mfma_f32_16x16x32_f16 v[50:53], v[190:193], v[206:209], v[50:53]
	v_mfma_f32_16x16x32_f16 v[46:49], v[198:201], v[206:209], v[46:49]
	v_mfma_f32_16x16x32_f16 v[34:37], v[190:193], v[214:217], v[34:37]
	v_mfma_f32_16x16x32_f16 v[30:33], v[198:201], v[214:217], v[30:33]
	v_mfma_f32_16x16x32_f16 v[18:21], v[190:193], v[222:225], v[18:21]
	v_mfma_f32_16x16x32_f16 v[14:17], v[198:201], v[222:225], v[14:17]
	v_mfma_f32_16x16x32_f16 v[10:13], v[190:193], v[230:233], v[10:13]
	v_mfma_f32_16x16x32_f16 v[6:9], v[198:201], v[230:233], v[6:9]
	v_mfma_f32_16x16x32_f16 v[50:53], v[194:197], v[210:213], v[50:53]
	v_mfma_f32_16x16x32_f16 v[46:49], v[202:205], v[210:213], v[46:49]
	v_mfma_f32_16x16x32_f16 v[34:37], v[194:197], v[218:221], v[34:37]
	v_mfma_f32_16x16x32_f16 v[30:33], v[202:205], v[218:221], v[30:33]
	v_mfma_f32_16x16x32_f16 v[18:21], v[194:197], v[226:229], v[18:21]
	v_mfma_f32_16x16x32_f16 v[14:17], v[202:205], v[226:229], v[14:17]
	v_mfma_f32_16x16x32_f16 v[10:13], v[194:197], v[234:237], v[10:13]
	v_mfma_f32_16x16x32_f16 v[6:9], v[202:205], v[234:237], v[6:9]
	s_barrier
	s_add_i32 s47, s47, 2
	s_add_u32 s20, s20, 0x100
	s_addc_u32 s21, s21, 0
	s_cmp_gt_u32 s47, 13
.LBB0_386:
	s_add_u32 s22, s45, s20
	s_addc_u32 s23, s46, s21
	s_add_u32 s22, s22, 0x520e100
	s_addc_u32 s23, s23, 0
	s_add_u32 s48, s43, s20
	s_addc_u32 s49, s44, s21
	s_add_i32 s50, 0, 0x10000
	s_cmpk_eq_i32 s20, 0x700
	s_cselect_b32 s27, s41, s23
	s_cselect_b32 s26, s9, s22
	v_add_u32_e32 v177, s50, v148
	s_cselect_b32 s23, s42, s49
	s_cselect_b32 s22, s11, s48
	s_add_i32 s51, 0, 0x14000
	ds_read_b128 v[152:155], v177
	ds_read_b128 v[178:181], v177 offset:1024
	ds_read_b128 v[182:185], v177 offset:2048
	ds_read_b128 v[186:189], v177 offset:3072
	v_add_u32_e32 v177, s51, v148
	ds_read_b128 v[190:193], v177
	ds_read_b128 v[194:197], v177 offset:1024
	ds_read_b128 v[198:201], v177 offset:2048
	ds_read_b128 v[202:205], v177 offset:3072
	v_lshl_add_u64 v[238:239], v[146:147], 0, s[20:21]
	s_add_i32 m0, s13, 0xc000
	ds_read_b128 v[206:209], v151
	ds_read_b128 v[210:213], v151 offset:1024
	ds_read_b128 v[214:217], v151 offset:2048
	ds_read_b128 v[218:221], v151 offset:3072
	ds_read_b128 v[222:225], v151 offset:4096
	ds_read_b128 v[226:229], v151 offset:5120
	ds_read_b128 v[230:233], v151 offset:6144
	ds_read_b128 v[234:237], v151 offset:7168
	global_load_lds_dwordx4 v[238:239], off
	v_lshl_add_u64 v[238:239], v[144:145], 0, s[20:21]
	s_add_i32 m0, s13, 0xe000
	s_nop 0
	global_load_lds_dwordx4 v[238:239], off
	s_waitcnt vmcnt(8)
	s_waitcnt lgkmcnt(0)
	s_barrier
; #define STAGE(bufoff, gbase, voff) do { _Pragma("unroll") for (int _i = 0; _i < 2; ++_i) \
;     __builtin_amdgcn_global_load_lds((const unsigned*)((const char*)(gbase) + (voff)[_i]), (LAS unsigned*)(lds + (bufoff) + ldsw + _i * 8192), 16, 0, 0); } while (0)
; #define LDA(dst, b, h) do { _Pragma("unroll") for (int m = 0; m < 4; ++m) _Pragma("unroll") for (int k = 0; k < 2; ++k) dst[m][k] = *(const LAS half8*)(lds + SA(b, h) + aoff + m * 2048 + k * 1024); } while (0)
; #define MMA(ai, bj, At_, Bt_) do { __builtin_amdgcn_s_setprio(1); \
;     _Pragma("unroll") for (int m = 0; m < 4; ++m) _Pragma("unroll") for (int n = 0; n < 2; ++n) _Pragma("unroll") for (int k = 0; k < 2; ++k) \
;       acc[ai][bj][m][n] = MFMA16(Bt_[n][k], At_[m][k], acc[ai][bj][m][n]); \
;     __builtin_amdgcn_s_setprio(0); } while (0)
; #define WAIT_V(n) asm volatile("s_waitcnt vmcnt(" #n ")" ::: "memory")
; #define WAIT_L(n) asm volatile("s_waitcnt lgkmcnt(" #n ")" ::: "memory")
; #define BAR __builtin_amdgcn_s_barrier()
; #define SCHED __builtin_amdgcn_sched_barrier(0)
; template <int EPI>
; DI void gemm_phase(const int wid_s, const h16* __restrict__ A, const h16* __restrict__ Bt, const int N, const int K, const EpiArgs ea) {
;     ...
;       WAIT_V(8); WAIT_L(0); BAR; MMA(0, 0, At, B0); MMA(0, 1, At, B1); BAR; SCHED;
;       LDA(At, 0, 1); STAGE(SB(0, 0), b2, voffB); STAGE(SB(0, 1), b2 + hstep, voffB); STAGE(SA(0, 0), a2, voffA);
;       WAIT_V(8); WAIT_L(0); BAR; MMA(1, 0, At, B0); MMA(1, 1, At, B1); BAR; SCHED;
	s_waitcnt lgkmcnt(0)
	v_mfma_f32_16x16x32_f16 v[130:133], v[152:155], v[206:209], v[130:133]
	v_mfma_f32_16x16x32_f16 v[126:129], v[182:185], v[206:209], v[126:129]
	v_mfma_f32_16x16x32_f16 v[122:125], v[152:155], v[214:217], v[122:125]
	v_mfma_f32_16x16x32_f16 v[118:121], v[182:185], v[214:217], v[118:121]
	v_mfma_f32_16x16x32_f16 v[106:109], v[152:155], v[222:225], v[106:109]
	v_mfma_f32_16x16x32_f16 v[102:105], v[182:185], v[222:225], v[102:105]
	v_mfma_f32_16x16x32_f16 v[90:93], v[152:155], v[230:233], v[90:93]
	v_mfma_f32_16x16x32_f16 v[86:89], v[182:185], v[230:233], v[86:89]
	v_mfma_f32_16x16x32_f16 v[130:133], v[178:181], v[210:213], v[130:133]
	v_mfma_f32_16x16x32_f16 v[126:129], v[186:189], v[210:213], v[126:129]
	v_mfma_f32_16x16x32_f16 v[122:125], v[178:181], v[218:221], v[122:125]
	v_mfma_f32_16x16x32_f16 v[118:121], v[186:189], v[218:221], v[118:121]
	v_mfma_f32_16x16x32_f16 v[106:109], v[178:181], v[226:229], v[106:109]
	v_mfma_f32_16x16x32_f16 v[102:105], v[186:189], v[226:229], v[102:105]
	v_mfma_f32_16x16x32_f16 v[90:93], v[178:181], v[234:237], v[90:93]
	v_mfma_f32_16x16x32_f16 v[86:89], v[186:189], v[234:237], v[86:89]
	s_add_i32 s48, s50, s30
	v_lshl_add_u64 v[238:239], s[22:23], 0, v[0:1]
	s_mov_b32 m0, s48
	v_mfma_f32_16x16x32_f16 v[114:117], v[190:193], v[206:209], v[114:117]
	v_mfma_f32_16x16x32_f16 v[110:113], v[198:201], v[206:209], v[110:113]
	v_mfma_f32_16x16x32_f16 v[98:101], v[190:193], v[214:217], v[98:101]
	v_mfma_f32_16x16x32_f16 v[94:97], v[198:201], v[214:217], v[94:97]
	v_mfma_f32_16x16x32_f16 v[82:85], v[190:193], v[222:225], v[82:85]
	v_mfma_f32_16x16x32_f16 v[78:81], v[198:201], v[222:225], v[78:81]
	v_mfma_f32_16x16x32_f16 v[74:77], v[190:193], v[230:233], v[74:77]
	v_mfma_f32_16x16x32_f16 v[70:73], v[198:201], v[230:233], v[70:73]
	v_mfma_f32_16x16x32_f16 v[114:117], v[194:197], v[210:213], v[114:117]
	v_mfma_f32_16x16x32_f16 v[110:113], v[202:205], v[210:213], v[110:113]
	v_mfma_f32_16x16x32_f16 v[98:101], v[194:197], v[218:221], v[98:101]
	v_mfma_f32_16x16x32_f16 v[94:97], v[202:205], v[218:221], v[94:97]
	v_mfma_f32_16x16x32_f16 v[82:85], v[194:197], v[226:229], v[82:85]
	v_mfma_f32_16x16x32_f16 v[78:81], v[202:205], v[226:229], v[78:81]
	v_mfma_f32_16x16x32_f16 v[74:77], v[194:197], v[234:237], v[74:77]
	v_mfma_f32_16x16x32_f16 v[70:73], v[202:205], v[234:237], v[70:73]
	s_barrier
	ds_read_b128 v[206:209], v151 offset:16384
	ds_read_b128 v[210:213], v151 offset:17408
	ds_read_b128 v[214:217], v151 offset:18432
	ds_read_b128 v[218:221], v151 offset:19456
	ds_read_b128 v[222:225], v151 offset:20480
	ds_read_b128 v[226:229], v151 offset:21504
	ds_read_b128 v[230:233], v151 offset:22528
	ds_read_b128 v[234:237], v151 offset:23552
	global_load_lds_dwordx4 v[238:239], off
	s_add_i32 m0, s48, 0x2000
	s_add_u32 s48, s22, 0x40000
	v_lshl_add_u64 v[240:241], s[22:23], 0, v[2:3]
	s_addc_u32 s49, s23, 0
	s_add_i32 s50, s51, s30
	global_load_lds_dwordx4 v[240:241], off
	v_lshl_add_u64 v[242:243], s[48:49], 0, v[0:1]
	s_mov_b32 m0, s50
	v_lshl_add_u64 v[244:245], s[26:27], 0, v[134:135]
	global_load_lds_dwordx4 v[242:243], off
	v_lshl_add_u64 v[242:243], s[48:49], 0, v[2:3]
	s_add_i32 m0, s50, 0x2000
	s_nop 0
	global_load_lds_dwordx4 v[242:243], off
	v_lshl_add_u64 v[242:243], s[26:27], 0, v[138:139]
	s_mov_b32 m0, s13
	s_nop 0
	global_load_lds_dwordx4 v[242:243], off
	s_mov_b32 m0, s15
	s_nop 0
	global_load_lds_dwordx4 v[244:245], off
	s_waitcnt vmcnt(8)
	s_waitcnt lgkmcnt(0)
	s_barrier
	s_waitcnt lgkmcnt(0)
	v_mfma_f32_16x16x32_f16 v[66:69], v[152:155], v[206:209], v[66:69]
	v_mfma_f32_16x16x32_f16 v[62:65], v[182:185], v[206:209], v[62:65]
	v_mfma_f32_16x16x32_f16 v[58:61], v[152:155], v[214:217], v[58:61]
	v_mfma_f32_16x16x32_f16 v[54:57], v[182:185], v[214:217], v[54:57]
	v_mfma_f32_16x16x32_f16 v[42:45], v[152:155], v[222:225], v[42:45]
	v_mfma_f32_16x16x32_f16 v[38:41], v[182:185], v[222:225], v[38:41]
	v_mfma_f32_16x16x32_f16 v[26:29], v[152:155], v[230:233], v[26:29]
	v_mfma_f32_16x16x32_f16 v[22:25], v[182:185], v[230:233], v[22:25]
	v_mfma_f32_16x16x32_f16 v[66:69], v[178:181], v[210:213], v[66:69]
	v_mfma_f32_16x16x32_f16 v[62:65], v[186:189], v[210:213], v[62:65]
	v_mfma_f32_16x16x32_f16 v[58:61], v[178:181], v[218:221], v[58:61]
	v_mfma_f32_16x16x32_f16 v[54:57], v[186:189], v[218:221], v[54:57]
	v_mfma_f32_16x16x32_f16 v[42:45], v[178:181], v[226:229], v[42:45]
	v_mfma_f32_16x16x32_f16 v[38:41], v[186:189], v[226:229], v[38:41]
	v_mfma_f32_16x16x32_f16 v[26:29], v[178:181], v[234:237], v[26:29]
	v_mfma_f32_16x16x32_f16 v[22:25], v[186:189], v[234:237], v[22:25]
	s_add_i32 s48, 0, 0x18000
	v_add_u32_e32 v177, s48, v148
	s_add_i32 s49, 0, 0x1c000
	v_mfma_f32_16x16x32_f16 v[50:53], v[190:193], v[206:209], v[50:53]
	v_mfma_f32_16x16x32_f16 v[46:49], v[198:201], v[206:209], v[46:49]
	v_mfma_f32_16x16x32_f16 v[34:37], v[190:193], v[214:217], v[34:37]
	v_mfma_f32_16x16x32_f16 v[30:33], v[198:201], v[214:217], v[30:33]
	v_mfma_f32_16x16x32_f16 v[18:21], v[190:193], v[222:225], v[18:21]
	v_mfma_f32_16x16x32_f16 v[14:17], v[198:201], v[222:225], v[14:17]
	v_mfma_f32_16x16x32_f16 v[10:13], v[190:193], v[230:233], v[10:13]
	v_mfma_f32_16x16x32_f16 v[6:9], v[198:201], v[230:233], v[6:9]
	v_mfma_f32_16x16x32_f16 v[50:53], v[194:197], v[210:213], v[50:53]
	v_mfma_f32_16x16x32_f16 v[46:49], v[202:205], v[210:213], v[46:49]
	v_mfma_f32_16x16x32_f16 v[34:37], v[194:197], v[218:221], v[34:37]
	v_mfma_f32_16x16x32_f16 v[30:33], v[202:205], v[218:221], v[30:33]
	v_mfma_f32_16x16x32_f16 v[18:21], v[194:197], v[226:229], v[18:21]
	v_mfma_f32_16x16x32_f16 v[14:17], v[202:205], v[226:229], v[14:17]
	v_mfma_f32_16x16x32_f16 v[10:13], v[194:197], v[234:237], v[10:13]
	v_mfma_f32_16x16x32_f16 v[6:9], v[202:205], v[234:237], v[6:9]
	s_barrier
; #define STAGE(bufoff, gbase, voff) do { _Pragma("unroll") for (int _i = 0; _i < 2; ++_i) \
;     __builtin_amdgcn_global_load_lds((const unsigned*)((const char*)(gbase) + (voff)[_i]), (LAS unsigned*)(lds + (bufoff) + ldsw + _i * 8192), 16, 0, 0); } while (0)
; #define LDA(dst, b, h) do { _Pragma("unroll") for (int m = 0; m < 4; ++m) _Pragma("unroll") for (int k = 0; k < 2; ++k) dst[m][k] = *(const LAS half8*)(lds + SA(b, h) + aoff + m * 2048 + k * 1024); } while (0)
; #define LDB(dst, b, h) do { _Pragma("unroll") for (int n = 0; n < 2; ++n) _Pragma("unroll") for (int k = 0; k < 2; ++k) dst[n][k] = *(const LAS half8*)(lds + SB(b, h) + boff + n * 2048 + k * 1024); } while (0)
; #define MMA(ai, bj, At_, Bt_) do { __builtin_amdgcn_s_setprio(1); \
;     _Pragma("unroll") for (int m = 0; m < 4; ++m) _Pragma("unroll") for (int n = 0; n < 2; ++n) _Pragma("unroll") for (int k = 0; k < 2; ++k) \
;       acc[ai][bj][m][n] = MFMA16(Bt_[n][k], At_[m][k], acc[ai][bj][m][n]); \
;     __builtin_amdgcn_s_setprio(0); } while (0)
; #define WAIT_V(n) asm volatile("s_waitcnt vmcnt(" #n ")" ::: "memory")
; #define WAIT_L(n) asm volatile("s_waitcnt lgkmcnt(" #n ")" ::: "memory")
; #define BAR __builtin_amdgcn_s_barrier()
; #define SCHED __builtin_amdgcn_sched_barrier(0)
; template <int EPI>
; DI void gemm_phase(const int wid_s, const h16* __restrict__ A, const h16* __restrict__ Bt, const int N, const int K, const EpiArgs ea) {
;     ...
;       LDB(B0, 1, 0); LDB(B1, 1, 1); SCHED; LDA(At, 1, 0); STAGE(SA(0, 1), a2 + hstep, voffA);
;       WAIT_V(8); WAIT_L(0); BAR; MMA(0, 0, At, B0); MMA(0, 1, At, B1); BAR; SCHED;
;       LDA(At, 1, 1); STAGE(SB(1, 0), b3, voffB); STAGE(SB(1, 1), b3 + hstep, voffB); STAGE(SA(1, 0), a3, voffA);
;       WAIT_V(8); WAIT_L(0); BAR; MMA(1, 0, At, B0); MMA(1, 1, At, B1); BAR; SCHED;
;     }
;     if (wr == 0) BAR;
	ds_read_b128 v[152:155], v177
	ds_read_b128 v[178:181], v177 offset:1024
	ds_read_b128 v[182:185], v177 offset:2048
	ds_read_b128 v[186:189], v177 offset:3072
	v_add_u32_e32 v177, s49, v148
	ds_read_b128 v[190:193], v177
	ds_read_b128 v[194:197], v177 offset:1024
	ds_read_b128 v[198:201], v177 offset:2048
	ds_read_b128 v[202:205], v177 offset:3072
	s_add_u32 s26, s26, 0x40000
	s_addc_u32 s27, s27, 0
	s_mov_b32 m0, s31
	v_lshl_add_u64 v[246:247], s[26:27], 0, v[138:139]
	ds_read_b128 v[206:209], v151 offset:32768
	ds_read_b128 v[210:213], v151 offset:33792
	ds_read_b128 v[214:217], v151 offset:34816
	ds_read_b128 v[218:221], v151 offset:35840
	ds_read_b128 v[222:225], v151 offset:36864
	ds_read_b128 v[226:229], v151 offset:37888
	ds_read_b128 v[230:233], v151 offset:38912
	ds_read_b128 v[234:237], v151 offset:39936
	global_load_lds_dwordx4 v[246:247], off
	v_lshl_add_u64 v[246:247], s[26:27], 0, v[134:135]
	s_mov_b32 m0, s38
	s_nop 0
	global_load_lds_dwordx4 v[246:247], off
	s_waitcnt vmcnt(8)
	s_waitcnt lgkmcnt(0)
	s_barrier
	s_waitcnt lgkmcnt(0)
	v_mfma_f32_16x16x32_f16 v[130:133], v[152:155], v[206:209], v[130:133]
	v_mfma_f32_16x16x32_f16 v[126:129], v[182:185], v[206:209], v[126:129]
	v_mfma_f32_16x16x32_f16 v[122:125], v[152:155], v[214:217], v[122:125]
	v_mfma_f32_16x16x32_f16 v[118:121], v[182:185], v[214:217], v[118:121]
	v_mfma_f32_16x16x32_f16 v[106:109], v[152:155], v[222:225], v[106:109]
	v_mfma_f32_16x16x32_f16 v[102:105], v[182:185], v[222:225], v[102:105]
	v_mfma_f32_16x16x32_f16 v[90:93], v[152:155], v[230:233], v[90:93]
	v_mfma_f32_16x16x32_f16 v[86:89], v[182:185], v[230:233], v[86:89]
	v_mfma_f32_16x16x32_f16 v[130:133], v[178:181], v[210:213], v[130:133]
	v_mfma_f32_16x16x32_f16 v[126:129], v[186:189], v[210:213], v[126:129]
	v_mfma_f32_16x16x32_f16 v[122:125], v[178:181], v[218:221], v[122:125]
	v_mfma_f32_16x16x32_f16 v[118:121], v[186:189], v[218:221], v[118:121]
	v_mfma_f32_16x16x32_f16 v[106:109], v[178:181], v[226:229], v[106:109]
	v_mfma_f32_16x16x32_f16 v[102:105], v[186:189], v[226:229], v[102:105]
	v_mfma_f32_16x16x32_f16 v[90:93], v[178:181], v[234:237], v[90:93]
	v_mfma_f32_16x16x32_f16 v[86:89], v[186:189], v[234:237], v[86:89]
	s_add_i32 s26, s48, s30
	v_lshl_add_u64 v[238:239], v[238:239], 0, s[36:37]
	s_mov_b32 m0, s26
	v_mfma_f32_16x16x32_f16 v[114:117], v[190:193], v[206:209], v[114:117]
	v_mfma_f32_16x16x32_f16 v[110:113], v[198:201], v[206:209], v[110:113]
	v_mfma_f32_16x16x32_f16 v[98:101], v[190:193], v[214:217], v[98:101]
	v_mfma_f32_16x16x32_f16 v[94:97], v[198:201], v[214:217], v[94:97]
	v_mfma_f32_16x16x32_f16 v[82:85], v[190:193], v[222:225], v[82:85]
	v_mfma_f32_16x16x32_f16 v[78:81], v[198:201], v[222:225], v[78:81]
	v_mfma_f32_16x16x32_f16 v[74:77], v[190:193], v[230:233], v[74:77]
	v_mfma_f32_16x16x32_f16 v[70:73], v[198:201], v[230:233], v[70:73]
	v_mfma_f32_16x16x32_f16 v[114:117], v[194:197], v[210:213], v[114:117]
	v_mfma_f32_16x16x32_f16 v[110:113], v[202:205], v[210:213], v[110:113]
	v_mfma_f32_16x16x32_f16 v[98:101], v[194:197], v[218:221], v[98:101]
	v_mfma_f32_16x16x32_f16 v[94:97], v[202:205], v[218:221], v[94:97]
	v_mfma_f32_16x16x32_f16 v[82:85], v[194:197], v[226:229], v[82:85]
	v_mfma_f32_16x16x32_f16 v[78:81], v[202:205], v[226:229], v[78:81]
	v_mfma_f32_16x16x32_f16 v[74:77], v[194:197], v[234:237], v[74:77]
	v_mfma_f32_16x16x32_f16 v[70:73], v[202:205], v[234:237], v[70:73]
	s_barrier
	ds_read_b128 v[206:209], v151 offset:49152
	ds_read_b128 v[210:213], v151 offset:50176
	ds_read_b128 v[214:217], v151 offset:51200
	ds_read_b128 v[218:221], v151 offset:52224
	ds_read_b128 v[222:225], v151 offset:53248
	ds_read_b128 v[226:229], v151 offset:54272
	ds_read_b128 v[230:233], v151 offset:55296
	ds_read_b128 v[234:237], v151 offset:56320
	global_load_lds_dwordx4 v[238:239], off
	s_add_i32 m0, s26, 0x2000
	s_add_u32 s22, s22, 0x40080
	v_lshl_add_u64 v[238:239], v[240:241], 0, s[36:37]
	s_addc_u32 s23, s23, 0
	s_add_i32 s26, s49, s30
	global_load_lds_dwordx4 v[238:239], off
	v_lshl_add_u64 v[238:239], s[22:23], 0, v[0:1]
	s_mov_b32 m0, s26
	s_nop 0
	global_load_lds_dwordx4 v[238:239], off
	v_lshl_add_u64 v[238:239], s[22:23], 0, v[2:3]
	s_add_i32 m0, s26, 0x2000
	s_nop 0
	global_load_lds_dwordx4 v[238:239], off
	v_lshl_add_u64 v[238:239], v[242:243], 0, s[36:37]
	s_mov_b32 m0, s39
	s_nop 0
	global_load_lds_dwordx4 v[238:239], off
	v_lshl_add_u64 v[238:239], v[244:245], 0, s[36:37]
	s_mov_b32 m0, s40
	s_nop 0
	global_load_lds_dwordx4 v[238:239], off
	s_waitcnt vmcnt(8)
	s_waitcnt lgkmcnt(0)
	s_barrier
	s_waitcnt lgkmcnt(0)
	v_mfma_f32_16x16x32_f16 v[66:69], v[152:155], v[206:209], v[66:69]
	v_mfma_f32_16x16x32_f16 v[62:65], v[182:185], v[206:209], v[62:65]
	v_mfma_f32_16x16x32_f16 v[58:61], v[152:155], v[214:217], v[58:61]
	v_mfma_f32_16x16x32_f16 v[54:57], v[182:185], v[214:217], v[54:57]
	v_mfma_f32_16x16x32_f16 v[42:45], v[152:155], v[222:225], v[42:45]
	v_mfma_f32_16x16x32_f16 v[38:41], v[182:185], v[222:225], v[38:41]
	v_mfma_f32_16x16x32_f16 v[26:29], v[152:155], v[230:233], v[26:29]
	v_mfma_f32_16x16x32_f16 v[22:25], v[182:185], v[230:233], v[22:25]
	v_mfma_f32_16x16x32_f16 v[66:69], v[178:181], v[210:213], v[66:69]
	v_mfma_f32_16x16x32_f16 v[62:65], v[186:189], v[210:213], v[62:65]
	v_mfma_f32_16x16x32_f16 v[58:61], v[178:181], v[218:221], v[58:61]
	v_mfma_f32_16x16x32_f16 v[54:57], v[186:189], v[218:221], v[54:57]
	v_mfma_f32_16x16x32_f16 v[42:45], v[178:181], v[226:229], v[42:45]
	v_mfma_f32_16x16x32_f16 v[38:41], v[186:189], v[226:229], v[38:41]
	v_mfma_f32_16x16x32_f16 v[26:29], v[178:181], v[234:237], v[26:29]
	v_mfma_f32_16x16x32_f16 v[22:25], v[186:189], v[234:237], v[22:25]
	v_mfma_f32_16x16x32_f16 v[50:53], v[190:193], v[206:209], v[50:53]
	v_mfma_f32_16x16x32_f16 v[46:49], v[198:201], v[206:209], v[46:49]
	v_mfma_f32_16x16x32_f16 v[34:37], v[190:193], v[214:217], v[34:37]
	v_mfma_f32_16x16x32_f16 v[30:33], v[198:201], v[214:217], v[30:33]
	v_mfma_f32_16x16x32_f16 v[18:21], v[190:193], v[222:225], v[18:21]
	v_mfma_f32_16x16x32_f16 v[14:17], v[198:201], v[222:225], v[14:17]
	v_mfma_f32_16x16x32_f16 v[10:13], v[190:193], v[230:233], v[10:13]
	v_mfma_f32_16x16x32_f16 v[6:9], v[198:201], v[230:233], v[6:9]
	v_mfma_f32_16x16x32_f16 v[50:53], v[194:197], v[210:213], v[50:53]
	v_mfma_f32_16x16x32_f16 v[46:49], v[202:205], v[210:213], v[46:49]
	v_mfma_f32_16x16x32_f16 v[34:37], v[194:197], v[218:221], v[34:37]
	v_mfma_f32_16x16x32_f16 v[30:33], v[202:205], v[218:221], v[30:33]
	v_mfma_f32_16x16x32_f16 v[18:21], v[194:197], v[226:229], v[18:21]
	v_mfma_f32_16x16x32_f16 v[14:17], v[202:205], v[226:229], v[14:17]
	v_mfma_f32_16x16x32_f16 v[10:13], v[194:197], v[234:237], v[10:13]
	v_mfma_f32_16x16x32_f16 v[6:9], v[202:205], v[234:237], v[6:9]
	s_barrier
	s_add_i32 s47, s47, 2
	s_add_u32 s20, s20, 0x100
	s_addc_u32 s21, s21, 0
	s_cmp_gt_u32 s47, 13
	s_cbranch_scc0 .LBB0_386
	s_and_b64 vcc, exec, s[4:5]
	s_cbranch_vccz .LBB0_389
	s_barrier
